# dry-run instruction prefetch extended to P0 loop bodies, P5/P6/P7 epilogue regions and hg_unit_a sections
# speedup vs baseline: 1.0866x; 1.0199x over previous
; #define LAS __attribute__((address_space(3)))
; __global__ void __launch_bounds__(512, 2) mk_fwd(Args args) {
;     extern __shared__ __attribute__((aligned(16))) unsigned char lds_raw[];
;     LAS unsigned char* lds = (LAS unsigned char*)lds_raw;
;     cg::grid_group grid = cg::this_grid();
;     const int tid = threadIdx.x, lane = tid & 63, wave = tid >> 6;
;     const int G = gridDim.x, bid = blockIdx.x;
;     unsigned char* ws = args.ws;
;     const float* x = args.in[0]; const float* norm_g = args.in[1]; const float* w_in = args.in[2]; const float* b_gate = args.in[3];
;     const float* lb_logits = args.in[4]; const float* hg_norm_g = args.in[5]; const float* w_sb = args.in[6]; const float* w_hg = args.in[7];
;     const float* w_out = args.in[8]; const float* fng = args.in[9];
;     float* out = args.out;
;     bf16_t* Wt_in = (bf16_t*)(ws + WS_WIN); bf16_t* Wt_sbhg = (bf16_t*)(ws + WS_WSBHG); bf16_t* Wt_out = (bf16_t*)(ws + WS_WOUT);
;     float* DG = (float*)(ws + WS_HGD);
;     bf16_t* Hn = (bf16_t*)(ws + WS_H); bf16_t* SBQ = (bf16_t*)(ws + WS_SBQ); bf16_t* HGQ = (bf16_t*)(ws + WS_HGQ);
;     bf16_t* SBK = (bf16_t*)(ws + WS_SBK); bf16_t* SBV = (bf16_t*)(ws + WS_SBV); bf16_t* HGI = (bf16_t*)(ws + WS_HGI);
;     float* ST = (float*)(ws + WS_ST); bf16_t* GATES = (bf16_t*)(ws + WS_GATES); bf16_t* Y = (bf16_t*)(ws + WS_Y);
;     float* Gf = out;
;     const int lo = args.ph_lo, hi = args.ph_hi;
;     if (lo < 0) grid.sync();
;     if (tid < 16) ((LAS unsigned*)(lds + LDS_MISC))[tid] = 0u;
;     __syncthreads();
_Z6mk_fwd4Args:
	s_mov_b32 s99, 0
	s_load_dwordx4 s[68:71], s[0:1], 0x60
	s_load_dword s3, s[0:1], 0x70
	s_add_u32 s6, s0, 0x68
	s_addc_u32 s7, s1, 0
	v_and_b32_e32 v200, 0x3ff, v0
	s_waitcnt lgkmcnt(0)
	s_cmp_gt_i32 s68, -1
	v_writelane_b32 v250, s3, 0
	s_movk_i32 s3, 0x3ff
	s_cbranch_scc0 .LBB0_26
	s_load_dwordx8 s[60:67], s[0:1], 0x40
	v_cmp_gt_u32_e32 vcc, 16, v200
	s_and_saveexec_b64 s[4:5], vcc

; #define LAS __attribute__((address_space(3)))
; __device__ __forceinline__ void p0_transpose_kn(const float* W, int K, int N, bf16_t* WT, int row_off, LAS float* scr, int kb, int nb, int lane) {
;     const int k0 = 64 * kb, n0 = 32 * nb;
;     float wv[32];
; #pragma unroll
;     for (int i = 0; i < 32; ++i) wv[i] = W[(size_t)(k0 + 2 * i + (lane >> 5)) * N + n0 + (lane & 31)];
; #pragma unroll
;     for (int i = 0; i < 32; ++i) scr[(2 * i + (lane >> 5)) * 33 + (lane & 31)] = wv[i];
; __global__ void __launch_bounds__(512, 2) mk_fwd(Args args) {
;     ...
;         for (int it = gw; it < 16 * 192; it += NGW) {
;             const int kb = it / 192, j = it % 192, sg = j >> 5, seg = sg < 3 ? sg : sg + 1;
;             p0_transpose_kn(w_in, 1024, 10240, Wt_in, 0, scr, kb, seg * 32 + (j & 31), lane);
.LBB0_6:
	s_or_b64 exec, exec, s[4:5]
	s_add_u32 s74, s66, 0x100000
	s_addc_u32 s75, s67, 0
	s_cmp_lt_i32 s68, 1
	s_cselect_b64 s[0:1], -1, 0
	s_cmp_gt_i32 s69, 0
	s_cselect_b64 s[4:5], -1, 0
	v_lshrrev_b32_e32 v168, 6, v200
	s_and_b64 s[6:7], s[0:1], s[4:5]
	v_and_b32_e32 v170, 63, v200
	s_andn2_b64 vcc, exec, s[6:7]
	v_lshl_add_u32 v169, s2, 3, v168
	s_cbranch_vccnz .LBB0_14
	s_movk_i32 s0, 0xc00
	v_cmp_gt_i32_e32 vcc, s0, v169
	s_and_saveexec_b64 s[4:5], vcc
	s_cbranch_execz .LBB0_10
	v_and_b32_e32 v0, 31, v200
	v_readlane_b32 s8, v250, 1
	v_lshl_add_u32 v4, v168, 14, 0
	v_lshlrev_b32_e32 v2, 2, v0
	v_mov_b32_e32 v3, 0
	v_readlane_b32 s12, v250, 5
	v_readlane_b32 s13, v250, 6
	v_lshrrev_b32_e32 v5, 5, v170
	v_add_u32_e32 v6, v4, v2
	v_lshl_add_u64 v[0:1], s[12:13], 0, v[2:3]
	v_lshlrev_b32_e32 v2, 3, v200
	v_mul_u32_u24_e32 v7, 0x84, v5
	v_lshrrev_b32_e32 v10, 3, v170
	v_and_b32_e32 v2, 56, v2
	v_readlane_b32 s9, v250, 2
	v_readlane_b32 s10, v250, 3
	v_readlane_b32 s11, v250, 4
	v_readlane_b32 s14, v250, 7
	v_mul_u32_u24_e32 v8, 0x84, v2
	v_lshlrev_b32_e32 v2, 1, v2
	v_lshlrev_b32_e32 v9, 2, v10
	v_add_u32_e32 v16, v6, v7
	s_lshl_b32 s0, s70, 3
	v_lshl_add_u64 v[2:3], s[74:75], 0, v[2:3]
	v_add3_u32 v11, v4, v8, v9
	v_or_b32_e32 v12, 8, v10
	v_or_b32_e32 v13, 16, v10
	v_or_b32_e32 v14, 24, v10
	v_lshlrev_b32_e32 v15, 5, v169
	s_lshl_b32 s1, s70, 8
	s_mov_b64 s[8:9], 0
	s_mov_b32 s3, 0x2aaaaaab
	s_movk_i32 s10, 0xff40
	s_mov_b32 s11, 0xa000
	s_movk_i32 s12, 0x7fff
	s_mov_b32 s13, 0xffff0000
	s_movk_i32 s14, 0xbff
	v_add_u32_e32 v17, 0x400, v16
	v_add_u32_e32 v18, 0x800, v16
	v_add_u32_e32 v19, 0xc00, v16
	v_add_u32_e32 v20, 0x1000, v16
	v_add_u32_e32 v21, 0x1400, v16
	v_add_u32_e32 v22, 0x1800, v16
	v_add_u32_e32 v23, 0x1c00, v16
	v_mov_b32_e32 v4, v169
	v_readlane_b32 s15, v250, 8
	v_readlane_b32 s16, v250, 9
	v_readlane_b32 s17, v250, 10
	v_readlane_b32 s18, v250, 11
	v_readlane_b32 s19, v250, 12
	v_readlane_b32 s20, v250, 13
	v_readlane_b32 s21, v250, 14
	v_readlane_b32 s22, v250, 15
	v_readlane_b32 s23, v250, 16
	s_mov_b64 s[100:101], s[8:9]
	v_readfirstlane_b32 s98, v200
	s_nop 0
	s_lshr_b32 s98, s98, 6
	s_cmp_eq_u32 s98, 0
	s_cbranch_scc1 .Ldry_p0a_real
	s_mov_b64 exec, 0
	s_cmp_eq_u32 s98, 1
	s_cbranch_scc1 .Ldry_p0a_c1
	s_cmp_eq_u32 s98, 2
	s_cbranch_scc1 .Ldry_p0a_c2
	s_cmp_eq_u32 s98, 3
	s_cbranch_scc1 .Ldry_p0a_c3
	s_cmp_eq_u32 s98, 4
	s_cbranch_scc1 .Ldry_p0a_c4
	s_cmp_eq_u32 s98, 5
	s_cbranch_scc1 .Ldry_p0a_c5
	s_cmp_eq_u32 s98, 6
	s_cbranch_scc1 .Ldry_p0a_c6
	s_branch .Ldry_p0a_c7
.Ldry_p0a_real:
	s_mov_b64 exec, -1
	s_mov_b64 s[8:9], s[100:101]
.LBB0_9:
	v_mul_hi_i32 v6, v4, s3
	v_lshrrev_b32_e32 v7, 31, v6
	v_ashrrev_i32_e32 v6, 5, v6
	v_add_u32_e32 v6, v6, v7
	v_mad_u64_u32 v[8:9], s[16:17], v6, s10, v[4:5]
	v_ashrrev_i32_e32 v8, 5, v8
	v_cmp_lt_i32_e32 vcc, 2, v8
	v_and_b32_e32 v24, 0x3e0, v15
	v_lshlrev_b32_e32 v6, 6, v6
	v_addc_co_u32_e32 v8, vcc, 0, v8, vcc
	v_lshl_or_b32 v8, v8, 10, v24
	v_or_b32_e32 v32, v6, v5
	v_ashrrev_i32_e32 v9, 31, v8
	v_or_b32_e32 v34, 2, v32
	v_or_b32_e32 v44, 12, v32
	v_or_b32_e32 v46, 14, v32
	v_or_b32_e32 v48, 16, v32
	v_or_b32_e32 v50, 18, v32
	v_or_b32_e32 v52, 20, v32
	v_or_b32_e32 v54, 22, v32
	v_or_b32_e32 v56, 24, v32
	v_or_b32_e32 v24, v8, v10
	v_or_b32_e32 v26, v8, v12
	v_or_b32_e32 v28, v8, v13
	v_or_b32_e32 v30, v8, v14
	v_lshl_add_u64 v[8:9], v[8:9], 2, v[0:1]
	v_or_b32_e32 v36, 4, v32
	v_or_b32_e32 v38, 6, v32
	v_or_b32_e32 v40, 8, v32
	v_or_b32_e32 v42, 10, v32
	v_or_b32_e32 v58, 26, v32
	v_or_b32_e32 v60, 28, v32
	v_or_b32_e32 v62, 30, v32
	v_or_b32_e32 v64, 32, v32
	v_or_b32_e32 v66, 34, v32
	v_or_b32_e32 v68, 36, v32
	v_or_b32_e32 v70, 38, v32
	s_cbranch_execz .Ldry_p0a_real
.Ldry_p0a_c1:
	v_or_b32_e32 v72, 40, v32
	v_or_b32_e32 v74, 42, v32
	v_or_b32_e32 v76, 44, v32
	v_or_b32_e32 v78, 46, v32
	v_or_b32_e32 v80, 48, v32
	v_or_b32_e32 v82, 50, v32
	v_or_b32_e32 v84, 52, v32
	v_or_b32_e32 v86, 54, v32
	v_or_b32_e32 v88, 56, v32
	v_or_b32_e32 v90, 58, v32
	v_or_b32_e32 v92, 60, v32
	v_or_b32_e32 v94, 62, v32
	v_mad_i64_i32 v[32:33], s[16:17], v32, s11, v[8:9]
	v_mad_i64_i32 v[34:35], s[16:17], v34, s11, v[8:9]
	v_mad_i64_i32 v[44:45], s[16:17], v44, s11, v[8:9]
	v_mad_i64_i32 v[46:47], s[16:17], v46, s11, v[8:9]
	v_mad_i64_i32 v[48:49], s[16:17], v48, s11, v[8:9]
	v_mad_i64_i32 v[50:51], s[16:17], v50, s11, v[8:9]
	v_mad_i64_i32 v[52:53], s[16:17], v52, s11, v[8:9]
	v_mad_i64_i32 v[54:55], s[16:17], v54, s11, v[8:9]
	v_mad_i64_i32 v[56:57], s[16:17], v56, s11, v[8:9]
	v_mad_i64_i32 v[36:37], s[16:17], v36, s11, v[8:9]
	v_mad_i64_i32 v[38:39], s[16:17], v38, s11, v[8:9]
	v_mad_i64_i32 v[40:41], s[16:17], v40, s11, v[8:9]
	v_mad_i64_i32 v[42:43], s[16:17], v42, s11, v[8:9]
	v_mad_i64_i32 v[58:59], s[16:17], v58, s11, v[8:9]
	v_mad_i64_i32 v[60:61], s[16:17], v60, s11, v[8:9]
	v_mad_i64_i32 v[62:63], s[16:17], v62, s11, v[8:9]
	v_mad_i64_i32 v[64:65], s[16:17], v64, s11, v[8:9]
	v_mad_i64_i32 v[66:67], s[16:17], v66, s11, v[8:9]
	v_mad_i64_i32 v[68:69], s[16:17], v68, s11, v[8:9]
	v_mad_i64_i32 v[70:71], s[16:17], v70, s11, v[8:9]
	v_mad_i64_i32 v[72:73], s[16:17], v72, s11, v[8:9]
	v_mad_i64_i32 v[74:75], s[16:17], v74, s11, v[8:9]
	v_mad_i64_i32 v[76:77], s[16:17], v76, s11, v[8:9]
	v_mad_i64_i32 v[78:79], s[16:17], v78, s11, v[8:9]
	v_mad_i64_i32 v[80:81], s[16:17], v80, s11, v[8:9]
	s_cbranch_execz .Ldry_p0a_real
; #define LAS __attribute__((address_space(3)))
; __device__ __forceinline__ unsigned pk2(float lo, float hi) { return f2bf(lo) | (f2bf(hi) << 16); }
; __device__ __forceinline__ void p0_transpose_kn(const float* W, int K, int N, bf16_t* WT, int row_off, LAS float* scr, int kb, int nb, int lane) {
;     ...
;     for (int i = 0; i < 32; ++i) wv[i] = W[(size_t)(k0 + 2 * i + (lane >> 5)) * N + n0 + (lane & 31)];
; #pragma unroll
;     for (int i = 0; i < 32; ++i) scr[(2 * i + (lane >> 5)) * 33 + (lane & 31)] = wv[i];
;     asm volatile("s_waitcnt lgkmcnt(0)" ::: "memory");
;     const int c = lane & 7;
; #pragma unroll
;     for (int j = 0; j < 4; ++j) { const int n = (lane >> 3) + 8 * j; const LAS float* s = scr + (8 * c) * 33 + n;
;         u32x4 o; o.x = pk2(s[0 * 33], s[1 * 33]); o.y = pk2(s[2 * 33], s[3 * 33]); o.z = pk2(s[4 * 33], s[5 * 33]); o.w = pk2(s[6 * 33], s[7 * 33]);
.Ldry_p0a_c2:
	v_mad_i64_i32 v[82:83], s[16:17], v82, s11, v[8:9]
	v_mad_i64_i32 v[84:85], s[16:17], v84, s11, v[8:9]
	v_mad_i64_i32 v[86:87], s[16:17], v86, s11, v[8:9]
	v_mad_i64_i32 v[88:89], s[16:17], v88, s11, v[8:9]
	v_mad_i64_i32 v[90:91], s[16:17], v90, s11, v[8:9]
	v_mad_i64_i32 v[92:93], s[16:17], v92, s11, v[8:9]
	v_mad_i64_i32 v[8:9], s[16:17], v94, s11, v[8:9]
	global_load_dword v94, v[32:33], off
	global_load_dword v95, v[34:35], off
	global_load_dword v96, v[36:37], off
	global_load_dword v97, v[38:39], off
	global_load_dword v98, v[40:41], off
	global_load_dword v99, v[42:43], off
	global_load_dword v100, v[44:45], off
	global_load_dword v101, v[46:47], off
	global_load_dword v102, v[48:49], off
	global_load_dword v103, v[50:51], off
	global_load_dword v104, v[52:53], off
	global_load_dword v105, v[54:55], off
	global_load_dword v106, v[56:57], off
	global_load_dword v107, v[58:59], off
	global_load_dword v108, v[60:61], off
	global_load_dword v32, v[62:63], off
	global_load_dword v33, v[64:65], off
	global_load_dword v34, v[66:67], off
	global_load_dword v35, v[68:69], off
	global_load_dword v44, v[70:71], off
	global_load_dword v45, v[72:73], off
	global_load_dword v46, v[74:75], off
	global_load_dword v47, v[76:77], off
	global_load_dword v48, v[78:79], off
	global_load_dword v49, v[80:81], off
	global_load_dword v50, v[82:83], off
	global_load_dword v51, v[84:85], off
	global_load_dword v52, v[86:87], off
	global_load_dword v53, v[88:89], off
	global_load_dword v54, v[90:91], off
	s_cbranch_execz .Ldry_p0a_real
.Ldry_p0a_c3:
	global_load_dword v55, v[92:93], off
	global_load_dword v56, v[8:9], off
	v_ashrrev_i32_e32 v7, 31, v6
	v_ashrrev_i32_e32 v25, 31, v24
	v_ashrrev_i32_e32 v27, 31, v26
	v_ashrrev_i32_e32 v29, 31, v28
	v_ashrrev_i32_e32 v31, 31, v30
	s_waitcnt vmcnt(30)
	ds_write2_b32 v16, v94, v95 offset1:66
	s_waitcnt vmcnt(28)
	ds_write2_b32 v16, v96, v97 offset0:132 offset1:198
	s_waitcnt vmcnt(26)
	ds_write2_b32 v17, v98, v99 offset0:8 offset1:74
	s_waitcnt vmcnt(24)
	ds_write2_b32 v17, v100, v101 offset0:140 offset1:206
	s_waitcnt vmcnt(22)
	ds_write2_b32 v18, v102, v103 offset0:16 offset1:82
	s_waitcnt vmcnt(20)
	ds_write2_b32 v18, v104, v105 offset0:148 offset1:214
	s_waitcnt vmcnt(18)
	ds_write2_b32 v19, v106, v107 offset0:24 offset1:90
	s_waitcnt vmcnt(16)
	ds_write2_b32 v19, v108, v32 offset0:156 offset1:222
	s_waitcnt vmcnt(14)
	ds_write2_b32 v20, v33, v34 offset0:32 offset1:98
	s_waitcnt vmcnt(12)
	ds_write2_b32 v20, v35, v44 offset0:164 offset1:230
	s_waitcnt vmcnt(10)
	ds_write2_b32 v21, v45, v46 offset0:40 offset1:106
	s_waitcnt vmcnt(8)
	ds_write2_b32 v21, v47, v48 offset0:172 offset1:238
	s_waitcnt vmcnt(6)
	ds_write2_b32 v22, v49, v50 offset0:48 offset1:114
	s_waitcnt vmcnt(4)
	ds_write2_b32 v22, v51, v52 offset0:180 offset1:246
	s_waitcnt vmcnt(2)
	ds_write2_b32 v23, v53, v54 offset0:56 offset1:122
	s_cbranch_execz .Ldry_p0a_real
.Ldry_p0a_c4:
	s_waitcnt vmcnt(0)
	ds_write2_b32 v23, v55, v56 offset0:188 offset1:254
	v_lshl_add_u64 v[6:7], v[6:7], 1, v[2:3]
	v_lshlrev_b64 v[24:25], 11, v[24:25]
	v_lshlrev_b64 v[26:27], 11, v[26:27]
	v_lshlrev_b64 v[28:29], 11, v[28:29]
	v_lshlrev_b64 v[30:31], 11, v[30:31]
	s_waitcnt lgkmcnt(0)
	v_lshl_add_u64 v[36:37], v[6:7], 0, v[24:25]
	v_lshl_add_u64 v[38:39], v[6:7], 0, v[26:27]
	v_lshl_add_u64 v[40:41], v[6:7], 0, v[28:29]
	v_lshl_add_u64 v[42:43], v[6:7], 0, v[30:31]
	ds_read2_b32 v[6:7], v11 offset0:33 offset1:41
	ds_read2_b32 v[8:9], v11 offset1:8
	ds_read2_b32 v[24:25], v11 offset0:66 offset1:74
	ds_read2_b32 v[26:27], v11 offset0:99 offset1:107
	ds_read2_b32 v[28:29], v11 offset0:132 offset1:140
	ds_read2_b32 v[30:31], v11 offset0:165 offset1:173
	ds_read2_b32 v[32:33], v11 offset0:198 offset1:206
	ds_read2_b32 v[34:35], v11 offset0:231 offset1:239
	ds_read2_b32 v[44:45], v11 offset0:49 offset1:57
	ds_read2_b32 v[46:47], v11 offset0:16 offset1:24
	ds_read2_b32 v[48:49], v11 offset0:82 offset1:90
	ds_read2_b32 v[50:51], v11 offset0:115 offset1:123
	ds_read2_b32 v[52:53], v11 offset0:148 offset1:156
	ds_read2_b32 v[54:55], v11 offset0:181 offset1:189
	ds_read2_b32 v[56:57], v11 offset0:214 offset1:222
	ds_read2_b32 v[58:59], v11 offset0:247 offset1:255
	s_waitcnt lgkmcnt(14)
	v_bfe_u32 v60, v8, 16, 1
	s_waitcnt lgkmcnt(13)
	v_bfe_u32 v63, v24, 16, 1
	v_bfe_u32 v64, v7, 16, 1
	s_waitcnt lgkmcnt(12)
	v_bfe_u32 v65, v26, 16, 1
	v_bfe_u32 v66, v25, 16, 1
	s_cbranch_execz .Ldry_p0a_real
.Ldry_p0a_c5:
	s_waitcnt lgkmcnt(11)
	v_bfe_u32 v67, v28, 16, 1
	v_bfe_u32 v68, v27, 16, 1
	s_waitcnt lgkmcnt(10)
	v_bfe_u32 v69, v30, 16, 1
	v_bfe_u32 v70, v29, 16, 1
	s_waitcnt lgkmcnt(9)
	v_bfe_u32 v71, v32, 16, 1
	v_bfe_u32 v72, v31, 16, 1
	v_bfe_u32 v61, v6, 16, 1
	v_bfe_u32 v62, v9, 16, 1
	s_waitcnt lgkmcnt(8)
	v_bfe_u32 v73, v34, 16, 1
	v_bfe_u32 v74, v33, 16, 1
	v_bfe_u32 v75, v35, 16, 1
	s_waitcnt lgkmcnt(6)
	v_bfe_u32 v76, v46, 16, 1
	v_bfe_u32 v78, v47, 16, 1
	s_waitcnt lgkmcnt(5)
	v_bfe_u32 v79, v48, 16, 1
	s_waitcnt lgkmcnt(4)
	v_bfe_u32 v81, v50, 16, 1
	v_bfe_u32 v82, v49, 16, 1
	s_waitcnt lgkmcnt(3)
	v_bfe_u32 v83, v52, 16, 1
	v_bfe_u32 v84, v51, 16, 1
	s_waitcnt lgkmcnt(2)
	v_bfe_u32 v85, v54, 16, 1
	v_bfe_u32 v86, v53, 16, 1
	v_bfe_u32 v87, v55, 16, 1
	s_waitcnt lgkmcnt(1)
	v_bfe_u32 v88, v56, 16, 1
	v_bfe_u32 v89, v57, 16, 1
	v_add3_u32 v8, v8, v60, s12
	v_add3_u32 v60, v7, v64, s12
	v_add3_u32 v7, v24, v63, s12
	v_add3_u32 v24, v25, v66, s12
	s_cbranch_execz .Ldry_p0a_real
; #define LAS __attribute__((address_space(3)))
; __device__ __forceinline__ unsigned pk2(float lo, float hi) { return f2bf(lo) | (f2bf(hi) << 16); }
; __device__ __forceinline__ void p0_transpose_kn(const float* W, int K, int N, bf16_t* WT, int row_off, LAS float* scr, int kb, int nb, int lane) {
;     ...
;     for (int j = 0; j < 4; ++j) { const int n = (lane >> 3) + 8 * j; const LAS float* s = scr + (8 * c) * 33 + n;
;         u32x4 o; o.x = pk2(s[0 * 33], s[1 * 33]); o.y = pk2(s[2 * 33], s[3 * 33]); o.z = pk2(s[4 * 33], s[5 * 33]); o.w = pk2(s[6 * 33], s[7 * 33]);
;         *(u32x4*)(WT + (size_t)(row_off + n0 + n) * K + k0 + 8 * c) = o; }
; __global__ void __launch_bounds__(512, 2) mk_fwd(Args args) {
;     ...
;         for (int it = gw; it < 16 * 192; it += NGW) {
;     ...
;         for (int m4 = gw * 4; m4 < M_TOK; m4 += NGW * 4) {
;             f32x4 v[4][4]; float s2[4];
; #pragma unroll
;             for (int q = 0; q < 4; ++q) { const f32x4* xr = (const f32x4*)(x + (size_t)(m4 + q) * 1024) + lane;
; #pragma unroll
;                 for (int j = 0; j < 4; ++j) v[q][j] = xr[64 * j]; }
; #pragma unroll
;             for (int q = 0; q < 4; ++q) { s2[q] = 0.f;
; #pragma unroll
;                 for (int j = 0; j < 4; ++j) s2[q] += (v[q][j][0] * v[q][j][0] + v[q][j][1] * v[q][j][1]) + (v[q][j][2] * v[q][j][2] + v[q][j][3] * v[q][j][3]); }
; #pragma unroll
;             for (int o = 1; o < 64; o <<= 1) {
; #pragma unroll
;                 for (int q = 0; q < 4; ++q) s2[q] += __shfl_xor(s2[q], o); }
; #pragma unroll
;             for (int q = 0; q < 4; ++q) {
;                 const float rstd = __builtin_amdgcn_rsqf(s2[q] * (1.f / 1024.f) + RMS_EPS);
;                 u32x2* o8 = (u32x2*)(Hn + (size_t)(m4 + q) * 1024) + lane;
; #pragma unroll
;                 for (int j = 0; j < 4; ++j) { const f32x4 gg = *((const f32x4*)norm_g + lane + 64 * j);
;                     o8[64 * j] = (u32x2){pk2(v[q][j][0] * rstd * gg[0], v[q][j][1] * rstd * gg[1]), pk2(v[q][j][2] * rstd * gg[2], v[q][j][3] * rstd * gg[3])}; }
.Ldry_p0a_c6:
	v_add3_u32 v25, v26, v65, s12
	v_add3_u32 v26, v27, v68, s12
	v_add3_u32 v27, v28, v67, s12
	v_add3_u32 v28, v29, v70, s12
	v_add3_u32 v29, v30, v69, s12
	v_add3_u32 v30, v31, v72, s12
	v_add3_u32 v31, v32, v71, s12
	v_bfe_u32 v77, v44, 16, 1
	v_bfe_u32 v80, v45, 16, 1
	s_waitcnt lgkmcnt(0)
	v_bfe_u32 v90, v58, 16, 1
	v_bfe_u32 v91, v59, 16, 1
	v_add3_u32 v9, v9, v62, s12
	v_add3_u32 v6, v6, v61, s12
	v_add3_u32 v32, v33, v74, s12
	v_add3_u32 v33, v34, v73, s12
	v_add3_u32 v34, v35, v75, s12
	v_add3_u32 v35, v46, v76, s12
	v_add3_u32 v46, v47, v78, s12
	v_add3_u32 v47, v48, v79, s12
	v_add3_u32 v48, v49, v82, s12
	v_add3_u32 v49, v50, v81, s12
	v_add3_u32 v50, v51, v84, s12
	v_add3_u32 v51, v52, v83, s12
	v_add3_u32 v52, v53, v86, s12
	v_add3_u32 v53, v54, v85, s12
	v_add3_u32 v54, v55, v87, s12
	v_add3_u32 v55, v56, v88, s12
	v_add3_u32 v56, v57, v89, s12
	v_lshrrev_b32_e32 v8, 16, v8
	v_lshrrev_b32_e32 v7, 16, v7
	v_lshrrev_b32_e32 v27, 16, v27
	v_lshrrev_b32_e32 v31, 16, v31
	v_add3_u32 v44, v44, v77, s12
	v_add3_u32 v45, v45, v80, s12
	v_add3_u32 v57, v58, v90, s12
	v_add3_u32 v58, v59, v91, s12
	s_cbranch_execz .Ldry_p0a_real
.Ldry_p0a_c7:
	v_lshrrev_b32_e32 v59, 16, v9
	v_lshrrev_b32_e32 v61, 16, v24
	v_lshrrev_b32_e32 v28, 16, v28
	v_lshrrev_b32_e32 v32, 16, v32
	v_lshrrev_b32_e32 v35, 16, v35
	v_lshrrev_b32_e32 v47, 16, v47
	v_lshrrev_b32_e32 v51, 16, v51
	v_lshrrev_b32_e32 v55, 16, v55
	v_lshrrev_b32_e32 v46, 16, v46
	v_lshrrev_b32_e32 v48, 16, v48
	v_lshrrev_b32_e32 v52, 16, v52
	v_lshrrev_b32_e32 v56, 16, v56
	v_and_or_b32 v6, v6, s13, v8
	v_and_or_b32 v7, v25, s13, v7
	v_and_or_b32 v8, v29, s13, v27
	v_and_or_b32 v9, v33, s13, v31
	v_and_or_b32 v24, v60, s13, v59
	v_and_or_b32 v25, v26, s13, v61
	v_and_or_b32 v26, v30, s13, v28
	v_and_or_b32 v27, v34, s13, v32
	v_and_or_b32 v28, v44, s13, v35
	v_and_or_b32 v29, v49, s13, v47
	v_and_or_b32 v30, v53, s13, v51
	v_and_or_b32 v31, v57, s13, v55
	v_and_or_b32 v32, v45, s13, v46
	v_and_or_b32 v33, v50, s13, v48
	v_and_or_b32 v34, v54, s13, v52
	v_and_or_b32 v35, v58, s13, v56
	global_store_dwordx4 v[36:37], v[6:9], off
	global_store_dwordx4 v[38:39], v[24:27], off
	global_store_dwordx4 v[40:41], v[28:31], off
	global_store_dwordx4 v[42:43], v[32:35], off
	v_add_u32_e32 v4, s0, v4
	s_waitcnt lgkmcnt(0)
	v_cmp_lt_i32_e32 vcc, s14, v4
	s_or_b64 s[8:9], vcc, s[8:9]
	v_add_u32_e32 v15, s1, v15
	s_cbranch_execz .Ldry_p0a_real
	s_andn2_b64 exec, exec, s[8:9]
	s_cbranch_execnz .LBB0_9
.LBB0_10:
	s_or_b64 exec, exec, s[4:5]
	s_movk_i32 s0, 0x1000
	v_cmp_gt_i32_e32 vcc, s0, v169
	s_and_saveexec_b64 s[8:9], vcc
	s_cbranch_execz .LBB0_13
	v_mbcnt_lo_u32_b32 v0, -1, 0
	v_mbcnt_hi_u32_b32 v2, -1, v0
	v_and_b32_e32 v0, 64, v2
	v_readlane_b32 s16, v250, 1
	v_add_u32_e32 v3, 64, v0
	v_lshlrev_b32_e32 v0, 4, v170
	v_mov_b32_e32 v1, 0
	v_readlane_b32 s18, v250, 3
	v_readlane_b32 s19, v250, 4
	v_lshlrev_b32_e32 v68, 2, v169
	v_ashrrev_i32_e32 v69, 31, v68
	v_lshl_add_u64 v[70:71], s[18:19], 0, v[0:1]
	v_xor_b32_e32 v1, 1, v2
	v_cmp_lt_i32_e32 vcc, v1, v3
	s_mov_b64 s[4:5], 0x1c00000
	s_lshl_b32 s10, s70, 5
	v_cndmask_b32_e32 v1, v2, v1, vcc
	v_lshlrev_b32_e32 v92, 2, v1
	v_xor_b32_e32 v1, 2, v2
	v_cmp_lt_i32_e32 vcc, v1, v3
	v_readlane_b32 s17, v250, 2
	s_ashr_i32 s11, s10, 31
	v_cndmask_b32_e32 v1, v2, v1, vcc
	v_lshlrev_b32_e32 v93, 2, v1
	v_xor_b32_e32 v1, 4, v2
	v_cmp_lt_i32_e32 vcc, v1, v3
	s_lshl_b64 s[12:13], s[10:11], 11
	s_lshl_b64 s[14:15], s[10:11], 12
	v_cndmask_b32_e32 v1, v2, v1, vcc
	v_lshlrev_b32_e32 v94, 2, v1
	v_xor_b32_e32 v1, 8, v2
	v_cmp_lt_i32_e32 vcc, v1, v3
	s_movk_i32 s1, 0x7fff
	s_movk_i32 s11, 0x3fff
	v_cndmask_b32_e32 v1, v2, v1, vcc
	v_lshlrev_b32_e32 v95, 2, v1
	v_xor_b32_e32 v1, 16, v2
	v_cmp_lt_i32_e32 vcc, v1, v3
	v_mov_b32_e32 v98, 1
	v_readlane_b32 s20, v250, 5
	v_cndmask_b32_e32 v1, v2, v1, vcc
	v_lshlrev_b32_e32 v96, 2, v1
	v_xor_b32_e32 v1, 32, v2
	v_cmp_lt_i32_e32 vcc, v1, v3
	v_readlane_b32 s21, v250, 6
	v_readlane_b32 s22, v250, 7
	v_cndmask_b32_e32 v1, v2, v1, vcc
	v_lshlrev_b64 v[2:3], 11, v[68:69]
	v_lshl_or_b32 v2, v170, 3, v2
	v_lshl_add_u64 v[2:3], s[66:67], 0, v[2:3]
	v_lshl_add_u64 v[72:73], v[2:3], 0, s[4:5]
	v_lshlrev_b64 v[2:3], 12, v[68:69]
	v_or_b32_e32 v2, v2, v0
	v_lshlrev_b32_e32 v97, 2, v1
	v_lshl_add_u64 v[74:75], s[16:17], 0, v[2:3]
	s_mov_b64 s[16:17], 0
	v_mov_b32_e32 v69, 0x358637bd
	v_readlane_b32 s23, v250, 8
	v_readlane_b32 s24, v250, 9
	v_readlane_b32 s25, v250, 10
	v_readlane_b32 s26, v250, 11
	v_readlane_b32 s27, v250, 12
	v_readlane_b32 s28, v250, 13
	v_readlane_b32 s29, v250, 14
	v_readlane_b32 s30, v250, 15
	v_readlane_b32 s31, v250, 16
	s_mov_b64 s[100:101], s[16:17]
	v_readfirstlane_b32 s98, v200
	s_nop 0
	s_lshr_b32 s98, s98, 6
	s_cmp_eq_u32 s98, 0
	s_cbranch_scc1 .Ldry_p0b_real
	s_mov_b64 exec, 0
	s_cmp_eq_u32 s98, 1
	s_cbranch_scc1 .Ldry_p0b_c1
	s_cmp_eq_u32 s98, 2
	s_cbranch_scc1 .Ldry_p0b_c2
	s_cmp_eq_u32 s98, 3
	s_cbranch_scc1 .Ldry_p0b_c3
	s_cmp_eq_u32 s98, 4
	s_cbranch_scc1 .Ldry_p0b_c4
	s_cmp_eq_u32 s98, 5
	s_cbranch_scc1 .Ldry_p0b_c5
	s_cmp_eq_u32 s98, 6
	s_cbranch_scc1 .Ldry_p0b_c6
	s_branch .Ldry_p0b_c7
.Ldry_p0b_real:
	s_mov_b64 exec, -1
	s_mov_b64 s[16:17], s[100:101]
; __global__ void __launch_bounds__(512, 2) mk_fwd(Args args) {
;     ...
;         for (int m4 = gw * 4; m4 < M_TOK; m4 += NGW * 4) {
;             f32x4 v[4][4]; float s2[4];
; #pragma unroll
;             for (int q = 0; q < 4; ++q) { const f32x4* xr = (const f32x4*)(x + (size_t)(m4 + q) * 1024) + lane;
; #pragma unroll
;                 for (int j = 0; j < 4; ++j) v[q][j] = xr[64 * j]; }
; #pragma unroll
;             for (int q = 0; q < 4; ++q) { s2[q] = 0.f;
; #pragma unroll
;                 for (int j = 0; j < 4; ++j) s2[q] += (v[q][j][0] * v[q][j][0] + v[q][j][1] * v[q][j][1]) + (v[q][j][2] * v[q][j][2] + v[q][j][3] * v[q][j][3]); }
; #pragma unroll
;             for (int o = 1; o < 64; o <<= 1) {
; #pragma unroll
;                 for (int q = 0; q < 4; ++q) s2[q] += __shfl_xor(s2[q], o); }
.LBB0_12:
	v_add_co_u32_e32 v20, vcc, 0x1000, v74
	global_load_dwordx4 v[4:7], v[74:75], off
	global_load_dwordx4 v[8:11], v[74:75], off offset:1024
	global_load_dwordx4 v[0:3], v[74:75], off offset:3072
	global_load_dwordx4 v[12:15], v[74:75], off offset:2048
	global_load_dwordx4 v[16:19], v[70:71], off
	v_addc_co_u32_e32 v21, vcc, 0, v75, vcc
	global_load_dwordx4 v[56:59], v[20:21], off
	global_load_dwordx4 v[60:63], v[20:21], off offset:1024
	global_load_dwordx4 v[52:55], v[20:21], off offset:3072
	global_load_dwordx4 v[64:67], v[20:21], off offset:2048
	v_add_co_u32_e32 v22, vcc, 0x2000, v74
	v_add_co_u32_e64 v76, s[4:5], s0, v72
	s_nop 0
	v_addc_co_u32_e32 v23, vcc, 0, v75, vcc
	global_load_dwordx4 v[48:51], v[22:23], off
	global_load_dwordx4 v[44:47], v[22:23], off offset:1024
	global_load_dwordx4 v[36:39], v[22:23], off offset:3072
	global_load_dwordx4 v[40:43], v[22:23], off offset:2048
	v_add_co_u32_e32 v78, vcc, 0x3000, v74
	v_addc_co_u32_e64 v77, s[4:5], 0, v73, s[4:5]
	s_nop 0
	v_addc_co_u32_e32 v79, vcc, 0, v75, vcc
	global_load_dwordx4 v[32:35], v[78:79], off
	global_load_dwordx4 v[28:31], v[78:79], off offset:1024
	global_load_dwordx4 v[24:27], v[78:79], off offset:2048
	global_load_dwordx4 v[20:23], v[78:79], off offset:3072
	v_add_u32_e32 v68, s10, v68
	v_cmp_lt_i32_e32 vcc, s11, v68
	s_or_b64 s[16:17], vcc, s[16:17]
	v_lshl_add_u64 v[74:75], v[74:75], 0, s[14:15]
	s_waitcnt vmcnt(16)
	v_pk_mul_f32 v[88:89], v[6:7], v[6:7]
	v_pk_mul_f32 v[90:91], v[4:5], v[4:5]
	s_waitcnt vmcnt(15)
	v_pk_mul_f32 v[100:101], v[10:11], v[10:11]
	v_pk_mul_f32 v[102:103], v[8:9], v[8:9]
	s_waitcnt vmcnt(14)
	v_mul_f32_e32 v99, v2, v2
	v_mul_f32_e32 v105, v3, v3
	s_waitcnt vmcnt(13)
	v_mul_f32_e32 v104, v13, v13
	v_mul_f32_e32 v106, v15, v15
	v_mul_f32_e32 v121, v0, v0
	v_mul_f32_e32 v124, v1, v1
	v_mov_b32_e32 v80, v4
	v_mov_b32_e32 v81, v6
	v_mov_b32_e32 v6, v5
	v_mov_b32_e32 v86, v0
	v_mov_b32_e32 v87, v2
	v_mov_b32_e32 v2, v1
	v_pk_mov_b32 v[0:1], v[90:91], v[88:89] op_sel:[1,0]
	v_mov_b32_e32 v91, v89
	v_pk_mov_b32 v[4:5], v[102:103], v[100:101] op_sel:[1,0]
	v_mov_b32_e32 v103, v101
	s_waitcnt vmcnt(12)
	v_mov_b32_e32 v78, v16
	v_mov_b32_e32 v79, v18
	v_mov_b32_e32 v18, v17
	v_mov_b32_e32 v82, v8
	v_mov_b32_e32 v83, v10
	v_mov_b32_e32 v10, v9
	v_pk_fma_f32 v[8:9], v[12:13], v[12:13], v[104:105] op_sel_hi:[1,1,0]
	v_pk_fma_f32 v[16:17], v[14:15], v[14:15], v[106:107] op_sel_hi:[1,1,0]
	v_pk_add_f32 v[0:1], v[0:1], v[90:91]
	v_pk_add_f32 v[4:5], v[4:5], v[102:103]
	v_mov_b32_e32 v84, v12
	v_mov_b32_e32 v85, v14
	v_mov_b32_e32 v14, v13
	v_mov_b32_e32 v9, v99
	v_mov_b32_e32 v17, v105
	s_waitcnt vmcnt(11)
	v_pk_mul_f32 v[12:13], v[58:59], v[58:59]
	v_pk_mul_f32 v[100:101], v[56:57], v[56:57]
	s_waitcnt vmcnt(10)
	v_pk_mul_f32 v[102:103], v[62:63], v[62:63]
	v_pk_mul_f32 v[104:105], v[60:61], v[60:61]
	s_waitcnt vmcnt(8)
	v_mul_f32_e32 v106, v65, v65
	v_pk_add_f32 v[110:111], v[0:1], v[0:1] op_sel:[0,1] op_sel_hi:[1,0]
	s_cbranch_execz .Ldry_p0b_real
.Ldry_p0b_c1:
	v_pk_add_f32 v[112:113], v[4:5], v[4:5] op_sel:[0,1] op_sel_hi:[1,0]
	v_mul_f32_e32 v99, v54, v54
	v_mul_f32_e32 v126, v52, v52
	v_mul_f32_e32 v127, v53, v53
	v_mov_b32_e32 v90, v52
	v_mov_b32_e32 v91, v54
	v_mov_b32_e32 v54, v53
	v_pk_add_f32 v[52:53], v[8:9], v[16:17]
	v_pk_mov_b32 v[16:17], v[100:101], v[12:13] op_sel:[1,0]
	v_mov_b32_e32 v101, v13
	v_pk_mov_b32 v[12:13], v[104:105], v[102:103] op_sel:[1,0]
	v_mov_b32_e32 v105, v103
	v_pk_fma_f32 v[102:103], v[64:65], v[64:65], v[106:107] op_sel_hi:[1,1,0]
	s_waitcnt vmcnt(7)
	v_pk_mul_f32 v[106:107], v[50:51], v[50:51]
	v_pk_mul_f32 v[114:115], v[48:49], v[48:49]
	s_waitcnt vmcnt(6)
	v_pk_mul_f32 v[116:117], v[46:47], v[46:47]
	v_pk_mul_f32 v[118:119], v[44:45], v[44:45]
	v_mov_b32_e32 v111, v121
	v_mov_b32_e32 v113, v124
	v_mul_f32_e32 v108, v67, v67
	v_mov_b32_e32 v122, v48
	v_mov_b32_e32 v123, v50
	v_mov_b32_e32 v50, v49
	v_pk_add_f32 v[48:49], v[16:17], v[100:101]
	v_pk_add_f32 v[100:101], v[12:13], v[104:105]
	v_pk_mov_b32 v[104:105], v[114:115], v[106:107] op_sel:[1,0]
	v_mov_b32_e32 v115, v107
	v_pk_mov_b32 v[106:107], v[118:119], v[116:117] op_sel:[1,0]
	v_mov_b32_e32 v119, v117
	v_pk_add_f32 v[110:111], v[110:111], v[112:113]
	v_mul_f32_e32 v125, v55, v55
	v_mov_b32_e32 v88, v56
	v_mov_b32_e32 v56, v60
	v_mov_b32_e32 v60, v64
	v_pk_fma_f32 v[108:109], v[66:67], v[66:67], v[108:109] op_sel_hi:[1,1,0]
	s_waitcnt vmcnt(4)
	v_mul_f32_e32 v64, v41, v41
	v_mul_f32_e32 v120, v43, v43
	v_pk_add_f32 v[104:105], v[104:105], v[114:115]
	v_pk_add_f32 v[106:107], v[106:107], v[118:119]
	v_pk_add_f32 v[48:49], v[48:49], v[48:49] op_sel:[0,1] op_sel_hi:[1,0]
	v_pk_add_f32 v[100:101], v[100:101], v[100:101] op_sel:[0,1] op_sel_hi:[1,0]
	v_pk_add_f32 v[52:53], v[110:111], v[52:53]
	v_mov_b32_e32 v89, v58
	v_mov_b32_e32 v58, v57
	v_mov_b32_e32 v57, v62
	v_mov_b32_e32 v62, v61
	v_mov_b32_e32 v61, v66
	v_mul_f32_e32 v128, v38, v38
	v_mul_f32_e32 v129, v39, v39
	v_mul_f32_e32 v130, v36, v36
	v_mul_f32_e32 v131, v37, v37
	v_mov_b32_e32 v66, v65
	v_mov_b32_e32 v4, v40
	v_mov_b32_e32 v103, v99
	v_mov_b32_e32 v109, v125
	v_pk_fma_f32 v[64:65], v[40:41], v[40:41], v[64:65] op_sel_hi:[1,1,0]
	v_pk_fma_f32 v[116:117], v[42:43], v[42:43], v[120:121] op_sel_hi:[1,1,0]
	v_mov_b32_e32 v49, v126
	v_mov_b32_e32 v101, v127
	v_pk_add_f32 v[104:105], v[104:105], v[104:105] op_sel:[0,1] op_sel_hi:[1,0]
	v_pk_add_f32 v[106:107], v[106:107], v[106:107] op_sel:[0,1] op_sel_hi:[1,0]
	v_add_f32_e32 v40, v52, v53
	v_mov_b32_e32 v5, v42
	v_pk_add_f32 v[102:103], v[102:103], v[108:109]
	v_mov_b32_e32 v65, v128
	v_mov_b32_e32 v117, v129
	v_pk_add_f32 v[48:49], v[48:49], v[100:101]
	v_mov_b32_e32 v105, v130
	v_mov_b32_e32 v107, v131
	ds_bpermute_b32 v42, v92, v40
	v_pk_add_f32 v[64:65], v[64:65], v[116:117]
	v_pk_add_f32 v[48:49], v[48:49], v[102:103]
	v_pk_add_f32 v[52:53], v[104:105], v[106:107]
	v_add_f32_e32 v48, v48, v49
	v_pk_add_f32 v[52:53], v[52:53], v[64:65]
	ds_bpermute_b32 v49, v92, v48
	s_cbranch_execz .Ldry_p0b_real
; __device__ __forceinline__ unsigned pk2(float lo, float hi) { return f2bf(lo) | (f2bf(hi) << 16); }
; __global__ void __launch_bounds__(512, 2) mk_fwd(Args args) {
;     ...
; #pragma unroll
;             for (int o = 1; o < 64; o <<= 1) {
; #pragma unroll
;                 for (int q = 0; q < 4; ++q) s2[q] += __shfl_xor(s2[q], o); }
; #pragma unroll
;             for (int q = 0; q < 4; ++q) {
;                 const float rstd = __builtin_amdgcn_rsqf(s2[q] * (1.f / 1024.f) + RMS_EPS);
;                 u32x2* o8 = (u32x2*)(Hn + (size_t)(m4 + q) * 1024) + lane;
; #pragma unroll
;                 for (int j = 0; j < 4; ++j) { const f32x4 gg = *((const f32x4*)norm_g + lane + 64 * j);
;                     o8[64 * j] = (u32x2){pk2(v[q][j][0] * rstd * gg[0], v[q][j][1] * rstd * gg[1]), pk2(v[q][j][2] * rstd * gg[2], v[q][j][3] * rstd * gg[3])}; }
.Ldry_p0b_c2:
	v_add_f32_e32 v52, v52, v53
	ds_bpermute_b32 v53, v92, v52
	s_waitcnt lgkmcnt(2)
	v_add_f32_e32 v40, v40, v42
	ds_bpermute_b32 v42, v93, v40
	s_waitcnt lgkmcnt(2)
	v_add_f32_e32 v48, v48, v49
	ds_bpermute_b32 v49, v93, v48
	s_waitcnt lgkmcnt(2)
	v_add_f32_e32 v52, v52, v53
	ds_bpermute_b32 v53, v93, v52
	s_waitcnt lgkmcnt(2)
	v_add_f32_e32 v40, v40, v42
	ds_bpermute_b32 v42, v94, v40
	s_waitcnt lgkmcnt(2)
	v_add_f32_e32 v48, v48, v49
	ds_bpermute_b32 v49, v94, v48
	s_waitcnt lgkmcnt(2)
	v_add_f32_e32 v52, v52, v53
	ds_bpermute_b32 v53, v94, v52
	s_waitcnt lgkmcnt(2)
	v_add_f32_e32 v40, v40, v42
	ds_bpermute_b32 v42, v95, v40
	s_waitcnt lgkmcnt(2)
	v_add_f32_e32 v48, v48, v49
	ds_bpermute_b32 v49, v95, v48
	s_waitcnt lgkmcnt(2)
	v_add_f32_e32 v52, v52, v53
	ds_bpermute_b32 v53, v95, v52
	s_waitcnt lgkmcnt(2)
	v_add_f32_e32 v40, v40, v42
	ds_bpermute_b32 v42, v96, v40
	s_waitcnt lgkmcnt(2)
	v_add_f32_e32 v48, v48, v49
	ds_bpermute_b32 v49, v96, v48
	s_waitcnt lgkmcnt(2)
	v_add_f32_e32 v52, v52, v53
	ds_bpermute_b32 v53, v96, v52
	s_waitcnt lgkmcnt(2)
	v_add_f32_e32 v40, v40, v42
	ds_bpermute_b32 v42, v97, v40
	s_waitcnt lgkmcnt(2)
	v_add_f32_e32 v48, v48, v49
	ds_bpermute_b32 v49, v97, v48
	s_waitcnt lgkmcnt(2)
	v_add_f32_e32 v52, v52, v53
	ds_bpermute_b32 v53, v97, v52
	s_waitcnt lgkmcnt(2)
	v_add_f32_e32 v40, v40, v42
	v_fmamk_f32 v40, v40, 0x3a800000, v69
	v_rsq_f32_e32 v42, v40
	s_waitcnt lgkmcnt(1)
	v_add_f32_e32 v40, v48, v49
	v_fmamk_f32 v40, v40, 0x3a800000, v69
	s_waitcnt lgkmcnt(0)
	v_add_f32_e32 v49, v52, v53
	v_rsq_f32_e32 v48, v40
	v_fmamk_f32 v40, v49, 0x3a800000, v69
	v_rsq_f32_e32 v40, v40
	v_pk_mul_f32 v[6:7], v[42:43], v[6:7] op_sel_hi:[0,1]
	v_pk_mul_f32 v[52:53], v[42:43], v[80:81] op_sel_hi:[0,1]
	v_pk_mul_f32 v[6:7], v[18:19], v[6:7]
	v_pk_mul_f32 v[18:19], v[78:79], v[52:53]
	v_pk_mul_f32 v[80:81], v[42:43], v[84:85] op_sel_hi:[0,1]
	v_and_b32_sdwa v49, v18, v98 dst_sel:DWORD dst_unused:UNUSED_PAD src0_sel:WORD_1 src1_sel:DWORD
	v_and_b32_sdwa v84, v7, v98 dst_sel:DWORD dst_unused:UNUSED_PAD src0_sel:WORD_1 src1_sel:DWORD
	v_and_b32_sdwa v85, v6, v98 dst_sel:DWORD dst_unused:UNUSED_PAD src0_sel:WORD_1 src1_sel:DWORD
	v_pk_mul_f32 v[10:11], v[42:43], v[10:11] op_sel_hi:[0,1]
	v_pk_mul_f32 v[14:15], v[42:43], v[14:15] op_sel_hi:[0,1]
	v_pk_mul_f32 v[64:65], v[42:43], v[82:83] op_sel_hi:[0,1]
	v_pk_mul_f32 v[2:3], v[42:43], v[2:3] op_sel_hi:[0,1]
	v_pk_mul_f32 v[82:83], v[42:43], v[86:87] op_sel_hi:[0,1]
	v_and_b32_sdwa v42, v19, v98 dst_sel:DWORD dst_unused:UNUSED_PAD src0_sel:WORD_1 src1_sel:DWORD
	v_pk_mul_f32 v[52:53], v[48:49], v[58:59] op_sel_hi:[0,1]
	v_pk_mul_f32 v[58:59], v[48:49], v[62:63] op_sel_hi:[0,1]
	v_pk_mul_f32 v[62:63], v[48:49], v[66:67] op_sel_hi:[0,1]
	v_pk_mul_f32 v[54:55], v[48:49], v[54:55] op_sel_hi:[0,1]
	v_pk_mul_f32 v[66:67], v[48:49], v[88:89] op_sel_hi:[0,1]
	v_pk_mul_f32 v[56:57], v[48:49], v[56:57] op_sel_hi:[0,1]
	v_pk_mul_f32 v[60:61], v[48:49], v[60:61] op_sel_hi:[0,1]
	s_cbranch_execz .Ldry_p0b_real
.Ldry_p0b_c3:
	v_pk_mul_f32 v[78:79], v[48:49], v[90:91] op_sel_hi:[0,1]
	v_add3_u32 v48, v18, v49, s1
	v_add3_u32 v49, v7, v84, s1
	v_add3_u32 v84, v6, v85, s1
	v_add3_u32 v42, v19, v42, s1
	v_pk_mul_f32 v[6:7], v[40:41], v[50:51] op_sel_hi:[0,1]
	v_and_b32_e32 v49, 0xffff0000, v49
	v_and_b32_e32 v50, 0xffff0000, v84
	v_or_b32_sdwa v49, v49, v42 dst_sel:DWORD dst_unused:UNUSED_PAD src0_sel:DWORD src1_sel:WORD_1
	v_or_b32_sdwa v48, v50, v48 dst_sel:DWORD dst_unused:UNUSED_PAD src0_sel:DWORD src1_sel:WORD_1
	global_store_dwordx2 v[72:73], v[48:49], off
	global_load_dwordx4 v[48:51], v[70:71], off offset:1024
	v_pk_mul_f32 v[18:19], v[40:41], v[122:123] op_sel_hi:[0,1]
	v_mov_b32_e32 v8, v44
	v_mov_b32_e32 v9, v46
	v_mov_b32_e32 v46, v45
	v_mov_b32_e32 v0, v36
	v_mov_b32_e32 v1, v38
	v_mov_b32_e32 v38, v37
	s_waitcnt vmcnt(5)
	v_pk_mul_f32 v[44:45], v[34:35], v[34:35]
	v_pk_mul_f32 v[12:13], v[32:33], v[32:33]
	s_waitcnt vmcnt(4)
	v_pk_mul_f32 v[16:17], v[30:31], v[30:31]
	v_pk_mul_f32 v[36:37], v[28:29], v[28:29]
	s_waitcnt vmcnt(2)
	v_mul_f32_e32 v99, v20, v20
	v_pk_mul_f32 v[0:1], v[40:41], v[0:1] op_sel_hi:[0,1]
	s_waitcnt vmcnt(0)
	v_mov_b32_e32 v85, v50
	v_mov_b32_e32 v50, v49
	v_mov_b32_e32 v84, v48
	v_pk_mul_f32 v[10:11], v[50:51], v[10:11]
	v_pk_mul_f32 v[48:49], v[84:85], v[64:65]
	v_and_b32_sdwa v51, v11, v98 dst_sel:DWORD dst_unused:UNUSED_PAD src0_sel:WORD_1 src1_sel:DWORD
	v_and_b32_sdwa v64, v10, v98 dst_sel:DWORD dst_unused:UNUSED_PAD src0_sel:WORD_1 src1_sel:DWORD
	v_and_b32_sdwa v42, v49, v98 dst_sel:DWORD dst_unused:UNUSED_PAD src0_sel:WORD_1 src1_sel:DWORD
	v_and_b32_sdwa v50, v48, v98 dst_sel:DWORD dst_unused:UNUSED_PAD src0_sel:WORD_1 src1_sel:DWORD
	v_add3_u32 v11, v11, v51, s1
	v_add3_u32 v10, v10, v64, s1
	v_add3_u32 v48, v48, v50, s1
	v_add3_u32 v42, v49, v42, s1
	v_and_b32_e32 v11, 0xffff0000, v11
	v_and_b32_e32 v10, 0xffff0000, v10
	v_or_b32_sdwa v11, v11, v42 dst_sel:DWORD dst_unused:UNUSED_PAD src0_sel:DWORD src1_sel:WORD_1
	v_or_b32_sdwa v10, v10, v48 dst_sel:DWORD dst_unused:UNUSED_PAD src0_sel:DWORD src1_sel:WORD_1
	global_store_dwordx2 v[72:73], v[10:11], off offset:512
	global_load_dwordx4 v[48:51], v[70:71], off offset:2048
	s_waitcnt vmcnt(0)
	v_mov_b32_e32 v11, v50
	v_mov_b32_e32 v50, v49
	v_mov_b32_e32 v10, v48
	v_pk_mul_f32 v[14:15], v[50:51], v[14:15]
	v_pk_mul_f32 v[10:11], v[10:11], v[80:81]
	v_and_b32_sdwa v49, v15, v98 dst_sel:DWORD dst_unused:UNUSED_PAD src0_sel:WORD_1 src1_sel:DWORD
	v_and_b32_sdwa v50, v14, v98 dst_sel:DWORD dst_unused:UNUSED_PAD src0_sel:WORD_1 src1_sel:DWORD
	v_and_b32_sdwa v42, v11, v98 dst_sel:DWORD dst_unused:UNUSED_PAD src0_sel:WORD_1 src1_sel:DWORD
	v_and_b32_sdwa v48, v10, v98 dst_sel:DWORD dst_unused:UNUSED_PAD src0_sel:WORD_1 src1_sel:DWORD
	v_add3_u32 v15, v15, v49, s1
	v_add3_u32 v14, v14, v50, s1
	v_add3_u32 v10, v10, v48, s1
	v_add3_u32 v11, v11, v42, s1
	v_and_b32_e32 v15, 0xffff0000, v15
	v_and_b32_e32 v14, 0xffff0000, v14
	v_or_b32_sdwa v11, v15, v11 dst_sel:DWORD dst_unused:UNUSED_PAD src0_sel:DWORD src1_sel:WORD_1
	v_or_b32_sdwa v10, v14, v10 dst_sel:DWORD dst_unused:UNUSED_PAD src0_sel:DWORD src1_sel:WORD_1
	global_store_dwordx2 v[72:73], v[10:11], off offset:1024
	global_load_dwordx4 v[48:51], v[70:71], off offset:3072
	s_waitcnt vmcnt(0)
	v_mov_b32_e32 v11, v50
	v_mov_b32_e32 v50, v49
	v_mov_b32_e32 v10, v48
	v_pk_mul_f32 v[2:3], v[50:51], v[2:3]
	v_pk_mul_f32 v[10:11], v[10:11], v[82:83]
	v_and_b32_sdwa v42, v3, v98 dst_sel:DWORD dst_unused:UNUSED_PAD src0_sel:WORD_1 src1_sel:DWORD
	v_and_b32_sdwa v48, v2, v98 dst_sel:DWORD dst_unused:UNUSED_PAD src0_sel:WORD_1 src1_sel:DWORD
	v_and_b32_sdwa v14, v11, v98 dst_sel:DWORD dst_unused:UNUSED_PAD src0_sel:WORD_1 src1_sel:DWORD
	v_and_b32_sdwa v15, v10, v98 dst_sel:DWORD dst_unused:UNUSED_PAD src0_sel:WORD_1 src1_sel:DWORD
	v_add3_u32 v3, v3, v42, s1
	s_cbranch_execz .Ldry_p0b_real
; __device__ __forceinline__ unsigned pk2(float lo, float hi) { return f2bf(lo) | (f2bf(hi) << 16); }
; __global__ void __launch_bounds__(512, 2) mk_fwd(Args args) {
;     ...
;             for (int q = 0; q < 4; ++q) {
;                 const float rstd = __builtin_amdgcn_rsqf(s2[q] * (1.f / 1024.f) + RMS_EPS);
;                 u32x2* o8 = (u32x2*)(Hn + (size_t)(m4 + q) * 1024) + lane;
; #pragma unroll
;                 for (int j = 0; j < 4; ++j) { const f32x4 gg = *((const f32x4*)norm_g + lane + 64 * j);
;                     o8[64 * j] = (u32x2){pk2(v[q][j][0] * rstd * gg[0], v[q][j][1] * rstd * gg[1]), pk2(v[q][j][2] * rstd * gg[2], v[q][j][3] * rstd * gg[3])}; }
.Ldry_p0b_c4:
	v_add3_u32 v2, v2, v48, s1
	v_add3_u32 v10, v10, v15, s1
	v_add3_u32 v11, v11, v14, s1
	v_and_b32_e32 v3, 0xffff0000, v3
	v_and_b32_e32 v2, 0xffff0000, v2
	v_or_b32_sdwa v3, v3, v11 dst_sel:DWORD dst_unused:UNUSED_PAD src0_sel:DWORD src1_sel:WORD_1
	v_or_b32_sdwa v2, v2, v10 dst_sel:DWORD dst_unused:UNUSED_PAD src0_sel:DWORD src1_sel:WORD_1
	global_store_dwordx2 v[72:73], v[2:3], off offset:1536
	global_load_dwordx4 v[48:51], v[70:71], off
	s_waitcnt vmcnt(0)
	v_mov_b32_e32 v3, v50
	v_mov_b32_e32 v50, v49
	v_mov_b32_e32 v2, v48
	v_pk_mul_f32 v[10:11], v[50:51], v[52:53]
	v_pk_mul_f32 v[2:3], v[2:3], v[66:67]
	v_and_b32_sdwa v42, v11, v98 dst_sel:DWORD dst_unused:UNUSED_PAD src0_sel:WORD_1 src1_sel:DWORD
	v_and_b32_sdwa v48, v10, v98 dst_sel:DWORD dst_unused:UNUSED_PAD src0_sel:WORD_1 src1_sel:DWORD
	v_and_b32_sdwa v14, v3, v98 dst_sel:DWORD dst_unused:UNUSED_PAD src0_sel:WORD_1 src1_sel:DWORD
	v_and_b32_sdwa v15, v2, v98 dst_sel:DWORD dst_unused:UNUSED_PAD src0_sel:WORD_1 src1_sel:DWORD
	v_add3_u32 v11, v11, v42, s1
	v_add3_u32 v10, v10, v48, s1
	v_add3_u32 v2, v2, v15, s1
	v_add3_u32 v3, v3, v14, s1
	v_and_b32_e32 v11, 0xffff0000, v11
	v_and_b32_e32 v10, 0xffff0000, v10
	v_or_b32_sdwa v3, v11, v3 dst_sel:DWORD dst_unused:UNUSED_PAD src0_sel:DWORD src1_sel:WORD_1
	v_or_b32_sdwa v2, v10, v2 dst_sel:DWORD dst_unused:UNUSED_PAD src0_sel:DWORD src1_sel:WORD_1
	global_store_dwordx2 v[72:73], v[2:3], off offset:2048
	global_load_dwordx4 v[48:51], v[70:71], off offset:1024
	s_waitcnt vmcnt(0)
	v_mov_b32_e32 v3, v50
	v_mov_b32_e32 v50, v49
	v_mov_b32_e32 v2, v48
	v_pk_mul_f32 v[10:11], v[50:51], v[58:59]
	v_pk_mul_f32 v[2:3], v[2:3], v[56:57]
	v_and_b32_sdwa v42, v11, v98 dst_sel:DWORD dst_unused:UNUSED_PAD src0_sel:WORD_1 src1_sel:DWORD
	v_and_b32_sdwa v48, v10, v98 dst_sel:DWORD dst_unused:UNUSED_PAD src0_sel:WORD_1 src1_sel:DWORD
	v_and_b32_sdwa v14, v3, v98 dst_sel:DWORD dst_unused:UNUSED_PAD src0_sel:WORD_1 src1_sel:DWORD
	v_and_b32_sdwa v15, v2, v98 dst_sel:DWORD dst_unused:UNUSED_PAD src0_sel:WORD_1 src1_sel:DWORD
	v_add3_u32 v11, v11, v42, s1
	v_add3_u32 v10, v10, v48, s1
	v_add3_u32 v2, v2, v15, s1
	v_add3_u32 v3, v3, v14, s1
	v_and_b32_e32 v11, 0xffff0000, v11
	v_and_b32_e32 v10, 0xffff0000, v10
	v_or_b32_sdwa v3, v11, v3 dst_sel:DWORD dst_unused:UNUSED_PAD src0_sel:DWORD src1_sel:WORD_1
	v_or_b32_sdwa v2, v10, v2 dst_sel:DWORD dst_unused:UNUSED_PAD src0_sel:DWORD src1_sel:WORD_1
	global_store_dwordx2 v[72:73], v[2:3], off offset:2560
	global_load_dwordx4 v[48:51], v[70:71], off offset:2048
	s_waitcnt vmcnt(0)
	v_mov_b32_e32 v3, v50
	v_mov_b32_e32 v50, v49
	v_mov_b32_e32 v2, v48
	v_pk_mul_f32 v[10:11], v[50:51], v[62:63]
	v_pk_mul_f32 v[2:3], v[2:3], v[60:61]
	v_and_b32_sdwa v42, v11, v98 dst_sel:DWORD dst_unused:UNUSED_PAD src0_sel:WORD_1 src1_sel:DWORD
	v_and_b32_sdwa v48, v10, v98 dst_sel:DWORD dst_unused:UNUSED_PAD src0_sel:WORD_1 src1_sel:DWORD
	v_and_b32_sdwa v14, v3, v98 dst_sel:DWORD dst_unused:UNUSED_PAD src0_sel:WORD_1 src1_sel:DWORD
	v_and_b32_sdwa v15, v2, v98 dst_sel:DWORD dst_unused:UNUSED_PAD src0_sel:WORD_1 src1_sel:DWORD
	v_add3_u32 v11, v11, v42, s1
	v_add3_u32 v10, v10, v48, s1
	v_add3_u32 v2, v2, v15, s1
	v_add3_u32 v3, v3, v14, s1
	v_and_b32_e32 v11, 0xffff0000, v11
	v_and_b32_e32 v10, 0xffff0000, v10
	v_or_b32_sdwa v3, v11, v3 dst_sel:DWORD dst_unused:UNUSED_PAD src0_sel:DWORD src1_sel:WORD_1
	v_or_b32_sdwa v2, v10, v2 dst_sel:DWORD dst_unused:UNUSED_PAD src0_sel:DWORD src1_sel:WORD_1
	global_store_dwordx2 v[72:73], v[2:3], off offset:3072
	global_load_dwordx4 v[48:51], v[70:71], off offset:3072
	s_waitcnt vmcnt(0)
	v_mov_b32_e32 v3, v50
	v_mov_b32_e32 v50, v49
	v_mov_b32_e32 v2, v48
	v_pk_mul_f32 v[10:11], v[50:51], v[54:55]
	v_pk_mul_f32 v[2:3], v[2:3], v[78:79]
	v_and_b32_sdwa v42, v11, v98 dst_sel:DWORD dst_unused:UNUSED_PAD src0_sel:WORD_1 src1_sel:DWORD
	v_and_b32_sdwa v48, v10, v98 dst_sel:DWORD dst_unused:UNUSED_PAD src0_sel:WORD_1 src1_sel:DWORD
	v_and_b32_sdwa v14, v3, v98 dst_sel:DWORD dst_unused:UNUSED_PAD src0_sel:WORD_1 src1_sel:DWORD
	v_and_b32_sdwa v15, v2, v98 dst_sel:DWORD dst_unused:UNUSED_PAD src0_sel:WORD_1 src1_sel:DWORD
	v_add3_u32 v11, v11, v42, s1
	s_cbranch_execz .Ldry_p0b_real
.Ldry_p0b_c5:
	v_add3_u32 v10, v10, v48, s1
	v_add3_u32 v2, v2, v15, s1
	v_add3_u32 v3, v3, v14, s1
	v_and_b32_e32 v11, 0xffff0000, v11
	v_and_b32_e32 v10, 0xffff0000, v10
	v_or_b32_sdwa v3, v11, v3 dst_sel:DWORD dst_unused:UNUSED_PAD src0_sel:DWORD src1_sel:WORD_1
	v_or_b32_sdwa v2, v10, v2 dst_sel:DWORD dst_unused:UNUSED_PAD src0_sel:DWORD src1_sel:WORD_1
	global_store_dwordx2 v[72:73], v[2:3], off offset:3584
	global_load_dwordx4 v[48:51], v[70:71], off
	v_mov_b32_e32 v42, v41
	v_lshl_add_u64 v[72:73], v[72:73], 0, s[12:13]
	s_waitcnt vmcnt(0)
	v_mov_b32_e32 v3, v50
	v_mov_b32_e32 v50, v49
	v_mov_b32_e32 v2, v48
	v_pk_mul_f32 v[6:7], v[50:51], v[6:7]
	v_pk_mul_f32 v[2:3], v[2:3], v[18:19]
	v_and_b32_sdwa v14, v7, v98 dst_sel:DWORD dst_unused:UNUSED_PAD src0_sel:WORD_1 src1_sel:DWORD
	v_and_b32_sdwa v15, v6, v98 dst_sel:DWORD dst_unused:UNUSED_PAD src0_sel:WORD_1 src1_sel:DWORD
	v_and_b32_sdwa v10, v3, v98 dst_sel:DWORD dst_unused:UNUSED_PAD src0_sel:WORD_1 src1_sel:DWORD
	v_and_b32_sdwa v11, v2, v98 dst_sel:DWORD dst_unused:UNUSED_PAD src0_sel:WORD_1 src1_sel:DWORD
	v_add3_u32 v7, v7, v14, s1
	v_add3_u32 v6, v6, v15, s1
	v_add3_u32 v2, v2, v11, s1
	v_add3_u32 v3, v3, v10, s1
	v_and_b32_e32 v7, 0xffff0000, v7
	v_and_b32_e32 v6, 0xffff0000, v6
	v_or_b32_sdwa v3, v7, v3 dst_sel:DWORD dst_unused:UNUSED_PAD src0_sel:DWORD src1_sel:WORD_1
	v_or_b32_sdwa v2, v6, v2 dst_sel:DWORD dst_unused:UNUSED_PAD src0_sel:DWORD src1_sel:WORD_1
	global_store_dwordx2 v[76:77], v[2:3], off
	global_load_dwordx4 v[48:51], v[70:71], off offset:1024
	v_pk_mul_f32 v[2:3], v[40:41], v[8:9] op_sel_hi:[0,1]
	v_pk_mul_f32 v[6:7], v[40:41], v[46:47] op_sel_hi:[0,1]
	v_mov_b32_e32 v18, v32
	v_mov_b32_e32 v19, v34
	v_mov_b32_e32 v34, v33
	v_pk_mov_b32 v[32:33], v[12:13], v[44:45] op_sel:[1,0]
	v_mov_b32_e32 v13, v45
	v_mul_f32_e32 v15, v21, v21
	v_mul_f32_e32 v14, v27, v27
	v_pk_add_f32 v[12:13], v[32:33], v[12:13]
	v_mul_f32_e32 v46, v22, v22
	v_mul_f32_e32 v47, v23, v23
	v_pk_add_f32 v[12:13], v[12:13], v[12:13] op_sel:[0,1] op_sel_hi:[1,0]
	s_waitcnt vmcnt(0)
; __device__ __forceinline__ unsigned pk2(float lo, float hi) { return f2bf(lo) | (f2bf(hi) << 16); }
; __global__ void __launch_bounds__(512, 2) mk_fwd(Args args) {
;     ...
;         for (int m4 = gw * 4; m4 < M_TOK; m4 += NGW * 4) {
;             f32x4 v[4][4]; float s2[4];
; #pragma unroll
;             for (int q = 0; q < 4; ++q) { const f32x4* xr = (const f32x4*)(x + (size_t)(m4 + q) * 1024) + lane;
; #pragma unroll
;                 for (int j = 0; j < 4; ++j) v[q][j] = xr[64 * j]; }
; #pragma unroll
;             for (int q = 0; q < 4; ++q) { s2[q] = 0.f;
; #pragma unroll
;                 for (int j = 0; j < 4; ++j) s2[q] += (v[q][j][0] * v[q][j][0] + v[q][j][1] * v[q][j][1]) + (v[q][j][2] * v[q][j][2] + v[q][j][3] * v[q][j][3]); }
; #pragma unroll
;             for (int o = 1; o < 64; o <<= 1) {
; #pragma unroll
;                 for (int q = 0; q < 4; ++q) s2[q] += __shfl_xor(s2[q], o); }
; #pragma unroll
;             for (int q = 0; q < 4; ++q) {
;                 const float rstd = __builtin_amdgcn_rsqf(s2[q] * (1.f / 1024.f) + RMS_EPS);
;                 u32x2* o8 = (u32x2*)(Hn + (size_t)(m4 + q) * 1024) + lane;
; #pragma unroll
;                 for (int j = 0; j < 4; ++j) { const f32x4 gg = *((const f32x4*)norm_g + lane + 64 * j);
;                     o8[64 * j] = (u32x2){pk2(v[q][j][0] * rstd * gg[0], v[q][j][1] * rstd * gg[1]), pk2(v[q][j][2] * rstd * gg[2], v[q][j][3] * rstd * gg[3])}; }
	v_mov_b32_e32 v9, v50
	v_mov_b32_e32 v50, v49
	v_mov_b32_e32 v8, v48
	v_pk_mul_f32 v[6:7], v[50:51], v[6:7]
	v_pk_mul_f32 v[2:3], v[8:9], v[2:3]
	v_and_b32_sdwa v10, v7, v98 dst_sel:DWORD dst_unused:UNUSED_PAD src0_sel:WORD_1 src1_sel:DWORD
	v_and_b32_sdwa v11, v6, v98 dst_sel:DWORD dst_unused:UNUSED_PAD src0_sel:WORD_1 src1_sel:DWORD
	v_and_b32_sdwa v8, v3, v98 dst_sel:DWORD dst_unused:UNUSED_PAD src0_sel:WORD_1 src1_sel:DWORD
	v_and_b32_sdwa v9, v2, v98 dst_sel:DWORD dst_unused:UNUSED_PAD src0_sel:WORD_1 src1_sel:DWORD
	v_add3_u32 v7, v7, v10, s1
	v_add3_u32 v6, v6, v11, s1
	v_add3_u32 v2, v2, v9, s1
	v_add3_u32 v3, v3, v8, s1
	v_and_b32_e32 v7, 0xffff0000, v7
	v_and_b32_e32 v6, 0xffff0000, v6
	v_or_b32_sdwa v3, v7, v3 dst_sel:DWORD dst_unused:UNUSED_PAD src0_sel:DWORD src1_sel:WORD_1
	v_or_b32_sdwa v2, v6, v2 dst_sel:DWORD dst_unused:UNUSED_PAD src0_sel:DWORD src1_sel:WORD_1
	global_store_dwordx2 v[76:77], v[2:3], off offset:512
	global_load_dwordx4 v[6:9], v[70:71], off offset:2048
	v_pk_mul_f32 v[2:3], v[40:41], v[4:5] op_sel_hi:[0,1]
	v_pk_mul_f32 v[4:5], v[40:41], v[42:43] op_sel_hi:[0,1]
	v_mul_f32_e32 v10, v25, v25
	v_mov_b32_e32 v13, v99
	s_waitcnt vmcnt(0)
	v_mov_b32_e32 v43, v8
	v_mov_b32_e32 v8, v7
	v_mov_b32_e32 v42, v6
	v_pk_mul_f32 v[4:5], v[8:9], v[4:5]
	v_pk_mul_f32 v[2:3], v[42:43], v[2:3]
	v_and_b32_sdwa v8, v5, v98 dst_sel:DWORD dst_unused:UNUSED_PAD src0_sel:WORD_1 src1_sel:DWORD
	v_and_b32_sdwa v9, v4, v98 dst_sel:DWORD dst_unused:UNUSED_PAD src0_sel:WORD_1 src1_sel:DWORD
	v_and_b32_sdwa v6, v3, v98 dst_sel:DWORD dst_unused:UNUSED_PAD src0_sel:WORD_1 src1_sel:DWORD
	v_and_b32_sdwa v7, v2, v98 dst_sel:DWORD dst_unused:UNUSED_PAD src0_sel:WORD_1 src1_sel:DWORD
	v_add3_u32 v5, v5, v8, s1
	v_add3_u32 v4, v4, v9, s1
	s_cbranch_execz .Ldry_p0b_real
.Ldry_p0b_c6:
	v_add3_u32 v2, v2, v7, s1
	v_add3_u32 v3, v3, v6, s1
	v_and_b32_e32 v5, 0xffff0000, v5
	v_and_b32_e32 v4, 0xffff0000, v4
	v_or_b32_sdwa v3, v5, v3 dst_sel:DWORD dst_unused:UNUSED_PAD src0_sel:DWORD src1_sel:WORD_1
	v_or_b32_sdwa v2, v4, v2 dst_sel:DWORD dst_unused:UNUSED_PAD src0_sel:DWORD src1_sel:WORD_1
	global_store_dwordx2 v[76:77], v[2:3], off offset:1024
	global_load_dwordx4 v[2:5], v[70:71], off offset:3072
	v_pk_mov_b32 v[6:7], v[36:37], v[16:17] op_sel:[1,0]
	v_mov_b32_e32 v37, v17
	v_pk_add_f32 v[6:7], v[6:7], v[36:37]
	v_pk_fma_f32 v[8:9], v[24:25], v[24:25], v[10:11] op_sel_hi:[1,1,0]
	v_pk_fma_f32 v[10:11], v[26:27], v[26:27], v[14:15] op_sel_hi:[1,1,0]
	v_pk_add_f32 v[6:7], v[6:7], v[6:7] op_sel:[0,1] op_sel_hi:[1,0]
	v_mov_b32_e32 v9, v46
	v_mov_b32_e32 v11, v47
	v_mov_b32_e32 v7, v15
	v_pk_add_f32 v[8:9], v[8:9], v[10:11]
	v_pk_add_f32 v[6:7], v[12:13], v[6:7]
	s_nop 0
	v_pk_add_f32 v[6:7], v[6:7], v[8:9]
	s_waitcnt vmcnt(0)
	v_mov_b32_e32 v9, v4
	v_add_f32_e32 v6, v6, v7
	ds_bpermute_b32 v7, v92, v6
	v_mov_b32_e32 v4, v3
	v_mov_b32_e32 v8, v2
	v_pk_mul_f32 v[0:1], v[8:9], v[0:1]
	s_waitcnt lgkmcnt(0)
	v_add_f32_e32 v10, v6, v7
	v_pk_mul_f32 v[6:7], v[40:41], v[38:39] op_sel_hi:[0,1]
	v_pk_mul_f32 v[2:3], v[4:5], v[6:7]
	v_and_b32_sdwa v4, v1, v98 dst_sel:DWORD dst_unused:UNUSED_PAD src0_sel:WORD_1 src1_sel:DWORD
	v_and_b32_sdwa v6, v3, v98 dst_sel:DWORD dst_unused:UNUSED_PAD src0_sel:WORD_1 src1_sel:DWORD
	v_and_b32_sdwa v7, v2, v98 dst_sel:DWORD dst_unused:UNUSED_PAD src0_sel:WORD_1 src1_sel:DWORD
	v_and_b32_sdwa v5, v0, v98 dst_sel:DWORD dst_unused:UNUSED_PAD src0_sel:WORD_1 src1_sel:DWORD
	v_add3_u32 v3, v3, v6, s1
	v_add3_u32 v2, v2, v7, s1
	v_add3_u32 v0, v0, v5, s1
	v_add3_u32 v1, v1, v4, s1
	v_and_b32_e32 v3, 0xffff0000, v3
	v_and_b32_e32 v2, 0xffff0000, v2
	v_or_b32_sdwa v1, v3, v1 dst_sel:DWORD dst_unused:UNUSED_PAD src0_sel:DWORD src1_sel:WORD_1
	v_or_b32_sdwa v0, v2, v0 dst_sel:DWORD dst_unused:UNUSED_PAD src0_sel:DWORD src1_sel:WORD_1
	global_store_dwordx2 v[76:77], v[0:1], off offset:1536
	global_load_dwordx4 v[0:3], v[70:71], off
	ds_bpermute_b32 v4, v93, v10
	s_waitcnt lgkmcnt(0)
	v_add_f32_e32 v4, v10, v4
	ds_bpermute_b32 v5, v94, v4
	s_waitcnt lgkmcnt(0)
	v_add_f32_e32 v4, v4, v5
	ds_bpermute_b32 v5, v95, v4
	s_waitcnt lgkmcnt(0)
	v_add_f32_e32 v4, v4, v5
	ds_bpermute_b32 v5, v96, v4
	s_waitcnt lgkmcnt(0)
	v_add_f32_e32 v4, v4, v5
	ds_bpermute_b32 v5, v97, v4
	s_waitcnt lgkmcnt(0)
	v_add_f32_e32 v4, v4, v5
	v_fmamk_f32 v4, v4, 0x3a800000, v69
	v_rsq_f32_e32 v4, v4
	s_waitcnt vmcnt(0)
	v_mov_b32_e32 v11, v2
	v_pk_mul_f32 v[8:9], v[4:5], v[34:35] op_sel_hi:[0,1]
	v_mov_b32_e32 v2, v1
	v_pk_mul_f32 v[6:7], v[4:5], v[18:19] op_sel_hi:[0,1]
	v_mov_b32_e32 v10, v0
	v_pk_mul_f32 v[2:3], v[2:3], v[8:9]
	v_pk_mul_f32 v[0:1], v[10:11], v[6:7]
	v_and_b32_sdwa v7, v3, v98 dst_sel:DWORD dst_unused:UNUSED_PAD src0_sel:WORD_1 src1_sel:DWORD
	v_and_b32_sdwa v8, v2, v98 dst_sel:DWORD dst_unused:UNUSED_PAD src0_sel:WORD_1 src1_sel:DWORD
	v_and_b32_sdwa v5, v1, v98 dst_sel:DWORD dst_unused:UNUSED_PAD src0_sel:WORD_1 src1_sel:DWORD
	v_and_b32_sdwa v6, v0, v98 dst_sel:DWORD dst_unused:UNUSED_PAD src0_sel:WORD_1 src1_sel:DWORD
	v_add3_u32 v3, v3, v7, s1
	v_add3_u32 v2, v2, v8, s1
	v_add3_u32 v0, v0, v6, s1
	v_add3_u32 v1, v1, v5, s1
	s_cbranch_execz .Ldry_p0b_real
; __device__ __forceinline__ unsigned pk2(float lo, float hi) { return f2bf(lo) | (f2bf(hi) << 16); }
; __global__ void __launch_bounds__(512, 2) mk_fwd(Args args) {
;     ...
;             for (int q = 0; q < 4; ++q) {
;                 const float rstd = __builtin_amdgcn_rsqf(s2[q] * (1.f / 1024.f) + RMS_EPS);
;                 u32x2* o8 = (u32x2*)(Hn + (size_t)(m4 + q) * 1024) + lane;
; #pragma unroll
;                 for (int j = 0; j < 4; ++j) { const f32x4 gg = *((const f32x4*)norm_g + lane + 64 * j);
;                     o8[64 * j] = (u32x2){pk2(v[q][j][0] * rstd * gg[0], v[q][j][1] * rstd * gg[1]), pk2(v[q][j][2] * rstd * gg[2], v[q][j][3] * rstd * gg[3])}; }
;             }
;         }
.Ldry_p0b_c7:
	v_and_b32_e32 v3, 0xffff0000, v3
	v_and_b32_e32 v2, 0xffff0000, v2
	v_or_b32_sdwa v1, v3, v1 dst_sel:DWORD dst_unused:UNUSED_PAD src0_sel:DWORD src1_sel:WORD_1
	v_or_b32_sdwa v0, v2, v0 dst_sel:DWORD dst_unused:UNUSED_PAD src0_sel:DWORD src1_sel:WORD_1
	global_store_dwordx2 v[76:77], v[0:1], off offset:2048
	global_load_dwordx4 v[0:3], v[70:71], off offset:1024
	v_mov_b32_e32 v7, v30
	v_mov_b32_e32 v30, v29
	v_mov_b32_e32 v6, v28
	v_pk_mul_f32 v[8:9], v[4:5], v[30:31] op_sel_hi:[0,1]
	v_pk_mul_f32 v[6:7], v[4:5], v[6:7] op_sel_hi:[0,1]
	s_waitcnt vmcnt(0)
	v_mov_b32_e32 v11, v2
	v_mov_b32_e32 v2, v1
	v_mov_b32_e32 v10, v0
	v_pk_mul_f32 v[2:3], v[2:3], v[8:9]
	v_pk_mul_f32 v[0:1], v[10:11], v[6:7]
	v_and_b32_sdwa v7, v3, v98 dst_sel:DWORD dst_unused:UNUSED_PAD src0_sel:WORD_1 src1_sel:DWORD
	v_and_b32_sdwa v8, v2, v98 dst_sel:DWORD dst_unused:UNUSED_PAD src0_sel:WORD_1 src1_sel:DWORD
	v_and_b32_sdwa v5, v1, v98 dst_sel:DWORD dst_unused:UNUSED_PAD src0_sel:WORD_1 src1_sel:DWORD
	v_and_b32_sdwa v6, v0, v98 dst_sel:DWORD dst_unused:UNUSED_PAD src0_sel:WORD_1 src1_sel:DWORD
	v_add3_u32 v3, v3, v7, s1
	v_add3_u32 v2, v2, v8, s1
	v_add3_u32 v0, v0, v6, s1
	v_add3_u32 v1, v1, v5, s1
	v_and_b32_e32 v3, 0xffff0000, v3
	v_and_b32_e32 v2, 0xffff0000, v2
	v_or_b32_sdwa v1, v3, v1 dst_sel:DWORD dst_unused:UNUSED_PAD src0_sel:DWORD src1_sel:WORD_1
	v_or_b32_sdwa v0, v2, v0 dst_sel:DWORD dst_unused:UNUSED_PAD src0_sel:DWORD src1_sel:WORD_1
	global_store_dwordx2 v[76:77], v[0:1], off offset:2560
	global_load_dwordx4 v[0:3], v[70:71], off offset:2048
	v_mov_b32_e32 v7, v26
	v_mov_b32_e32 v26, v25
	v_mov_b32_e32 v6, v24
	v_pk_mul_f32 v[8:9], v[4:5], v[26:27] op_sel_hi:[0,1]
	v_pk_mul_f32 v[6:7], v[4:5], v[6:7] op_sel_hi:[0,1]
	s_waitcnt vmcnt(0)
	v_mov_b32_e32 v11, v2
	v_mov_b32_e32 v2, v1
	v_mov_b32_e32 v10, v0
	v_pk_mul_f32 v[2:3], v[2:3], v[8:9]
	v_pk_mul_f32 v[0:1], v[10:11], v[6:7]
	v_and_b32_sdwa v7, v3, v98 dst_sel:DWORD dst_unused:UNUSED_PAD src0_sel:WORD_1 src1_sel:DWORD
	v_and_b32_sdwa v8, v2, v98 dst_sel:DWORD dst_unused:UNUSED_PAD src0_sel:WORD_1 src1_sel:DWORD
	v_and_b32_sdwa v5, v1, v98 dst_sel:DWORD dst_unused:UNUSED_PAD src0_sel:WORD_1 src1_sel:DWORD
	v_and_b32_sdwa v6, v0, v98 dst_sel:DWORD dst_unused:UNUSED_PAD src0_sel:WORD_1 src1_sel:DWORD
	v_add3_u32 v3, v3, v7, s1
	v_add3_u32 v2, v2, v8, s1
	v_add3_u32 v0, v0, v6, s1
	v_add3_u32 v1, v1, v5, s1
	v_and_b32_e32 v3, 0xffff0000, v3
	v_and_b32_e32 v2, 0xffff0000, v2
	v_or_b32_sdwa v1, v3, v1 dst_sel:DWORD dst_unused:UNUSED_PAD src0_sel:DWORD src1_sel:WORD_1
	v_or_b32_sdwa v0, v2, v0 dst_sel:DWORD dst_unused:UNUSED_PAD src0_sel:DWORD src1_sel:WORD_1
	global_store_dwordx2 v[76:77], v[0:1], off offset:3072
	global_load_dwordx4 v[0:3], v[70:71], off offset:3072
	v_mov_b32_e32 v6, v20
	v_mov_b32_e32 v7, v22
	v_mov_b32_e32 v22, v21
	v_pk_mul_f32 v[6:7], v[4:5], v[6:7] op_sel_hi:[0,1]
	v_pk_mul_f32 v[4:5], v[4:5], v[22:23] op_sel_hi:[0,1]
	s_waitcnt vmcnt(0)
	v_mov_b32_e32 v9, v2
	v_mov_b32_e32 v2, v1
	v_mov_b32_e32 v8, v0
	v_pk_mul_f32 v[2:3], v[2:3], v[4:5]
	v_pk_mul_f32 v[0:1], v[8:9], v[6:7]
	v_and_b32_sdwa v6, v3, v98 dst_sel:DWORD dst_unused:UNUSED_PAD src0_sel:WORD_1 src1_sel:DWORD
	v_and_b32_sdwa v7, v2, v98 dst_sel:DWORD dst_unused:UNUSED_PAD src0_sel:WORD_1 src1_sel:DWORD
	v_and_b32_sdwa v4, v1, v98 dst_sel:DWORD dst_unused:UNUSED_PAD src0_sel:WORD_1 src1_sel:DWORD
	v_and_b32_sdwa v5, v0, v98 dst_sel:DWORD dst_unused:UNUSED_PAD src0_sel:WORD_1 src1_sel:DWORD
	v_add3_u32 v3, v3, v6, s1
	v_add3_u32 v2, v2, v7, s1
	v_add3_u32 v0, v0, v5, s1
	v_add3_u32 v1, v1, v4, s1
	v_and_b32_e32 v3, 0xffff0000, v3
	v_and_b32_e32 v2, 0xffff0000, v2
	v_or_b32_sdwa v1, v3, v1 dst_sel:DWORD dst_unused:UNUSED_PAD src0_sel:DWORD src1_sel:WORD_1
	v_or_b32_sdwa v0, v2, v0 dst_sel:DWORD dst_unused:UNUSED_PAD src0_sel:DWORD src1_sel:WORD_1
	global_store_dwordx2 v[76:77], v[0:1], off offset:3584
	s_cbranch_execz .Ldry_p0b_real
	s_andn2_b64 exec, exec, s[16:17]
	s_cbranch_execnz .LBB0_12

; __device__ __forceinline__ float bf2f(unsigned u) { return __uint_as_float(u << 16); }
; template <bool FULL>
; __device__ __forceinline__ void hg_load(HgRegs& R, size_t m0, int h, const float* G, const bf16_t* HQ, const bf16_t* HI) {
;     const int tid = threadIdx.x, k = tid & 127, part = tid >> 7;
;     const size_t base = (m0 + 16 * part) * 1024 + h * 128 + k;
; #pragma unroll
;     for (int i = 0; i < 16; ++i) R.gv[i] = bf2f(((const bf16_t*)G)[base + (size_t)i * 1024]);
; #pragma unroll
;     for (int i = 0; i < 16; ++i) R.vv[i] = HI[base + (size_t)i * 1024];
; __device__ __forceinline__ void hg_unit_a(LAS unsigned char* lds, int unit, const float* G, const bf16_t* HI, float* ST, float* DG, unsigned* cnt) {
;     const int tid = threadIdx.x, lane = tid & 63, w = tid >> 6, r = lane & 15, g = lane >> 4;
;     const int bh = unit >> 5, c = unit & 31, b = bh >> 3, h = bh & 7;
;     f32x4 S[8];
; #pragma unroll
;     for (int i = 0; i < 8; ++i) S[i] = (f32x4){0.f, 0.f, 0.f, 0.f};
;     float cumtot = 0.f;
;     HgRegs R;
;     const size_t mu = (size_t)b * SEQ + c * 256;
;     hg_load<false>(R, mu, h, G, nullptr, HI);
.LBB0_209:
	s_bitcmp1_b32 s99, 0
	s_cbranch_scc1 .Ldry_hga1_skip
	s_bitset1_b32 s99, 0
	s_mov_b64 s[100:101], exec
	v_readfirstlane_b32 s98, v200
	s_nop 0
	s_lshr_b32 s98, s98, 6
	s_cmp_eq_u32 s98, 0
	s_cbranch_scc1 .Ldry_hga1_real
	s_mov_b64 exec, 0
	s_cmp_eq_u32 s98, 1
	s_cbranch_scc1 .Ldry_hga1_c1
	s_cmp_eq_u32 s98, 2
	s_cbranch_scc1 .Ldry_hga1_c2
	s_cmp_eq_u32 s98, 3
	s_cbranch_scc1 .Ldry_hga1_c3
	s_cmp_eq_u32 s98, 4
	s_cbranch_scc1 .Ldry_hga1_c4
	s_cmp_eq_u32 s98, 5
	s_cbranch_scc1 .Ldry_hga1_c5
	s_cmp_eq_u32 s98, 6
	s_cbranch_scc1 .Ldry_hga1_c6
	s_branch .Ldry_hga1_c7
.Ldry_hga1_real:
	s_mov_b64 exec, s[100:101]
.Ldry_hga1_skip:
	s_ashr_i32 s16, s14, 8
	s_ashr_i32 s17, s16, 31
	s_lshl_b32 s1, s14, 8
	s_lshl_b64 s[18:19], s[16:17], 13
	s_and_b32 s1, s1, 0x1f00
	s_ashr_i32 s40, s14, 5
	s_or_b32 s1, s18, s1
	v_mov_b32_e32 v1, s19
	v_or_b32_e32 v0, s1, v34
	s_lshl_b32 s1, s40, 7
	v_lshlrev_b64 v[0:1], 10, v[0:1]
	s_and_b32 s1, s1, 0x380
	v_or_b32_e32 v0, s1, v0
	v_or_b32_e32 v0, v0, v32
	v_lshlrev_b64 v[0:1], 1, v[0:1]
	v_lshl_add_u64 v[2:3], s[64:65], 0, v[0:1]
	v_add_co_u32_e32 v4, vcc, s28, v2
	v_lshl_add_u64 v[0:1], s[42:43], 0, v[0:1]
	s_nop 0
	s_cbranch_execz .Ldry_hga1_real
.Ldry_hga1_c1:
	v_addc_co_u32_e32 v5, vcc, 0, v3, vcc
	v_add_co_u32_e32 v6, vcc, s30, v2
	s_lshl_b32 s1, s26, 11
	s_nop 0
	v_addc_co_u32_e32 v7, vcc, 0, v3, vcc
	v_add_co_u32_e32 v8, vcc, s34, v2
	s_and_b32 s1, s1, 0xf80000
	s_nop 0
	v_addc_co_u32_e32 v9, vcc, 0, v3, vcc
	v_add_co_u32_e32 v10, vcc, s36, v2
	s_lshl_b64 s[16:17], s[16:17], 24
	s_nop 0
	v_addc_co_u32_e32 v11, vcc, 0, v3, vcc
	global_load_ushort v14, v[2:3], off offset:2048
	global_load_ushort v15, v[4:5], off offset:2048
	global_load_ushort v16, v[6:7], off offset:2048
	global_load_ushort v17, v[8:9], off offset:2048
	global_load_ushort v18, v[10:11], off
	global_load_ushort v19, v[2:3], off
	s_cbranch_execz .Ldry_hga1_real
.Ldry_hga1_c2:
	v_add_co_u32_e32 v4, vcc, s29, v2
	s_lshl_b32 s3, s40, 8
	s_nop 0
	v_addc_co_u32_e32 v5, vcc, 0, v3, vcc
	v_add_co_u32_e32 v6, vcc, s31, v2
	s_or_b32 s1, s16, s1
	s_nop 0
	v_addc_co_u32_e32 v7, vcc, 0, v3, vcc
	v_add_co_u32_e32 v2, vcc, s35, v2
	s_and_b32 s3, s3, 0x700
	s_nop 0
	v_addc_co_u32_e32 v3, vcc, 0, v3, vcc
	global_load_ushort v20, v[4:5], off offset:-4096
	global_load_ushort v21, v[6:7], off offset:-4096
	global_load_ushort v22, v[2:3], off offset:-4096
	global_load_ushort v23, v[2:3], off
	global_load_ushort v24, v[6:7], off
	global_load_ushort v25, v[4:5], off
	global_load_ushort v26, v[4:5], off offset:2048
	s_cbranch_execz .Ldry_hga1_real
.Ldry_hga1_c3:
	global_load_ushort v27, v[6:7], off offset:2048
	global_load_ushort v28, v[10:11], off offset:2048
	global_load_ushort v29, v[2:3], off offset:2048
	v_add_co_u32_e32 v2, vcc, s28, v0
	s_or_b32 s16, s1, s3
	s_nop 0
	v_addc_co_u32_e32 v3, vcc, 0, v1, vcc
	v_add_co_u32_e32 v4, vcc, s29, v0
	v_lshl_add_u64 v[42:43], v[38:39], 0, s[16:17]
	s_nop 0
	v_addc_co_u32_e32 v5, vcc, 0, v1, vcc
	v_add_co_u32_e32 v6, vcc, s30, v0
	v_lshl_add_u64 v[44:45], v[40:41], 0, s[16:17]
	s_nop 0
	v_addc_co_u32_e32 v7, vcc, 0, v1, vcc
	v_add_co_u32_e32 v8, vcc, s31, v0
	s_mov_b64 s[16:17], 0
	s_nop 0
	v_addc_co_u32_e32 v9, vcc, 0, v1, vcc
	s_cbranch_execz .Ldry_hga1_real
.Ldry_hga1_c4:
	v_add_co_u32_e32 v10, vcc, s34, v0
	v_mov_b32_e32 v91, 0
	s_nop 0
	v_addc_co_u32_e32 v11, vcc, 0, v1, vcc
	v_add_co_u32_e32 v12, vcc, s35, v0
	v_mov_b32_e32 v30, v37
	s_nop 0
	v_addc_co_u32_e32 v13, vcc, 0, v1, vcc
	global_load_ushort v92, v[4:5], off offset:-4096
	global_load_ushort v93, v[4:5], off
	global_load_ushort v94, v[4:5], off offset:2048
	global_load_ushort v95, v[8:9], off offset:-4096
	global_load_ushort v100, v[8:9], off
	global_load_ushort v101, v[8:9], off offset:2048
	global_load_ushort v102, v[12:13], off offset:-4096
	global_load_ushort v103, v[12:13], off
	global_load_ushort v104, v[12:13], off offset:2048
	v_add_co_u32_e32 v4, vcc, 0x7000, v0
	s_cbranch_execz .Ldry_hga1_real
.Ldry_hga1_c5:
	v_mov_b32_e32 v8, 0
	s_nop 0
	v_addc_co_u32_e32 v5, vcc, 0, v1, vcc
	global_load_ushort v96, v[0:1], off
	global_load_ushort v97, v[0:1], off offset:2048
	global_load_ushort v98, v[2:3], off offset:2048
	global_load_ushort v99, v[6:7], off offset:2048
	global_load_ushort v105, v[10:11], off offset:2048
	global_load_ushort v106, v[4:5], off
	global_load_ushort v107, v[4:5], off offset:2048
	v_mov_b32_e32 v4, 0
	v_mov_b32_e32 v5, v37
	v_mov_b32_e32 v6, v37
	v_mov_b32_e32 v7, v37
	v_mov_b32_e32 v0, 0
	v_mov_b32_e32 v1, v37
	v_mov_b32_e32 v2, v37
	v_mov_b32_e32 v3, v37
	v_mov_b32_e32 v9, v37
	s_cbranch_execz .Ldry_hga1_real
.Ldry_hga1_c6:
	v_mov_b32_e32 v10, v37
	v_mov_b32_e32 v11, v37
	v_mov_b32_e32 v12, 0
	v_mov_b32_e32 v13, v37
	v_mov_b32_e32 v31, v37
	s_waitcnt vmcnt(0)
	v_lshlrev_b32_e32 v46, 16, v14
	v_lshlrev_b32_e32 v48, 16, v15
	v_lshlrev_b32_e32 v52, 16, v16
	v_lshlrev_b32_e32 v56, 16, v17
	v_lshlrev_b32_e32 v57, 16, v18
	v_lshlrev_b32_e32 v33, 16, v19
	v_mov_b32_e32 v14, v37
	v_mov_b32_e32 v15, v37
	v_mov_b32_e32 v16, 0
	v_mov_b32_e32 v17, v37
	v_mov_b32_e32 v18, v37
	v_mov_b32_e32 v19, v37
	v_lshlrev_b32_e32 v35, 16, v20
	s_cbranch_execz .Ldry_hga1_real
.Ldry_hga1_c7:
	v_lshlrev_b32_e32 v49, 16, v21
	v_lshlrev_b32_e32 v53, 16, v22
	v_lshlrev_b32_e32 v55, 16, v23
	v_lshlrev_b32_e32 v51, 16, v24
	v_lshlrev_b32_e32 v47, 16, v25
	v_lshlrev_b32_e32 v50, 16, v26
	v_lshlrev_b32_e32 v54, 16, v27
	v_lshlrev_b32_e32 v60, 16, v28
	v_lshlrev_b32_e32 v58, 16, v29
	v_mov_b32_e32 v20, 0
	v_mov_b32_e32 v21, v37
	v_mov_b32_e32 v22, v37
	v_mov_b32_e32 v23, v37
	v_mov_b32_e32 v24, 0
	v_mov_b32_e32 v25, v37
	v_mov_b32_e32 v26, v37
	v_mov_b32_e32 v27, v37
	v_mov_b32_e32 v28, 0
	v_mov_b32_e32 v29, v37
	s_cbranch_execz .Ldry_hga1_real
	s_branch .LBB0_211

; template <bool FULL>
; __device__ __forceinline__ float hg_prep(LAS unsigned char* lds, const HgRegs& R) {
;     ...
;     ptot[part * 128 + k] = run;
;     unsigned vv[16];
; #pragma unroll
;     for (int i = 0; i < 16; ++i) vv[i] = R.vv[i];
;     __syncthreads();
;     const float p0 = ptot[k], p1 = ptot[128 + k], p2 = ptot[256 + k], p3 = ptot[384 + k];
;     const float off = (part == 0) ? 0.f : (part == 1) ? p0 : (part == 2) ? (p0 + p1) : (p0 + p1 + p2);
.LBB0_219:
	s_or_b64 exec, exec, s[18:19]
	s_bitcmp1_b32 s99, 1
	s_cbranch_scc1 .Ldry_hga2_skip
	s_bitset1_b32 s99, 1
	s_mov_b64 s[100:101], exec
	v_readfirstlane_b32 s98, v200
	s_nop 0
	s_lshr_b32 s98, s98, 6
	s_cmp_eq_u32 s98, 0
	s_cbranch_scc1 .Ldry_hga2_real
	s_mov_b64 exec, 0
	s_cmp_eq_u32 s98, 1
	s_cbranch_scc1 .Ldry_hga2_c1
	s_cmp_eq_u32 s98, 2
	s_cbranch_scc1 .Ldry_hga2_c2
	s_cmp_eq_u32 s98, 3
	s_cbranch_scc1 .Ldry_hga2_c3
	s_cmp_eq_u32 s98, 4
	s_cbranch_scc1 .Ldry_hga2_c4
	s_cmp_eq_u32 s98, 5
	s_cbranch_scc1 .Ldry_hga2_c5
	s_cmp_eq_u32 s98, 6
	s_cbranch_scc1 .Ldry_hga2_c6
	s_branch .Ldry_hga2_c7

; #define LAS __attribute__((address_space(3)))
; __device__ __forceinline__ float bf2f(unsigned u) { return __uint_as_float(u << 16); }
; template <bool FULL>
; __device__ __forceinline__ float hg_prep(LAS unsigned char* lds, const HgRegs& R) {
;     ...
;     const float p0 = ptot[k], p1 = ptot[128 + k], p2 = ptot[256 + k], p3 = ptot[384 + k];
;     const float off = (part == 0) ? 0.f : (part == 1) ? p0 : (part == 2) ? (p0 + p1) : (p0 + p1 + p2);
;     const float last = (p0 + p1) + (p2 + p3), mid = p0 + p1;
;     LAS bf16_t* kdT = (LAS bf16_t*)(lds + HG_KD);
;     LAS bf16_t* vT = (LAS bf16_t*)(lds + HG_VT);
;     unsigned pk[8];
;     float kkv[16], em[16];
;     const float clm = __expf(last - mid);
; #pragma unroll
;     for (int i = 0; i < 16; ++i) { kkv[i] = 1.f - __expf(gv[i]); em[i] = __expf((FULL ? mid : last) - (cs[i] + off)); }
; #pragma unroll
;     for (int i = 0; i < 8; ++i) {
;         const float a = kkv[2 * i] * em[2 * i] * (FULL ? clm : 1.f), c = kkv[2 * i + 1] * em[2 * i + 1] * (FULL ? clm : 1.f);
;         pk[i] = cvt_pk_bf16(a, c);
;     }
;     *(LAS u32x4*)(kdT + k * 72 + 16 * part) = (u32x4){pk[0], pk[1], pk[2], pk[3]};
;     *(LAS u32x4*)(kdT + k * 72 + 16 * part + 8) = (u32x4){pk[4], pk[5], pk[6], pk[7]};
;     *(LAS u32x4*)(vT + k * 72 + 16 * part) = (u32x4){vv[0] | (vv[1] << 16), vv[2] | (vv[3] << 16), vv[4] | (vv[5] << 16), vv[6] | (vv[7] << 16)};
;     *(LAS u32x4*)(vT + k * 72 + 16 * part + 8) = (u32x4){vv[8] | (vv[9] << 16), vv[10] | (vv[11] << 16), vv[12] | (vv[13] << 16), vv[14] | (vv[15] << 16)};
;     if (FULL) {
;         LAS bf16_t* qt = (LAS bf16_t*)(lds + HG_QT);
;         LAS bf16_t* kt = (LAS bf16_t*)(lds + HG_KT);
; #pragma unroll
;         for (int i = 0; i < 16; ++i) {
;             const float q = bf2f(R.qv[i]);
;             qt[(16 * part + i) * 136 + k] = (bf16_t)f2bf(q * __builtin_amdgcn_rcpf(em[i]));
;             kt[(16 * part + i) * 136 + k] = (bf16_t)f2bf(kkv[i] * em[i]);
;         }
;     }
;     if (part == 0) { ((LAS float*)(lds + HG_DL))[k] = __expf(last); if (FULL) ((LAS float*)(lds + HG_DM))[k] = __expf(mid); }
; __device__ __forceinline__ void hg_unit_a(LAS unsigned char* lds, int unit, const float* G, const bf16_t* HI, float* ST, float* DG, unsigned* cnt) {
;     ...
;         if (sc < 3) hg_load<false>(R, mu + (sc + 1) * 64, h, G, nullptr, HI);
.Ldry_hga2_skip:
	s_waitcnt lgkmcnt(1)
	v_add_f32_e32 v62, v66, v67
	s_waitcnt lgkmcnt(0)
	v_add_f32_e32 v64, v68, v69
	v_add_f32_e32 v124, v122, v65
	v_add_f32_e32 v125, v121, v65
	v_pk_add_f32 v[62:63], v[62:63], v[64:65]
	v_mul_f32_e32 v66, 0x3fb8aa3b, v33
	v_mul_f32_e32 v67, 0x3fb8aa3b, v46
	v_add_f32_e32 v126, v120, v65
	v_add_f32_e32 v127, v119, v65
	v_add_f32_e32 v128, v118, v65
	v_add_f32_e32 v129, v117, v65
	v_add_f32_e32 v130, v116, v65
	v_add_f32_e32 v131, v115, v65
	v_add_f32_e32 v132, v114, v65
	v_add_f32_e32 v133, v113, v65
	v_add_f32_e32 v134, v112, v65
	v_add_f32_e32 v135, v111, v65
	s_cbranch_execz .Ldry_hga2_real
.Ldry_hga2_c1:
	v_add_f32_e32 v136, v110, v65
	v_add_f32_e32 v137, v109, v65
	v_mul_f32_e32 v109, 0x3fb8aa3b, v57
	v_add_f32_e32 v138, v108, v65
	v_mul_f32_e32 v108, 0x3fb8aa3b, v60
	v_sub_f32_e32 v64, v62, v124
	v_sub_f32_e32 v65, v62, v125
	v_exp_f32_e32 v66, v66
	v_exp_f32_e32 v67, v67
	v_mul_f32_e32 v68, 0x3fb8aa3b, v35
	v_mul_f32_e32 v69, 0x3fb8aa3b, v48
	v_exp_f32_e32 v122, v109
	v_exp_f32_e32 v123, v108
	v_mul_f32_e32 v64, 0x3fb8aa3b, v64
	v_mul_f32_e32 v65, 0x3fb8aa3b, v65
	v_sub_f32_e32 v108, v62, v126
	v_sub_f32_e32 v109, v62, v127
	v_exp_f32_e32 v68, v68
	s_cbranch_execz .Ldry_hga2_real
.Ldry_hga2_c2:
	v_exp_f32_e32 v69, v69
	v_mul_f32_e32 v119, 0x3fb8aa3b, v47
	v_mul_f32_e32 v118, 0x3fb8aa3b, v50
	v_mul_f32_e32 v117, 0x3fb8aa3b, v49
	v_mul_f32_e32 v116, 0x3fb8aa3b, v52
	v_mul_f32_e32 v115, 0x3fb8aa3b, v51
	v_mul_f32_e32 v114, 0x3fb8aa3b, v54
	v_mul_f32_e32 v113, 0x3fb8aa3b, v53
	v_mul_f32_e32 v112, 0x3fb8aa3b, v56
	v_mul_f32_e32 v111, 0x3fb8aa3b, v55
	v_mul_f32_e32 v110, 0x3fb8aa3b, v58
	v_exp_f32_e32 v64, v64
	v_exp_f32_e32 v65, v65
	v_mul_f32_e32 v108, 0x3fb8aa3b, v108
	v_mul_f32_e32 v109, 0x3fb8aa3b, v109
	v_exp_f32_e32 v120, v119
	v_exp_f32_e32 v121, v118
	v_exp_f32_e32 v118, v117
	v_exp_f32_e32 v119, v116
	s_cbranch_execz .Ldry_hga2_real
.Ldry_hga2_c3:
	v_exp_f32_e32 v116, v115
	v_exp_f32_e32 v117, v114
	v_exp_f32_e32 v114, v113
	v_exp_f32_e32 v115, v112
	v_exp_f32_e32 v112, v111
	v_exp_f32_e32 v113, v110
	v_exp_f32_e32 v108, v108
	v_exp_f32_e32 v109, v109
	v_sub_f32_e32 v110, v62, v128
	v_sub_f32_e32 v111, v62, v129
	v_sub_f32_e32 v124, v62, v130
	v_sub_f32_e32 v125, v62, v131
	v_mul_f32_e32 v110, 0x3fb8aa3b, v110
	v_mul_f32_e32 v111, 0x3fb8aa3b, v111
	v_mul_f32_e32 v124, 0x3fb8aa3b, v124
	v_mul_f32_e32 v125, 0x3fb8aa3b, v125
	v_exp_f32_e32 v110, v110
	v_exp_f32_e32 v111, v111
	s_cbranch_execz .Ldry_hga2_real
.Ldry_hga2_c4:
	v_exp_f32_e32 v124, v124
	v_exp_f32_e32 v125, v125
	v_sub_f32_e32 v126, v62, v132
	v_sub_f32_e32 v127, v62, v133
	v_pk_add_f32 v[66:67], v[66:67], 1.0 op_sel_hi:[1,0] neg_lo:[1,0] neg_hi:[1,0]
	v_mul_f32_e32 v126, 0x3fb8aa3b, v126
	v_mul_f32_e32 v127, 0x3fb8aa3b, v127
	v_pk_mul_f32 v[64:65], v[66:67], v[64:65]
	v_pk_add_f32 v[66:67], v[68:69], 1.0 op_sel_hi:[1,0] neg_lo:[1,0] neg_hi:[1,0]
	v_exp_f32_e32 v126, v126
	v_exp_f32_e32 v127, v127
	v_sub_f32_e32 v128, v62, v134
	v_sub_f32_e32 v129, v62, v135
	v_pk_mul_f32 v[66:67], v[66:67], v[108:109]
	v_mul_f32_e32 v128, 0x3fb8aa3b, v128
	v_mul_f32_e32 v129, 0x3fb8aa3b, v129
	v_cvt_pk_bf16_f32 v64, v64, v65
	v_cvt_pk_bf16_f32 v65, v66, v67
	v_pk_add_f32 v[66:67], v[120:121], 1.0 op_sel_hi:[1,0] neg_lo:[1,0] neg_hi:[1,0]
	s_cbranch_execz .Ldry_hga2_real
.Ldry_hga2_c5:
	v_pk_add_f32 v[68:69], v[118:119], 1.0 op_sel_hi:[1,0] neg_lo:[1,0] neg_hi:[1,0]
	v_exp_f32_e32 v128, v128
	v_exp_f32_e32 v129, v129
	v_sub_f32_e32 v130, v62, v136
	v_sub_f32_e32 v131, v62, v137
	v_pk_mul_f32 v[66:67], v[66:67], v[110:111]
	v_pk_mul_f32 v[68:69], v[68:69], v[124:125]
	v_mul_f32_e32 v130, 0x3fb8aa3b, v130
	v_mul_f32_e32 v131, 0x3fb8aa3b, v131
	v_cvt_pk_bf16_f32 v66, v66, v67
	v_cvt_pk_bf16_f32 v67, v68, v69
	v_pk_add_f32 v[68:69], v[116:117], 1.0 op_sel_hi:[1,0] neg_lo:[1,0] neg_hi:[1,0]
	v_exp_f32_e32 v130, v130
	v_exp_f32_e32 v131, v131
	v_sub_f32_e32 v132, v62, v138
	v_sub_f32_e32 v63, v62, v63
	v_pk_mul_f32 v[68:69], v[68:69], v[126:127]
	v_mul_f32_e32 v132, 0x3fb8aa3b, v132
	v_mul_f32_e32 v63, 0x3fb8aa3b, v63
	s_cbranch_execz .Ldry_hga2_real
.Ldry_hga2_c6:
	v_cvt_pk_bf16_f32 v108, v68, v69
	v_pk_add_f32 v[68:69], v[114:115], 1.0 op_sel_hi:[1,0] neg_lo:[1,0] neg_hi:[1,0]
	v_exp_f32_e32 v132, v132
	v_exp_f32_e32 v133, v63
	v_pk_mul_f32 v[68:69], v[68:69], v[128:129]
	s_nop 0
	v_cvt_pk_bf16_f32 v109, v68, v69
	v_pk_add_f32 v[68:69], v[112:113], 1.0 op_sel_hi:[1,0] neg_lo:[1,0] neg_hi:[1,0]
	s_nop 0
	v_pk_mul_f32 v[68:69], v[68:69], v[130:131]
	s_nop 0
	v_cvt_pk_bf16_f32 v110, v68, v69
	v_pk_add_f32 v[68:69], v[122:123], 1.0 op_sel_hi:[1,0] neg_lo:[1,0] neg_hi:[1,0]
	s_nop 0
	v_pk_mul_f32 v[68:69], v[68:69], v[132:133]
	s_nop 0
	v_cvt_pk_bf16_f32 v111, v68, v69
	ds_write_b128 v72, v[64:67] offset:34816
	s_cbranch_execz .Ldry_hga2_real
.Ldry_hga2_c7:
	ds_write_b128 v72, v[108:111] offset:34832
	s_waitcnt vmcnt(14)
	v_lshl_or_b32 v64, v97, 16, v96
	s_waitcnt vmcnt(12)
	v_lshl_or_b32 v65, v98, 16, v92
	s_waitcnt vmcnt(10)
	v_lshl_or_b32 v66, v94, 16, v93
	s_waitcnt vmcnt(8)
	v_lshl_or_b32 v67, v99, 16, v95
	ds_write_b128 v72, v[64:67] offset:53248
	s_waitcnt vmcnt(6)
	v_lshl_or_b32 v64, v101, 16, v100
	s_waitcnt vmcnt(4)
	v_lshl_or_b32 v65, v105, 16, v102
	s_waitcnt vmcnt(2)
	v_lshl_or_b32 v66, v104, 16, v103
	s_waitcnt vmcnt(0)
	v_lshl_or_b32 v67, v107, 16, v106
	ds_write_b128 v72, v[64:67] offset:53264
	s_cbranch_execz .Ldry_hga2_real
	s_and_saveexec_b64 s[18:19], s[6:7]
	s_cbranch_execz .LBB0_221
	v_mul_f32_e32 v63, 0x3fb8aa3b, v62
	v_exp_f32_e32 v63, v63
	ds_write_b32 v76, v63
.LBB0_221:
	s_or_b64 exec, exec, s[18:19]
	s_cmp_eq_u32 s16, 0x60000
	s_cbranch_scc1 .LBB0_210
	s_bitcmp1_b32 s99, 2
	s_cbranch_scc1 .Ldry_hga3_skip
	s_bitset1_b32 s99, 2
	s_mov_b64 s[100:101], exec
	v_readfirstlane_b32 s98, v200
	s_nop 0
	s_lshr_b32 s98, s98, 6
	s_cmp_eq_u32 s98, 0
	s_cbranch_scc1 .Ldry_hga3_real
	s_mov_b64 exec, 0
	s_cmp_eq_u32 s98, 1
	s_cbranch_scc1 .Ldry_hga3_c1
	s_cmp_eq_u32 s98, 2
	s_cbranch_scc1 .Ldry_hga3_c2
	s_cmp_eq_u32 s98, 3
	s_cbranch_scc1 .Ldry_hga3_c3
	s_cmp_eq_u32 s98, 4
	s_cbranch_scc1 .Ldry_hga3_c4
	s_cmp_eq_u32 s98, 5
	s_cbranch_scc1 .Ldry_hga3_c5
	s_cmp_eq_u32 s98, 6
	s_cbranch_scc1 .Ldry_hga3_c6
	s_branch .Ldry_hga3_c7

; __device__ __forceinline__ float bf2f(unsigned u) { return __uint_as_float(u << 16); }
; template <bool FULL>
; __device__ __forceinline__ void hg_load(HgRegs& R, size_t m0, int h, const float* G, const bf16_t* HQ, const bf16_t* HI) {
;     const int tid = threadIdx.x, k = tid & 127, part = tid >> 7;
;     const size_t base = (m0 + 16 * part) * 1024 + h * 128 + k;
; #pragma unroll
;     for (int i = 0; i < 16; ++i) R.gv[i] = bf2f(((const bf16_t*)G)[base + (size_t)i * 1024]);
; #pragma unroll
;     for (int i = 0; i < 16; ++i) R.vv[i] = HI[base + (size_t)i * 1024];
; __device__ __forceinline__ void hg_unit_a(LAS unsigned char* lds, int unit, const float* G, const bf16_t* HI, float* ST, float* DG, unsigned* cnt) {
;     ...
;         if (sc < 3) hg_load<false>(R, mu + (sc + 1) * 64, h, G, nullptr, HI);
.Ldry_hga3_skip:
	v_lshl_add_u64 v[46:47], v[44:45], 0, s[16:17]
	v_add_co_u32_e32 v48, vcc, 0x20000, v46
	s_nop 1
	v_addc_co_u32_e32 v49, vcc, 0, v47, vcc
	v_add_co_u32_e32 v50, vcc, 0x21000, v46
	s_nop 1
	v_addc_co_u32_e32 v51, vcc, 0, v47, vcc
	v_add_co_u32_e32 v52, vcc, 0x22000, v46
	s_nop 1
	v_addc_co_u32_e32 v53, vcc, 0, v47, vcc
	v_add_co_u32_e32 v54, vcc, 0x23000, v46
	s_nop 1
	s_cbranch_execz .Ldry_hga3_real
.Ldry_hga3_c1:
	v_addc_co_u32_e32 v55, vcc, 0, v47, vcc
	global_load_ushort v35, v[48:49], off offset:2048
	global_load_ushort v56, v[50:51], off offset:2048
	global_load_ushort v57, v[52:53], off offset:2048
	global_load_ushort v58, v[54:55], off offset:2048
	global_load_ushort v60, v[54:55], off
	global_load_ushort v63, v[52:53], off
	global_load_ushort v64, v[50:51], off
	global_load_ushort v33, v[48:49], off
	v_add_co_u32_e32 v48, vcc, 0x24000, v46
	s_waitcnt vmcnt(0)
	v_lshlrev_b32_e32 v33, 16, v33
	v_addc_co_u32_e32 v49, vcc, 0, v47, vcc
	s_cbranch_execz .Ldry_hga3_real
.Ldry_hga3_c2:
	v_add_co_u32_e32 v50, vcc, 0x25000, v46
	s_nop 1
	v_addc_co_u32_e32 v51, vcc, 0, v47, vcc
	v_add_co_u32_e32 v52, vcc, 0x26000, v46
	s_nop 1
	v_addc_co_u32_e32 v53, vcc, 0, v47, vcc
	v_add_co_u32_e32 v46, vcc, 0x27000, v46
	s_nop 1
	v_addc_co_u32_e32 v47, vcc, 0, v47, vcc
	global_load_ushort v65, v[48:49], off offset:2048
	global_load_ushort v66, v[50:51], off offset:2048
	global_load_ushort v67, v[52:53], off offset:2048
	s_cbranch_execz .Ldry_hga3_real
.Ldry_hga3_c3:
	global_load_ushort v68, v[46:47], off offset:2048
	global_load_ushort v69, v[46:47], off
	global_load_ushort v108, v[52:53], off
	global_load_ushort v109, v[50:51], off
	global_load_ushort v110, v[48:49], off
	v_lshl_add_u64 v[46:47], v[42:43], 0, s[16:17]
	v_add_co_u32_e32 v48, vcc, 0xbc20000, v46
	s_nop 1
	v_addc_co_u32_e32 v49, vcc, 0, v47, vcc
	v_add_co_u32_e32 v50, vcc, 0xbc21000, v46
	s_nop 1
	v_addc_co_u32_e32 v51, vcc, 0, v47, vcc
	v_add_co_u32_e32 v52, vcc, 0xbc22000, v46
	s_cbranch_execz .Ldry_hga3_real
.Ldry_hga3_c4:
	s_nop 1
	v_addc_co_u32_e32 v53, vcc, 0, v47, vcc
	v_add_co_u32_e32 v54, vcc, 0xbc23000, v46
	s_nop 1
	v_addc_co_u32_e32 v55, vcc, 0, v47, vcc
	global_load_ushort v96, v[48:49], off
	global_load_ushort v97, v[48:49], off offset:2048
	global_load_ushort v92, v[50:51], off
	global_load_ushort v98, v[50:51], off offset:2048
	global_load_ushort v93, v[52:53], off
	global_load_ushort v94, v[52:53], off offset:2048
	global_load_ushort v95, v[54:55], off
	s_cbranch_execz .Ldry_hga3_real
.Ldry_hga3_c5:
	global_load_ushort v99, v[54:55], off offset:2048
	v_add_co_u32_e32 v48, vcc, 0xbc24000, v46
	s_waitcnt vmcnt(15)
	v_lshlrev_b32_e32 v54, 16, v65
	v_addc_co_u32_e32 v49, vcc, 0, v47, vcc
	v_add_co_u32_e32 v50, vcc, 0xbc25000, v46
	s_waitcnt vmcnt(10)
	v_lshlrev_b32_e32 v55, 16, v108
	v_addc_co_u32_e32 v51, vcc, 0, v47, vcc
	v_add_co_u32_e32 v52, vcc, 0xbc26000, v46
	s_nop 1
	v_addc_co_u32_e32 v53, vcc, 0, v47, vcc
	s_cbranch_execz .Ldry_hga3_real
.Ldry_hga3_c6:
	v_add_co_u32_e32 v46, vcc, 0xbc27000, v46
	s_nop 1
	v_addc_co_u32_e32 v47, vcc, 0, v47, vcc
	global_load_ushort v100, v[48:49], off
	global_load_ushort v101, v[48:49], off offset:2048
	global_load_ushort v102, v[50:51], off
	global_load_ushort v105, v[50:51], off offset:2048
	global_load_ushort v103, v[52:53], off
	global_load_ushort v104, v[52:53], off offset:2048
	global_load_ushort v106, v[46:47], off
	global_load_ushort v107, v[46:47], off offset:2048
	v_lshlrev_b32_e32 v46, 16, v35
	v_lshlrev_b32_e32 v35, 16, v64
	s_cbranch_execz .Ldry_hga3_real
.Ldry_hga3_c7:
	v_lshlrev_b32_e32 v48, 16, v56
	v_lshlrev_b32_e32 v47, 16, v63
	v_lshlrev_b32_e32 v50, 16, v57
	v_lshlrev_b32_e32 v49, 16, v60
	v_lshlrev_b32_e32 v52, 16, v58
	s_waitcnt vmcnt(16)
	v_lshlrev_b32_e32 v51, 16, v110
	v_lshlrev_b32_e32 v53, 16, v109
	v_lshlrev_b32_e32 v56, 16, v66
	v_lshlrev_b32_e32 v58, 16, v67
	v_lshlrev_b32_e32 v57, 16, v69
	v_lshlrev_b32_e32 v60, 16, v68
	s_cbranch_execz .Ldry_hga3_real
	s_branch .LBB0_210

; __device__ __forceinline__ void hg_unit_a(LAS unsigned char* lds, int unit, const float* G, const bf16_t* HI, float* ST, float* DG, unsigned* cnt) {
;     ...
;     float* U = ST + (size_t)unit * 16384;
; #pragma unroll
;     for (int i = 0; i < 8; ++i)
; #pragma unroll
;         for (int rg = 0; rg < 4; ++rg) __hip_atomic_store(&U[(16 * i + 4 * g + rg) * 128 + 16 * w + r], S[i][rg], __ATOMIC_RELAXED, __HIP_MEMORY_SCOPE_AGENT);
;     if (tid < 128) __hip_atomic_store(&DG[unit * 128 + tid], __expf(cumtot), __ATOMIC_RELAXED, __HIP_MEMORY_SCOPE_AGENT);
.LBB0_225:
	s_bitcmp1_b32 s99, 3
	s_cbranch_scc1 .Ldry_hga4_skip
	s_bitset1_b32 s99, 3
	s_mov_b64 s[100:101], exec
	v_readfirstlane_b32 s98, v200
	s_nop 0
	s_lshr_b32 s98, s98, 6
	s_cmp_eq_u32 s98, 0
	s_cbranch_scc1 .Ldry_hga4_real
	s_mov_b64 exec, 0
	s_cmp_eq_u32 s98, 1
	s_cbranch_scc1 .Ldry_hga4_c1
	s_cmp_eq_u32 s98, 2
	s_cbranch_scc1 .Ldry_hga4_c2
	s_cmp_eq_u32 s98, 3
	s_cbranch_scc1 .Ldry_hga4_c3
	s_cmp_eq_u32 s98, 4
	s_cbranch_scc1 .Ldry_hga4_c4
	s_cmp_eq_u32 s98, 5
	s_cbranch_scc1 .Ldry_hga4_c5
	s_cmp_eq_u32 s98, 6
	s_cbranch_scc1 .Ldry_hga4_c6
	s_branch .Ldry_hga4_c7

; __device__ __forceinline__ void hg_unit_a(LAS unsigned char* lds, int unit, const float* G, const bf16_t* HI, float* ST, float* DG, unsigned* cnt) {
;     ...
;     float* U = ST + (size_t)unit * 16384;
; #pragma unroll
;     for (int i = 0; i < 8; ++i)
; #pragma unroll
;         for (int rg = 0; rg < 4; ++rg) __hip_atomic_store(&U[(16 * i + 4 * g + rg) * 128 + 16 * w + r], S[i][rg], __ATOMIC_RELAXED, __HIP_MEMORY_SCOPE_AGENT);
;     if (tid < 128) __hip_atomic_store(&DG[unit * 128 + tid], __expf(cumtot), __ATOMIC_RELAXED, __HIP_MEMORY_SCOPE_AGENT);
.Ldry_hga4_skip:
	s_ashr_i32 s15, s14, 31
	s_lshl_b64 s[16:17], s[14:15], 16
	s_add_u32 s16, s52, s16
	s_addc_u32 s17, s53, s17
	v_lshl_add_u64 v[42:43], s[16:17], 0, v[36:37]
	global_store_dword v36, v28, s[16:17] sc1
	global_store_dword v36, v29, s[16:17] offset:512 sc1
	s_cbranch_execz .Ldry_hga4_real
.Ldry_hga4_c1:
	global_store_dword v36, v30, s[16:17] offset:1024 sc1
	global_store_dword v36, v31, s[16:17] offset:1536 sc1
	v_add_co_u32_e32 v28, vcc, s29, v42
	s_nop 1
	v_addc_co_u32_e32 v29, vcc, 0, v43, vcc
	global_store_dword v[28:29], v24, off sc1
	global_store_dword v77, v25, s[16:17] sc1
	s_cbranch_execz .Ldry_hga4_real
.Ldry_hga4_c2:
	global_store_dword v[28:29], v26, off offset:1024 sc1
	global_store_dword v78, v27, s[16:17] sc1
	v_add_co_u32_e32 v24, vcc, s31, v42
	s_nop 1
	v_addc_co_u32_e32 v25, vcc, 0, v43, vcc
	global_store_dword v[24:25], v20, off sc1
	global_store_dword v79, v21, s[16:17] sc1
	global_store_dword v[24:25], v22, off offset:1024 sc1
	s_cbranch_execz .Ldry_hga4_real
.Ldry_hga4_c3:
	global_store_dword v80, v23, s[16:17] sc1
	v_add_co_u32_e32 v20, vcc, s35, v42
	s_nop 1
	v_addc_co_u32_e32 v21, vcc, 0, v43, vcc
	global_store_dword v[20:21], v16, off sc1
	global_store_dword v81, v17, s[16:17] sc1
	global_store_dword v[20:21], v18, off offset:1024 sc1
	s_cbranch_execz .Ldry_hga4_real
.Ldry_hga4_c4:
	global_store_dword v82, v19, s[16:17] sc1
	v_add_co_u32_e32 v16, vcc, s37, v42
	s_nop 1
	v_addc_co_u32_e32 v17, vcc, 0, v43, vcc
	global_store_dword v[16:17], v12, off sc1
	global_store_dword v83, v13, s[16:17] sc1
	global_store_dword v[16:17], v14, off offset:1024 sc1
	s_cbranch_execz .Ldry_hga4_real
.Ldry_hga4_c5:
	global_store_dword v84, v15, s[16:17] sc1
	v_add_co_u32_e32 v12, vcc, s38, v42
	s_nop 1
	v_addc_co_u32_e32 v13, vcc, 0, v43, vcc
	global_store_dword v[12:13], v8, off sc1
	global_store_dword v85, v9, s[16:17] sc1
	global_store_dword v[12:13], v10, off offset:1024 sc1
	global_store_dword v86, v11, s[16:17] sc1
	s_cbranch_execz .Ldry_hga4_real
.Ldry_hga4_c6:
	v_add_co_u32_e32 v8, vcc, s39, v42
	s_nop 1
	v_addc_co_u32_e32 v9, vcc, 0, v43, vcc
	global_store_dword v[8:9], v0, off sc1
	global_store_dword v87, v1, s[16:17] sc1
	global_store_dword v[8:9], v2, off offset:1024 sc1
	global_store_dword v88, v3, s[16:17] sc1
	s_cbranch_execz .Ldry_hga4_real
.Ldry_hga4_c7:
	v_add_co_u32_e32 v0, vcc, 0xe000, v42
	s_nop 1
	v_addc_co_u32_e32 v1, vcc, 0, v43, vcc
	global_store_dword v[0:1], v4, off sc1
	global_store_dword v89, v5, s[16:17] sc1
	global_store_dword v[0:1], v6, off offset:1024 sc1
	global_store_dword v90, v7, s[16:17] sc1
	s_cbranch_execz .Ldry_hga4_real
	s_and_saveexec_b64 s[16:17], s[6:7]
	s_cbranch_execz .LBB0_227
	v_mul_f32_e32 v0, 0x3fb8aa3b, v91
	v_exp_f32_e32 v2, v0
	v_lshl_or_b32 v0, s14, 7, v200
	v_ashrrev_i32_e32 v1, 31, v0
	v_lshl_add_u64 v[0:1], v[0:1], 2, s[82:83]
	global_store_dword v[0:1], v2, off sc1

; __device__ __forceinline__ unsigned cvt_pk_bf16(float lo, float hi) { f32x2_t v = {lo, hi}; bf16x2_t b = __builtin_convertvector(v, bf16x2_t); return __builtin_bit_cast(unsigned, b); }
; __device__ __forceinline__ float bf2f(unsigned u) { return __uint_as_float(u << 16); }
; __device__ __forceinline__ float siluf_(float v) { return v * sigmoidf_(v); }
;     __device__ __forceinline__ void operator()(const f32x4 (&acc)[2][2][4][2], const pg8::Unit& u, int wr, int wc, int fr, int fq) const {
;     ...
;             bf16_t* base = seg == 3 ? asb : ahg;
; #pragma unroll
;             for (int ai = 0; ai < 2; ++ai) {
;                 u32x4 ov[4][2];
; #pragma unroll
;                 for (int m = 0; m < 4; ++m)
; #pragma unroll
;                     for (int bj = 0; bj < 2; ++bj) ov[m][bj] = *(const u32x4*)(base + (size_t)(row0 + ai * 128 + m * 16) * 1024 + col0 + bj * 128);
; #pragma unroll
;                 for (int m = 0; m < 4; ++m)
; #pragma unroll
;                     for (int bj = 0; bj < 2; ++bj) {
;                         const u32x4 o = ov[m][bj];
;                         const f32x4 a = acc[ai][bj][m][0], b = acc[ai][bj][m][1];
;                         u32x4 w;
;                         w.x = cvt_pk_bf16(bf2f(o.x & 0xffffu) * siluf_(a[0]), bf2f(o.x >> 16) * siluf_(a[1]));
;                         w.y = cvt_pk_bf16(bf2f(o.y & 0xffffu) * siluf_(a[2]), bf2f(o.y >> 16) * siluf_(a[3]));
;                         w.z = cvt_pk_bf16(bf2f(o.z & 0xffffu) * siluf_(b[0]), bf2f(o.z >> 16) * siluf_(b[1]));
;                         w.w = cvt_pk_bf16(bf2f(o.w & 0xffffu) * siluf_(b[2]), bf2f(o.w >> 16) * siluf_(b[3]));
;                         *(u32x4*)(base + (size_t)(row0 + ai * 128 + m * 16) * 1024 + col0 + bj * 128) = w;
;                     }
.LBB0_527:
	v_lshl_add_u32 v176, s40, 8, v190
	s_lshl_b32 s3, s48, 8
	s_ashr_i32 s27, s48, 2
	s_and_b32 s3, s3, 0x300
	v_or_b32_e32 v174, 16, v176
	v_or_b32_e32 v172, 32, v176
	v_or_b32_e32 v170, 48, v176
	v_or_b32_e32 v196, s3, v192
	s_mov_b64 s[40:41], -1
	s_cmp_lt_i32 s27, 8
	v_ashrrev_i32_e32 v177, 31, v176
	v_ashrrev_i32_e32 v175, 31, v174
	v_ashrrev_i32_e32 v173, 31, v172
	v_ashrrev_i32_e32 v171, 31, v170
	s_cbranch_scc0 .LBB0_530
	v_readfirstlane_b32 s98, v200
	s_nop 0
	s_lshr_b32 s98, s98, 6
	s_cmp_eq_u32 s98, 0
	s_cbranch_scc1 .Ldry_p5a_real
	s_mov_b64 exec, 0
	s_cmp_eq_u32 s98, 1
	s_cbranch_scc1 .Ldry_p5a_c1
	s_cmp_eq_u32 s98, 2
	s_cbranch_scc1 .Ldry_p5a_c2
	s_cmp_eq_u32 s98, 3
	s_cbranch_scc1 .Ldry_p5a_c3
	s_cmp_eq_u32 s98, 4
	s_cbranch_scc1 .Ldry_p5a_c4
	s_cmp_eq_u32 s98, 5
	s_cbranch_scc1 .Ldry_p5a_c5
	s_cmp_eq_u32 s98, 6
	s_cbranch_scc1 .Ldry_p5a_c6
	s_branch .Ldry_p5a_c7
.Ldry_p5a_real:
	s_mov_b64 exec, -1
	v_readlane_b32 s12, v250, 17
	s_cmp_eq_u32 s27, 3
	v_readlane_b32 s13, v250, 18
	s_cselect_b32 s41, s77, s13
	s_cselect_b32 s40, s76, s12
	v_lshlrev_b32_e32 v160, 1, v196
	v_lshl_add_u64 v[128:129], s[40:41], 0, v[160:161]
	v_lshlrev_b64 v[130:131], 11, v[176:177]
	v_lshl_add_u64 v[178:179], v[128:129], 0, v[130:131]
	global_load_dwordx4 v[182:185], v[178:179], off
	global_load_dwordx4 v[186:189], v[178:179], off offset:256
	v_lshlrev_b64 v[130:131], 11, v[174:175]
	v_lshlrev_b64 v[132:133], 11, v[172:173]
	v_lshlrev_b64 v[134:135], 11, v[170:171]
	v_mul_f32_e32 v136, 0xbfb8aa3b, v124
	v_mul_f32_e32 v137, 0xbfb8aa3b, v125
	v_mul_f32_e32 v138, 0xbfb8aa3b, v126
	v_mul_f32_e32 v139, 0xbfb8aa3b, v127
	v_mul_f32_e32 v140, 0xbfb8aa3b, v120
	v_mul_f32_e32 v141, 0xbfb8aa3b, v121
	v_mul_f32_e32 v142, 0xbfb8aa3b, v122
	v_mul_f32_e32 v143, 0xbfb8aa3b, v123
	v_mul_f32_e32 v144, 0xbfb8aa3b, v60
	v_mul_f32_e32 v145, 0xbfb8aa3b, v61
	v_mul_f32_e32 v146, 0xbfb8aa3b, v62
	v_lshl_add_u64 v[180:181], v[128:129], 0, v[130:131]
	v_exp_f32_e32 v197, v136
	v_exp_f32_e32 v198, v137
	v_exp_f32_e32 v199, v138
	v_exp_f32_e32 v201, v139
	v_exp_f32_e32 v206, v140
	v_exp_f32_e32 v207, v141
	v_exp_f32_e32 v208, v142
	v_exp_f32_e32 v209, v143
	v_exp_f32_e32 v210, v144
	v_exp_f32_e32 v211, v145
	v_exp_f32_e32 v220, v146
	v_lshl_add_u64 v[150:151], v[128:129], 0, v[132:133]
	v_lshl_add_u64 v[148:149], v[128:129], 0, v[134:135]
	global_load_dwordx4 v[202:205], v[180:181], off
	global_load_dwordx4 v[144:147], v[180:181], off offset:256
	global_load_dwordx4 v[140:143], v[150:151], off
	global_load_dwordx4 v[136:139], v[150:151], off offset:256
	global_load_dwordx4 v[132:135], v[148:149], off
	global_load_dwordx4 v[128:131], v[148:149], off offset:256
	v_add_f32_e32 v197, 1.0, v197
	v_add_f32_e32 v212, 1.0, v198
	v_add_f32_e32 v213, 1.0, v199
	v_add_f32_e32 v201, 1.0, v201
	v_add_f32_e32 v214, 1.0, v206
	v_add_f32_e32 v215, 1.0, v207
	v_add_f32_e32 v216, 1.0, v208
	v_add_f32_e32 v217, 1.0, v209
	v_add_f32_e32 v218, 1.0, v210
	v_add_f32_e32 v219, 1.0, v211
	v_rcp_f32_e32 v198, v197
	v_rcp_f32_e32 v199, v212
	v_rcp_f32_e32 v206, v213
	v_rcp_f32_e32 v207, v201
	v_rcp_f32_e32 v208, v214
	v_rcp_f32_e32 v209, v215
	v_rcp_f32_e32 v210, v216
	v_rcp_f32_e32 v211, v217
	v_mul_f32_e32 v160, 0xbfb8aa3b, v63
	v_rcp_f32_e32 v212, v218
	v_rcp_f32_e32 v213, v219
	v_exp_f32_e32 v160, v160
	v_pk_mul_f32 v[198:199], v[124:125], v[198:199]
	v_pk_mul_f32 v[206:207], v[126:127], v[206:207]
	v_pk_mul_f32 v[208:209], v[120:121], v[208:209]
	v_pk_mul_f32 v[210:211], v[122:123], v[210:211]
	v_pk_mul_f32 v[212:213], v[60:61], v[212:213]
	v_add_f32_e32 v160, 1.0, v160
	s_mov_b32 s3, 0x40000
	s_mov_b64 s[40:41], 0x40000
	v_mul_f32_e32 v197, 0xbfb8aa3b, v95
	v_exp_f32_e32 v197, v197
	s_mov_b64 s[12:13], 0x58000
	s_waitcnt vmcnt(0)
	v_lshlrev_b32_e32 v214, 16, v182
	v_and_b32_e32 v215, 0xffff0000, v182
	v_lshlrev_b32_e32 v182, 16, v183
	v_and_b32_e32 v183, 0xffff0000, v183
	v_lshlrev_b32_e32 v216, 16, v184
	v_and_b32_e32 v217, 0xffff0000, v184
	v_lshlrev_b32_e32 v184, 16, v185
	v_and_b32_e32 v185, 0xffff0000, v185
	v_pk_mul_f32 v[198:199], v[198:199], v[214:215]
	v_pk_mul_f32 v[206:207], v[206:207], v[182:183]
	v_pk_mul_f32 v[208:209], v[208:209], v[216:217]
	v_pk_mul_f32 v[210:211], v[210:211], v[184:185]
	v_lshlrev_b32_e32 v218, 16, v186
	v_and_b32_e32 v219, 0xffff0000, v186
	v_cvt_pk_bf16_f32 v182, v198, v199
	v_cvt_pk_bf16_f32 v183, v206, v207
	v_cvt_pk_bf16_f32 v184, v208, v209
	v_cvt_pk_bf16_f32 v185, v210, v211
	global_store_dwordx4 v[178:179], v[182:185], off
	v_lshlrev_b32_e32 v186, 16, v187
	v_and_b32_e32 v187, 0xffff0000, v187
	v_pk_mul_f32 v[182:183], v[212:213], v[218:219]
	v_add_f32_e32 v184, 1.0, v220
	v_rcp_f32_e32 v185, v160
	v_mul_f32_e32 v160, 0xbfb8aa3b, v56
	v_rcp_f32_e32 v184, v184
	v_cvt_pk_bf16_f32 v182, v182, v183
	v_exp_f32_e32 v160, v160
	v_mul_f32_e32 v183, 0xbfb8aa3b, v57
	v_exp_f32_e32 v183, v183
	v_pk_mul_f32 v[184:185], v[62:63], v[184:185]
	v_add_f32_e32 v160, 1.0, v160
	v_pk_mul_f32 v[184:185], v[184:185], v[186:187]
	v_rcp_f32_e32 v186, v160
	v_add_f32_e32 v160, 1.0, v183
	s_cbranch_execz .Ldry_p5a_real
; __device__ __forceinline__ unsigned cvt_pk_bf16(float lo, float hi) { f32x2_t v = {lo, hi}; bf16x2_t b = __builtin_convertvector(v, bf16x2_t); return __builtin_bit_cast(unsigned, b); }
; __device__ __forceinline__ float bf2f(unsigned u) { return __uint_as_float(u << 16); }
; __device__ __forceinline__ float siluf_(float v) { return v * sigmoidf_(v); }
;     __device__ __forceinline__ void operator()(const f32x4 (&acc)[2][2][4][2], const pg8::Unit& u, int wr, int wc, int fr, int fq) const {
;     ...
;             bf16_t* base = seg == 3 ? asb : ahg;
; #pragma unroll
;             for (int ai = 0; ai < 2; ++ai) {
;                 u32x4 ov[4][2];
; #pragma unroll
;                 for (int m = 0; m < 4; ++m)
; #pragma unroll
;                     for (int bj = 0; bj < 2; ++bj) ov[m][bj] = *(const u32x4*)(base + (size_t)(row0 + ai * 128 + m * 16) * 1024 + col0 + bj * 128);
; #pragma unroll
;                 for (int m = 0; m < 4; ++m)
; #pragma unroll
;                     for (int bj = 0; bj < 2; ++bj) {
;                         const u32x4 o = ov[m][bj];
;                         const f32x4 a = acc[ai][bj][m][0], b = acc[ai][bj][m][1];
;                         u32x4 w;
;                         w.x = cvt_pk_bf16(bf2f(o.x & 0xffffu) * siluf_(a[0]), bf2f(o.x >> 16) * siluf_(a[1]));
;                         w.y = cvt_pk_bf16(bf2f(o.y & 0xffffu) * siluf_(a[2]), bf2f(o.y >> 16) * siluf_(a[3]));
;                         w.z = cvt_pk_bf16(bf2f(o.z & 0xffffu) * siluf_(b[0]), bf2f(o.z >> 16) * siluf_(b[1]));
;                         w.w = cvt_pk_bf16(bf2f(o.w & 0xffffu) * siluf_(b[2]), bf2f(o.w >> 16) * siluf_(b[3]));
;                         *(u32x4*)(base + (size_t)(row0 + ai * 128 + m * 16) * 1024 + col0 + bj * 128) = w;
;                     }
.Ldry_p5a_c1:
	v_rcp_f32_e32 v187, v160
	v_mul_f32_e32 v160, 0xbfb8aa3b, v58
	v_cvt_pk_bf16_f32 v183, v184, v185
	v_lshlrev_b32_e32 v184, 16, v188
	v_and_b32_e32 v185, 0xffff0000, v188
	v_exp_f32_e32 v160, v160
	v_mul_f32_e32 v188, 0xbfb8aa3b, v59
	v_exp_f32_e32 v188, v188
	v_pk_mul_f32 v[186:187], v[56:57], v[186:187]
	v_add_f32_e32 v160, 1.0, v160
	v_pk_mul_f32 v[184:185], v[186:187], v[184:185]
	v_rcp_f32_e32 v186, v160
	v_add_f32_e32 v160, 1.0, v188
	v_rcp_f32_e32 v187, v160
	v_mul_f32_e32 v160, 0xbfb8aa3b, v116
	v_cvt_pk_bf16_f32 v184, v184, v185
	v_lshlrev_b32_e32 v188, 16, v189
	v_and_b32_e32 v189, 0xffff0000, v189
	v_pk_mul_f32 v[186:187], v[58:59], v[186:187]
	v_exp_f32_e32 v160, v160
	v_mul_f32_e32 v185, 0xbfb8aa3b, v117
	v_pk_mul_f32 v[186:187], v[186:187], v[188:189]
	v_exp_f32_e32 v188, v185
	v_add_f32_e32 v160, 1.0, v160
	v_cvt_pk_bf16_f32 v185, v186, v187
	v_rcp_f32_e32 v186, v160
	v_add_f32_e32 v160, 1.0, v188
	v_rcp_f32_e32 v187, v160
	v_mul_f32_e32 v160, 0xbfb8aa3b, v118
	global_store_dwordx4 v[178:179], v[182:185], off offset:256
	v_exp_f32_e32 v160, v160
	v_mul_f32_e32 v188, 0xbfb8aa3b, v115
	v_pk_mul_f32 v[184:185], v[116:117], v[186:187]
	v_mul_f32_e32 v186, 0xbfb8aa3b, v119
	v_exp_f32_e32 v186, v186
	v_lshlrev_b32_e32 v182, 16, v202
	v_and_b32_e32 v183, 0xffff0000, v202
	v_add_f32_e32 v160, 1.0, v160
	v_pk_mul_f32 v[182:183], v[184:185], v[182:183]
	v_rcp_f32_e32 v184, v160
	v_add_f32_e32 v160, 1.0, v186
	v_rcp_f32_e32 v185, v160
	v_mul_f32_e32 v160, 0xbfb8aa3b, v112
	v_cvt_pk_bf16_f32 v182, v182, v183
	v_exp_f32_e32 v160, v160
	v_mul_f32_e32 v183, 0xbfb8aa3b, v113
	v_exp_f32_e32 v183, v183
	v_lshlrev_b32_e32 v186, 16, v203
	v_and_b32_e32 v187, 0xffff0000, v203
	v_pk_mul_f32 v[184:185], v[118:119], v[184:185]
	v_add_f32_e32 v160, 1.0, v160
	v_pk_mul_f32 v[184:185], v[184:185], v[186:187]
	v_rcp_f32_e32 v186, v160
	v_add_f32_e32 v160, 1.0, v183
	v_rcp_f32_e32 v187, v160
	v_mul_f32_e32 v160, 0xbfb8aa3b, v114
	v_exp_f32_e32 v160, v160
	v_exp_f32_e32 v188, v188
	v_cvt_pk_bf16_f32 v183, v184, v185
	v_lshlrev_b32_e32 v184, 16, v204
	v_and_b32_e32 v185, 0xffff0000, v204
	v_pk_mul_f32 v[186:187], v[112:113], v[186:187]
	v_add_f32_e32 v160, 1.0, v160
	v_pk_mul_f32 v[184:185], v[186:187], v[184:185]
	v_rcp_f32_e32 v186, v160
	v_add_f32_e32 v160, 1.0, v188
	v_rcp_f32_e32 v187, v160
	v_mul_f32_e32 v160, 0xbfb8aa3b, v52
	v_cvt_pk_bf16_f32 v184, v184, v185
	v_lshlrev_b32_e32 v188, 16, v205
	v_and_b32_e32 v189, 0xffff0000, v205
	v_pk_mul_f32 v[186:187], v[114:115], v[186:187]
	v_exp_f32_e32 v160, v160
	v_mul_f32_e32 v185, 0xbfb8aa3b, v53
	v_pk_mul_f32 v[186:187], v[186:187], v[188:189]
	v_exp_f32_e32 v188, v185
	v_cvt_pk_bf16_f32 v185, v186, v187
	v_add_f32_e32 v160, 1.0, v160
	v_rcp_f32_e32 v186, v160
	v_add_f32_e32 v160, 1.0, v188
	global_store_dwordx4 v[180:181], v[182:185], off
	v_rcp_f32_e32 v187, v160
	v_mul_f32_e32 v160, 0xbfb8aa3b, v55
	v_lshlrev_b32_e32 v182, 16, v144
	v_and_b32_e32 v183, 0xffff0000, v144
	v_mul_f32_e32 v144, 0xbfb8aa3b, v54
	v_exp_f32_e32 v144, v144
	v_exp_f32_e32 v160, v160
	v_pk_mul_f32 v[184:185], v[52:53], v[186:187]
	v_add_co_u32_e32 v198, vcc, s3, v178
	v_add_f32_e32 v144, 1.0, v144
	v_pk_mul_f32 v[182:183], v[184:185], v[182:183]
	v_rcp_f32_e32 v184, v144
	v_add_f32_e32 v144, 1.0, v160
	v_rcp_f32_e32 v185, v144
	v_cvt_pk_bf16_f32 v144, v182, v183
	v_lshlrev_b32_e32 v182, 16, v145
	v_and_b32_e32 v183, 0xffff0000, v145
	v_mul_f32_e32 v145, 0xbfb8aa3b, v48
	v_exp_f32_e32 v145, v145
	v_mul_f32_e32 v160, 0xbfb8aa3b, v49
	v_exp_f32_e32 v160, v160
	v_pk_mul_f32 v[184:185], v[54:55], v[184:185]
	v_add_f32_e32 v145, 1.0, v145
	v_pk_mul_f32 v[182:183], v[184:185], v[182:183]
	v_rcp_f32_e32 v184, v145
	v_add_f32_e32 v145, 1.0, v160
	v_rcp_f32_e32 v185, v145
	v_cvt_pk_bf16_f32 v145, v182, v183
	v_lshlrev_b32_e32 v182, 16, v146
	v_and_b32_e32 v183, 0xffff0000, v146
	v_mul_f32_e32 v146, 0xbfb8aa3b, v50
	v_exp_f32_e32 v146, v146
	v_mul_f32_e32 v160, 0xbfb8aa3b, v51
	v_exp_f32_e32 v160, v160
	s_cbranch_execz .Ldry_p5a_real
.Ldry_p5a_c2:
	v_pk_mul_f32 v[184:185], v[48:49], v[184:185]
	v_add_f32_e32 v146, 1.0, v146
	v_pk_mul_f32 v[182:183], v[184:185], v[182:183]
	v_rcp_f32_e32 v184, v146
	v_add_f32_e32 v146, 1.0, v160
	v_rcp_f32_e32 v185, v146
	v_cvt_pk_bf16_f32 v146, v182, v183
	v_lshlrev_b32_e32 v182, 16, v147
	v_and_b32_e32 v183, 0xffff0000, v147
	v_mul_f32_e32 v147, 0xbfb8aa3b, v108
	v_pk_mul_f32 v[184:185], v[50:51], v[184:185]
	v_exp_f32_e32 v160, v147
	v_mul_f32_e32 v147, 0xbfb8aa3b, v109
	v_pk_mul_f32 v[182:183], v[184:185], v[182:183]
	v_exp_f32_e32 v184, v147
	v_cvt_pk_bf16_f32 v147, v182, v183
	v_add_f32_e32 v160, 1.0, v160
	v_rcp_f32_e32 v182, v160
	v_add_f32_e32 v160, 1.0, v184
	global_store_dwordx4 v[180:181], v[144:147], off offset:256
	v_rcp_f32_e32 v183, v160
	v_mul_f32_e32 v160, 0xbfb8aa3b, v111
	v_lshlrev_b32_e32 v144, 16, v140
	v_and_b32_e32 v145, 0xffff0000, v140
	v_mul_f32_e32 v140, 0xbfb8aa3b, v110
	v_exp_f32_e32 v140, v140
	v_exp_f32_e32 v160, v160
	v_pk_mul_f32 v[146:147], v[108:109], v[182:183]
	v_addc_co_u32_e32 v199, vcc, 0, v179, vcc
	v_add_f32_e32 v140, 1.0, v140
	v_pk_mul_f32 v[144:145], v[146:147], v[144:145]
	v_rcp_f32_e32 v146, v140
	v_add_f32_e32 v140, 1.0, v160
	v_rcp_f32_e32 v147, v140
	v_cvt_pk_bf16_f32 v140, v144, v145
	v_lshlrev_b32_e32 v144, 16, v141
	v_and_b32_e32 v145, 0xffff0000, v141
	v_mul_f32_e32 v141, 0xbfb8aa3b, v104
	v_exp_f32_e32 v141, v141
	v_mul_f32_e32 v160, 0xbfb8aa3b, v105
	v_exp_f32_e32 v160, v160
	v_pk_mul_f32 v[146:147], v[110:111], v[146:147]
	v_add_f32_e32 v141, 1.0, v141
	v_pk_mul_f32 v[144:145], v[146:147], v[144:145]
	v_rcp_f32_e32 v146, v141
; __device__ __forceinline__ unsigned cvt_pk_bf16(float lo, float hi) { f32x2_t v = {lo, hi}; bf16x2_t b = __builtin_convertvector(v, bf16x2_t); return __builtin_bit_cast(unsigned, b); }
; __device__ __forceinline__ float bf2f(unsigned u) { return __uint_as_float(u << 16); }
; __device__ __forceinline__ float siluf_(float v) { return v * sigmoidf_(v); }
;     __device__ __forceinline__ void operator()(const f32x4 (&acc)[2][2][4][2], const pg8::Unit& u, int wr, int wc, int fr, int fq) const {
;     ...
;             bf16_t* base = seg == 3 ? asb : ahg;
; #pragma unroll
;             for (int ai = 0; ai < 2; ++ai) {
;                 u32x4 ov[4][2];
; #pragma unroll
;                 for (int m = 0; m < 4; ++m)
; #pragma unroll
;                     for (int bj = 0; bj < 2; ++bj) ov[m][bj] = *(const u32x4*)(base + (size_t)(row0 + ai * 128 + m * 16) * 1024 + col0 + bj * 128);
; #pragma unroll
;                 for (int m = 0; m < 4; ++m)
; #pragma unroll
;                     for (int bj = 0; bj < 2; ++bj) {
;                         const u32x4 o = ov[m][bj];
;                         const f32x4 a = acc[ai][bj][m][0], b = acc[ai][bj][m][1];
;                         u32x4 w;
;                         w.x = cvt_pk_bf16(bf2f(o.x & 0xffffu) * siluf_(a[0]), bf2f(o.x >> 16) * siluf_(a[1]));
;                         w.y = cvt_pk_bf16(bf2f(o.y & 0xffffu) * siluf_(a[2]), bf2f(o.y >> 16) * siluf_(a[3]));
;                         w.z = cvt_pk_bf16(bf2f(o.z & 0xffffu) * siluf_(b[0]), bf2f(o.z >> 16) * siluf_(b[1]));
;                         w.w = cvt_pk_bf16(bf2f(o.w & 0xffffu) * siluf_(b[2]), bf2f(o.w >> 16) * siluf_(b[3]));
;                         *(u32x4*)(base + (size_t)(row0 + ai * 128 + m * 16) * 1024 + col0 + bj * 128) = w;
;                     }
	v_add_f32_e32 v141, 1.0, v160
	v_rcp_f32_e32 v147, v141
	v_cvt_pk_bf16_f32 v141, v144, v145
	v_lshlrev_b32_e32 v144, 16, v142
	v_and_b32_e32 v145, 0xffff0000, v142
	v_mul_f32_e32 v142, 0xbfb8aa3b, v106
	v_exp_f32_e32 v142, v142
	v_mul_f32_e32 v160, 0xbfb8aa3b, v107
	v_exp_f32_e32 v160, v160
	v_pk_mul_f32 v[146:147], v[104:105], v[146:147]
	v_add_f32_e32 v142, 1.0, v142
	v_pk_mul_f32 v[144:145], v[146:147], v[144:145]
	v_rcp_f32_e32 v146, v142
	v_add_f32_e32 v142, 1.0, v160
	v_rcp_f32_e32 v147, v142
	v_cvt_pk_bf16_f32 v142, v144, v145
	v_lshlrev_b32_e32 v144, 16, v143
	v_and_b32_e32 v145, 0xffff0000, v143
	v_pk_mul_f32 v[146:147], v[106:107], v[146:147]
	v_mul_f32_e32 v143, 0xbfb8aa3b, v44
	v_pk_mul_f32 v[144:145], v[146:147], v[144:145]
	v_exp_f32_e32 v146, v143
	v_mul_f32_e32 v143, 0xbfb8aa3b, v45
	v_exp_f32_e32 v147, v143
	v_cvt_pk_bf16_f32 v143, v144, v145
	v_add_f32_e32 v144, 1.0, v146
	v_rcp_f32_e32 v144, v144
	v_add_f32_e32 v145, 1.0, v147
	v_rcp_f32_e32 v145, v145
	global_store_dwordx4 v[150:151], v[140:143], off
	global_load_dwordx4 v[202:205], v[198:199], off
	v_lshl_add_u64 v[210:211], v[178:179], 0, s[40:41]
	v_lshlrev_b32_e32 v140, 16, v136
	v_and_b32_e32 v141, 0xffff0000, v136
	v_mul_f32_e32 v136, 0xbfb8aa3b, v46
	v_pk_mul_f32 v[142:143], v[44:45], v[144:145]
	v_exp_f32_e32 v136, v136
	v_mul_f32_e32 v144, 0xbfb8aa3b, v47
	v_exp_f32_e32 v144, v144
	v_pk_mul_f32 v[140:141], v[142:143], v[140:141]
	v_add_f32_e32 v136, 1.0, v136
	v_rcp_f32_e32 v142, v136
	v_add_f32_e32 v136, 1.0, v144
	v_rcp_f32_e32 v143, v136
	v_cvt_pk_bf16_f32 v136, v140, v141
	v_lshlrev_b32_e32 v140, 16, v137
	v_and_b32_e32 v141, 0xffff0000, v137
	v_mul_f32_e32 v137, 0xbfb8aa3b, v40
	v_exp_f32_e32 v137, v137
	v_mul_f32_e32 v144, 0xbfb8aa3b, v41
	v_exp_f32_e32 v144, v144
	v_pk_mul_f32 v[142:143], v[46:47], v[142:143]
	v_add_f32_e32 v137, 1.0, v137
	v_pk_mul_f32 v[140:141], v[142:143], v[140:141]
	v_rcp_f32_e32 v142, v137
	v_add_f32_e32 v137, 1.0, v144
	v_rcp_f32_e32 v143, v137
	v_cvt_pk_bf16_f32 v137, v140, v141
	v_lshlrev_b32_e32 v140, 16, v138
	v_and_b32_e32 v141, 0xffff0000, v138
	v_mul_f32_e32 v138, 0xbfb8aa3b, v42
	v_exp_f32_e32 v138, v138
	v_mul_f32_e32 v144, 0xbfb8aa3b, v43
	v_exp_f32_e32 v144, v144
	v_pk_mul_f32 v[142:143], v[40:41], v[142:143]
	v_add_f32_e32 v138, 1.0, v138
	v_pk_mul_f32 v[140:141], v[142:143], v[140:141]
	v_rcp_f32_e32 v142, v138
	v_add_f32_e32 v138, 1.0, v144
	v_rcp_f32_e32 v143, v138
	s_cbranch_execz .Ldry_p5a_real
.Ldry_p5a_c3:
	v_cvt_pk_bf16_f32 v138, v140, v141
	v_lshlrev_b32_e32 v140, 16, v139
	v_and_b32_e32 v141, 0xffff0000, v139
	v_pk_mul_f32 v[142:143], v[42:43], v[142:143]
	v_mul_f32_e32 v139, 0xbfb8aa3b, v100
	v_pk_mul_f32 v[140:141], v[142:143], v[140:141]
	v_exp_f32_e32 v142, v139
	v_mul_f32_e32 v139, 0xbfb8aa3b, v101
	v_exp_f32_e32 v143, v139
	v_cvt_pk_bf16_f32 v139, v140, v141
	v_add_f32_e32 v140, 1.0, v142
	v_rcp_f32_e32 v140, v140
	v_add_f32_e32 v141, 1.0, v143
	v_rcp_f32_e32 v141, v141
	global_store_dwordx4 v[150:151], v[136:139], off offset:256
	global_load_dwordx4 v[206:209], v[210:211], off offset:256
	s_mov_b32 s3, 0x48000
	v_lshlrev_b32_e32 v136, 16, v132
	v_and_b32_e32 v137, 0xffff0000, v132
	v_mul_f32_e32 v132, 0xbfb8aa3b, v102
	v_pk_mul_f32 v[138:139], v[100:101], v[140:141]
	v_exp_f32_e32 v132, v132
	v_mul_f32_e32 v140, 0xbfb8aa3b, v103
	v_exp_f32_e32 v140, v140
	v_pk_mul_f32 v[136:137], v[138:139], v[136:137]
	v_add_f32_e32 v132, 1.0, v132
	v_rcp_f32_e32 v138, v132
	v_add_f32_e32 v132, 1.0, v140
	v_rcp_f32_e32 v139, v132
	v_cvt_pk_bf16_f32 v132, v136, v137
	v_lshlrev_b32_e32 v136, 16, v133
	v_and_b32_e32 v137, 0xffff0000, v133
	v_mul_f32_e32 v133, 0xbfb8aa3b, v96
	v_exp_f32_e32 v133, v133
	v_mul_f32_e32 v140, 0xbfb8aa3b, v97
	v_exp_f32_e32 v140, v140
	v_pk_mul_f32 v[138:139], v[102:103], v[138:139]
	v_add_f32_e32 v133, 1.0, v133
	v_pk_mul_f32 v[136:137], v[138:139], v[136:137]
	v_rcp_f32_e32 v138, v133
	v_add_f32_e32 v133, 1.0, v140
	v_rcp_f32_e32 v139, v133
	v_cvt_pk_bf16_f32 v133, v136, v137
	v_lshlrev_b32_e32 v136, 16, v134
	v_and_b32_e32 v137, 0xffff0000, v134
	v_pk_mul_f32 v[138:139], v[96:97], v[138:139]
	v_mul_f32_e32 v134, 0xbfb8aa3b, v98
	v_pk_mul_f32 v[136:137], v[138:139], v[136:137]
	v_exp_f32_e32 v138, v134
	v_mul_f32_e32 v134, 0xbfb8aa3b, v99
	v_exp_f32_e32 v139, v134
	v_cvt_pk_bf16_f32 v134, v136, v137
	v_add_f32_e32 v136, 1.0, v138
	v_rcp_f32_e32 v136, v136
	v_add_f32_e32 v137, 1.0, v139
	v_rcp_f32_e32 v137, v137
	v_lshlrev_b32_e32 v138, 16, v135
	v_and_b32_e32 v139, 0xffff0000, v135
	v_mul_f32_e32 v135, 0xbfb8aa3b, v36
	v_pk_mul_f32 v[136:137], v[98:99], v[136:137]
	v_exp_f32_e32 v140, v135
	v_pk_mul_f32 v[136:137], v[136:137], v[138:139]
	v_add_co_u32_e32 v188, vcc, s3, v178
	v_cvt_pk_bf16_f32 v135, v136, v137
	v_mul_f32_e32 v137, 0xbfb8aa3b, v37
	v_exp_f32_e32 v137, v137
	v_add_f32_e32 v136, 1.0, v140
	v_rcp_f32_e32 v136, v136
	global_store_dwordx4 v[148:149], v[132:135], off
	v_add_f32_e32 v137, 1.0, v137
	v_rcp_f32_e32 v137, v137
	v_lshlrev_b32_e32 v132, 16, v128
	v_and_b32_e32 v133, 0xffff0000, v128
	v_mul_f32_e32 v128, 0xbfb8aa3b, v38
	v_pk_mul_f32 v[134:135], v[36:37], v[136:137]
	v_exp_f32_e32 v128, v128
	v_mul_f32_e32 v136, 0xbfb8aa3b, v39
	v_exp_f32_e32 v136, v136
	v_pk_mul_f32 v[132:133], v[134:135], v[132:133]
	v_add_f32_e32 v128, 1.0, v128
	v_rcp_f32_e32 v134, v128
	v_add_f32_e32 v128, 1.0, v136
	v_rcp_f32_e32 v135, v128
	v_cvt_pk_bf16_f32 v128, v132, v133
	v_lshlrev_b32_e32 v132, 16, v129
	v_and_b32_e32 v133, 0xffff0000, v129
	v_mul_f32_e32 v129, 0xbfb8aa3b, v32
	v_exp_f32_e32 v129, v129
	v_mul_f32_e32 v136, 0xbfb8aa3b, v33
	v_exp_f32_e32 v136, v136
	v_pk_mul_f32 v[134:135], v[38:39], v[134:135]
	v_add_f32_e32 v129, 1.0, v129
	v_pk_mul_f32 v[132:133], v[134:135], v[132:133]
	v_rcp_f32_e32 v134, v129
	v_add_f32_e32 v129, 1.0, v136
	v_rcp_f32_e32 v135, v129
	v_cvt_pk_bf16_f32 v129, v132, v133
	v_lshlrev_b32_e32 v132, 16, v130
	v_and_b32_e32 v133, 0xffff0000, v130
	v_mul_f32_e32 v130, 0xbfb8aa3b, v34
	v_exp_f32_e32 v130, v130
	v_mul_f32_e32 v136, 0xbfb8aa3b, v35
	v_exp_f32_e32 v136, v136
	v_pk_mul_f32 v[134:135], v[32:33], v[134:135]
	v_add_f32_e32 v130, 1.0, v130
	v_pk_mul_f32 v[132:133], v[134:135], v[132:133]
	v_rcp_f32_e32 v134, v130
	v_add_f32_e32 v130, 1.0, v136
	v_rcp_f32_e32 v135, v130
	v_cvt_pk_bf16_f32 v130, v132, v133
	v_lshlrev_b32_e32 v132, 16, v131
	v_and_b32_e32 v133, 0xffff0000, v131
	v_pk_mul_f32 v[134:135], v[34:35], v[134:135]
	s_mov_b64 s[40:41], 0x48000
	s_cbranch_execz .Ldry_p5a_real
; __device__ __forceinline__ unsigned cvt_pk_bf16(float lo, float hi) { f32x2_t v = {lo, hi}; bf16x2_t b = __builtin_convertvector(v, bf16x2_t); return __builtin_bit_cast(unsigned, b); }
; __device__ __forceinline__ float bf2f(unsigned u) { return __uint_as_float(u << 16); }
; __device__ __forceinline__ float siluf_(float v) { return v * sigmoidf_(v); }
;     __device__ __forceinline__ void operator()(const f32x4 (&acc)[2][2][4][2], const pg8::Unit& u, int wr, int wc, int fr, int fq) const {
;     ...
;             bf16_t* base = seg == 3 ? asb : ahg;
; #pragma unroll
;             for (int ai = 0; ai < 2; ++ai) {
;                 u32x4 ov[4][2];
; #pragma unroll
;                 for (int m = 0; m < 4; ++m)
; #pragma unroll
;                     for (int bj = 0; bj < 2; ++bj) ov[m][bj] = *(const u32x4*)(base + (size_t)(row0 + ai * 128 + m * 16) * 1024 + col0 + bj * 128);
; #pragma unroll
;                 for (int m = 0; m < 4; ++m)
; #pragma unroll
;                     for (int bj = 0; bj < 2; ++bj) {
;                         const u32x4 o = ov[m][bj];
;                         const f32x4 a = acc[ai][bj][m][0], b = acc[ai][bj][m][1];
;                         u32x4 w;
;                         w.x = cvt_pk_bf16(bf2f(o.x & 0xffffu) * siluf_(a[0]), bf2f(o.x >> 16) * siluf_(a[1]));
;                         w.y = cvt_pk_bf16(bf2f(o.y & 0xffffu) * siluf_(a[2]), bf2f(o.y >> 16) * siluf_(a[3]));
;                         w.z = cvt_pk_bf16(bf2f(o.z & 0xffffu) * siluf_(b[0]), bf2f(o.z >> 16) * siluf_(b[1]));
;                         w.w = cvt_pk_bf16(bf2f(o.w & 0xffffu) * siluf_(b[2]), bf2f(o.w >> 16) * siluf_(b[3]));
;                         *(u32x4*)(base + (size_t)(row0 + ai * 128 + m * 16) * 1024 + col0 + bj * 128) = w;
;                     }
.Ldry_p5a_c4:
	v_pk_mul_f32 v[132:133], v[134:135], v[132:133]
	v_addc_co_u32_e32 v189, vcc, 0, v179, vcc
	v_cvt_pk_bf16_f32 v131, v132, v133
	global_store_dwordx4 v[148:149], v[128:131], off offset:256
	v_lshl_add_u64 v[186:187], v[178:179], 0, s[40:41]
	global_load_dwordx4 v[148:151], v[188:189], off
	global_load_dwordx4 v[144:147], v[186:187], off offset:256
	v_mul_f32_e32 v128, 0xbfb8aa3b, v92
	v_exp_f32_e32 v128, v128
	v_mul_f32_e32 v129, 0xbfb8aa3b, v93
	v_exp_f32_e32 v129, v129
	v_mul_f32_e32 v160, 0xbfb8aa3b, v94
	v_add_f32_e32 v128, 1.0, v128
	v_rcp_f32_e32 v212, v128
	v_add_f32_e32 v128, 1.0, v129
	v_rcp_f32_e32 v213, v128
	v_exp_f32_e32 v160, v160
	s_waitcnt vmcnt(6)
	v_lshlrev_b32_e32 v214, 16, v202
	v_and_b32_e32 v215, 0xffff0000, v202
	v_pk_mul_f32 v[212:213], v[92:93], v[212:213]
	v_add_f32_e32 v160, 1.0, v160
	v_pk_mul_f32 v[212:213], v[212:213], v[214:215]
	v_rcp_f32_e32 v214, v160
	v_add_f32_e32 v160, 1.0, v197
	v_rcp_f32_e32 v215, v160
	v_mul_f32_e32 v160, 0xbfb8aa3b, v88
	v_exp_f32_e32 v160, v160
	v_mul_f32_e32 v197, 0xbfb8aa3b, v89
	v_exp_f32_e32 v197, v197
	v_cvt_pk_bf16_f32 v202, v212, v213
	v_lshlrev_b32_e32 v212, 16, v203
	v_and_b32_e32 v213, 0xffff0000, v203
	v_pk_mul_f32 v[214:215], v[94:95], v[214:215]
	v_add_f32_e32 v160, 1.0, v160
	v_pk_mul_f32 v[212:213], v[214:215], v[212:213]
	v_rcp_f32_e32 v214, v160
	v_add_f32_e32 v160, 1.0, v197
	v_rcp_f32_e32 v215, v160
	v_mul_f32_e32 v160, 0xbfb8aa3b, v90
	v_exp_f32_e32 v160, v160
	v_mul_f32_e32 v197, 0xbfb8aa3b, v91
	v_exp_f32_e32 v197, v197
	v_cvt_pk_bf16_f32 v203, v212, v213
	v_lshlrev_b32_e32 v212, 16, v204
	v_and_b32_e32 v213, 0xffff0000, v204
	v_pk_mul_f32 v[214:215], v[88:89], v[214:215]
	v_add_f32_e32 v160, 1.0, v160
	v_pk_mul_f32 v[212:213], v[214:215], v[212:213]
	v_rcp_f32_e32 v214, v160
	v_add_f32_e32 v160, 1.0, v197
	v_rcp_f32_e32 v215, v160
	v_mul_f32_e32 v160, 0xbfb8aa3b, v28
	v_exp_f32_e32 v160, v160
	v_mul_f32_e32 v197, 0xbfb8aa3b, v29
	v_exp_f32_e32 v197, v197
	v_cvt_pk_bf16_f32 v204, v212, v213
	v_lshlrev_b32_e32 v212, 16, v205
	v_and_b32_e32 v213, 0xffff0000, v205
	v_pk_mul_f32 v[214:215], v[90:91], v[214:215]
	v_add_f32_e32 v160, 1.0, v160
	v_pk_mul_f32 v[212:213], v[214:215], v[212:213]
	v_add_co_u32_e32 v184, vcc, s85, v178
	v_cvt_pk_bf16_f32 v205, v212, v213
	v_rcp_f32_e32 v212, v160
	v_add_f32_e32 v160, 1.0, v197
	v_rcp_f32_e32 v213, v160
	v_mul_f32_e32 v160, 0xbfb8aa3b, v30
	v_exp_f32_e32 v160, v160
	v_mul_f32_e32 v197, 0xbfb8aa3b, v31
	v_exp_f32_e32 v197, v197
	v_addc_co_u32_e32 v185, vcc, 0, v179, vcc
	s_mov_b32 s3, 0x58000
	v_lshl_add_u64 v[182:183], v[178:179], 0, s[94:95]
	v_lshl_add_u64 v[180:181], v[178:179], 0, s[12:13]
	v_add_co_u32_e32 v178, vcc, s3, v178
	v_add_f32_e32 v160, 1.0, v160
	s_nop 0
	v_addc_co_u32_e32 v179, vcc, 0, v179, vcc
	global_load_dwordx4 v[140:143], v[184:185], off
	global_load_dwordx4 v[136:139], v[182:183], off offset:256
	global_load_dwordx4 v[132:135], v[178:179], off
	global_load_dwordx4 v[128:131], v[180:181], off offset:256
	s_nop 0
	global_store_dwordx4 v[198:199], v[202:205], off
	s_waitcnt vmcnt(9)
	v_lshlrev_b32_e32 v198, 16, v206
	v_and_b32_e32 v199, 0xffff0000, v206
	v_rcp_f32_e32 v204, v160
	v_add_f32_e32 v160, 1.0, v197
	v_rcp_f32_e32 v205, v160
	v_mul_f32_e32 v160, 0xbfb8aa3b, v24
	v_exp_f32_e32 v160, v160
	v_mul_f32_e32 v197, 0xbfb8aa3b, v25
	v_exp_f32_e32 v197, v197
	v_pk_mul_f32 v[202:203], v[28:29], v[212:213]
	v_pk_mul_f32 v[204:205], v[30:31], v[204:205]
	v_pk_mul_f32 v[198:199], v[202:203], v[198:199]
	v_add_f32_e32 v160, 1.0, v160
	v_cvt_pk_bf16_f32 v202, v198, v199
	v_lshlrev_b32_e32 v198, 16, v207
	v_and_b32_e32 v199, 0xffff0000, v207
	v_pk_mul_f32 v[198:199], v[204:205], v[198:199]
	v_rcp_f32_e32 v204, v160
	v_add_f32_e32 v160, 1.0, v197
	v_rcp_f32_e32 v205, v160
	v_mul_f32_e32 v160, 0xbfb8aa3b, v26
	v_exp_f32_e32 v160, v160
	v_mul_f32_e32 v197, 0xbfb8aa3b, v27
	v_exp_f32_e32 v197, v197
	v_cvt_pk_bf16_f32 v203, v198, v199
	v_add_f32_e32 v160, 1.0, v160
	v_rcp_f32_e32 v206, v160
	v_add_f32_e32 v160, 1.0, v197
	s_cbranch_execz .Ldry_p5a_real
.Ldry_p5a_c5:
	v_rcp_f32_e32 v207, v160
	v_mul_f32_e32 v160, 0xbfb8aa3b, v84
	v_lshlrev_b32_e32 v198, 16, v208
	v_and_b32_e32 v199, 0xffff0000, v208
	v_pk_mul_f32 v[204:205], v[24:25], v[204:205]
	v_exp_f32_e32 v160, v160
	v_mul_f32_e32 v197, 0xbfb8aa3b, v85
	v_pk_mul_f32 v[198:199], v[204:205], v[198:199]
	v_exp_f32_e32 v197, v197
	v_cvt_pk_bf16_f32 v204, v198, v199
	v_lshlrev_b32_e32 v198, 16, v209
	v_and_b32_e32 v199, 0xffff0000, v209
	v_pk_mul_f32 v[206:207], v[26:27], v[206:207]
	v_add_f32_e32 v160, 1.0, v160
	v_pk_mul_f32 v[198:199], v[206:207], v[198:199]
	s_nop 0
	v_cvt_pk_bf16_f32 v205, v198, v199
	v_rcp_f32_e32 v198, v160
	v_add_f32_e32 v160, 1.0, v197
	global_store_dwordx4 v[210:211], v[202:205], off offset:256
	v_rcp_f32_e32 v199, v160
	v_mul_f32_e32 v160, 0xbfb8aa3b, v87
	s_waitcnt vmcnt(7)
; __device__ __forceinline__ unsigned cvt_pk_bf16(float lo, float hi) { f32x2_t v = {lo, hi}; bf16x2_t b = __builtin_convertvector(v, bf16x2_t); return __builtin_bit_cast(unsigned, b); }
; __device__ __forceinline__ float bf2f(unsigned u) { return __uint_as_float(u << 16); }
; __device__ __forceinline__ float siluf_(float v) { return v * sigmoidf_(v); }
;     __device__ __forceinline__ void operator()(const f32x4 (&acc)[2][2][4][2], const pg8::Unit& u, int wr, int wc, int fr, int fq) const {
;     ...
;             bf16_t* base = seg == 3 ? asb : ahg;
; #pragma unroll
;             for (int ai = 0; ai < 2; ++ai) {
;                 u32x4 ov[4][2];
; #pragma unroll
;                 for (int m = 0; m < 4; ++m)
; #pragma unroll
;                     for (int bj = 0; bj < 2; ++bj) ov[m][bj] = *(const u32x4*)(base + (size_t)(row0 + ai * 128 + m * 16) * 1024 + col0 + bj * 128);
; #pragma unroll
;                 for (int m = 0; m < 4; ++m)
; #pragma unroll
;                     for (int bj = 0; bj < 2; ++bj) {
;                         const u32x4 o = ov[m][bj];
;                         const f32x4 a = acc[ai][bj][m][0], b = acc[ai][bj][m][1];
;                         u32x4 w;
;                         w.x = cvt_pk_bf16(bf2f(o.x & 0xffffu) * siluf_(a[0]), bf2f(o.x >> 16) * siluf_(a[1]));
;                         w.y = cvt_pk_bf16(bf2f(o.y & 0xffffu) * siluf_(a[2]), bf2f(o.y >> 16) * siluf_(a[3]));
;                         w.z = cvt_pk_bf16(bf2f(o.z & 0xffffu) * siluf_(b[0]), bf2f(o.z >> 16) * siluf_(b[1]));
;                         w.w = cvt_pk_bf16(bf2f(o.w & 0xffffu) * siluf_(b[2]), bf2f(o.w >> 16) * siluf_(b[3]));
;                         *(u32x4*)(base + (size_t)(row0 + ai * 128 + m * 16) * 1024 + col0 + bj * 128) = w;
;                     }
	v_lshlrev_b32_e32 v202, 16, v148
	v_and_b32_e32 v203, 0xffff0000, v148
	v_mul_f32_e32 v148, 0xbfb8aa3b, v86
	v_exp_f32_e32 v148, v148
	v_exp_f32_e32 v160, v160
	v_pk_mul_f32 v[198:199], v[84:85], v[198:199]
	v_add_f32_e32 v148, 1.0, v148
	v_pk_mul_f32 v[198:199], v[198:199], v[202:203]
	v_rcp_f32_e32 v202, v148
	v_add_f32_e32 v148, 1.0, v160
	v_rcp_f32_e32 v203, v148
	v_cvt_pk_bf16_f32 v148, v198, v199
	v_lshlrev_b32_e32 v198, 16, v149
	v_and_b32_e32 v199, 0xffff0000, v149
	v_mul_f32_e32 v149, 0xbfb8aa3b, v80
	v_exp_f32_e32 v149, v149
	v_mul_f32_e32 v160, 0xbfb8aa3b, v81
	v_exp_f32_e32 v160, v160
	v_pk_mul_f32 v[202:203], v[86:87], v[202:203]
	v_add_f32_e32 v149, 1.0, v149
	v_pk_mul_f32 v[198:199], v[202:203], v[198:199]
	v_rcp_f32_e32 v202, v149
	v_add_f32_e32 v149, 1.0, v160
	v_rcp_f32_e32 v203, v149
	v_cvt_pk_bf16_f32 v149, v198, v199
	v_lshlrev_b32_e32 v198, 16, v150
	v_and_b32_e32 v199, 0xffff0000, v150
	v_mul_f32_e32 v150, 0xbfb8aa3b, v82
	v_exp_f32_e32 v150, v150
	v_mul_f32_e32 v160, 0xbfb8aa3b, v83
	v_exp_f32_e32 v160, v160
	v_pk_mul_f32 v[202:203], v[80:81], v[202:203]
	v_add_f32_e32 v150, 1.0, v150
	v_pk_mul_f32 v[198:199], v[202:203], v[198:199]
	v_rcp_f32_e32 v202, v150
	v_add_f32_e32 v150, 1.0, v160
	v_rcp_f32_e32 v203, v150
	v_cvt_pk_bf16_f32 v150, v198, v199
	v_lshlrev_b32_e32 v198, 16, v151
	v_and_b32_e32 v199, 0xffff0000, v151
	v_mul_f32_e32 v151, 0xbfb8aa3b, v20
	v_exp_f32_e32 v160, v151
	v_mul_f32_e32 v151, 0xbfb8aa3b, v21
	v_exp_f32_e32 v197, v151
	v_pk_mul_f32 v[202:203], v[82:83], v[202:203]
	v_add_f32_e32 v160, 1.0, v160
	v_pk_mul_f32 v[198:199], v[202:203], v[198:199]
	s_nop 0
	v_cvt_pk_bf16_f32 v151, v198, v199
	v_rcp_f32_e32 v198, v160
	v_add_f32_e32 v160, 1.0, v197
	global_store_dwordx4 v[188:189], v[148:151], off
	v_rcp_f32_e32 v199, v160
	v_mul_f32_e32 v160, 0xbfb8aa3b, v23
	s_waitcnt vmcnt(7)
	v_lshlrev_b32_e32 v148, 16, v144
	v_and_b32_e32 v149, 0xffff0000, v144
	v_mul_f32_e32 v144, 0xbfb8aa3b, v22
	v_exp_f32_e32 v144, v144
	v_exp_f32_e32 v160, v160
	v_pk_mul_f32 v[150:151], v[20:21], v[198:199]
	v_add_f32_e32 v144, 1.0, v144
	v_pk_mul_f32 v[148:149], v[150:151], v[148:149]
	v_rcp_f32_e32 v150, v144
	v_add_f32_e32 v144, 1.0, v160
	v_rcp_f32_e32 v151, v144
	v_cvt_pk_bf16_f32 v144, v148, v149
	v_lshlrev_b32_e32 v148, 16, v145
	v_and_b32_e32 v149, 0xffff0000, v145
	v_mul_f32_e32 v145, 0xbfb8aa3b, v16
	v_exp_f32_e32 v145, v145
	v_mul_f32_e32 v160, 0xbfb8aa3b, v17
	v_exp_f32_e32 v160, v160
	v_pk_mul_f32 v[150:151], v[22:23], v[150:151]
	v_add_f32_e32 v145, 1.0, v145
	v_pk_mul_f32 v[148:149], v[150:151], v[148:149]
	v_rcp_f32_e32 v150, v145
	v_add_f32_e32 v145, 1.0, v160
	v_rcp_f32_e32 v151, v145
	v_cvt_pk_bf16_f32 v145, v148, v149
	v_lshlrev_b32_e32 v148, 16, v146
	v_and_b32_e32 v149, 0xffff0000, v146
	v_mul_f32_e32 v146, 0xbfb8aa3b, v18
	v_exp_f32_e32 v146, v146
	v_mul_f32_e32 v160, 0xbfb8aa3b, v19
	v_exp_f32_e32 v160, v160
	v_pk_mul_f32 v[150:151], v[16:17], v[150:151]
	v_add_f32_e32 v146, 1.0, v146
	v_pk_mul_f32 v[148:149], v[150:151], v[148:149]
	v_rcp_f32_e32 v150, v146
	v_add_f32_e32 v146, 1.0, v160
	v_rcp_f32_e32 v151, v146
	s_cbranch_execz .Ldry_p5a_real
.Ldry_p5a_c6:
	v_cvt_pk_bf16_f32 v146, v148, v149
	v_lshlrev_b32_e32 v148, 16, v147
	v_and_b32_e32 v149, 0xffff0000, v147
	v_pk_mul_f32 v[150:151], v[18:19], v[150:151]
	v_mul_f32_e32 v147, 0xbfb8aa3b, v76
	v_pk_mul_f32 v[148:149], v[150:151], v[148:149]
	v_exp_f32_e32 v150, v147
	v_mul_f32_e32 v147, 0xbfb8aa3b, v77
	v_exp_f32_e32 v151, v147
	v_cvt_pk_bf16_f32 v147, v148, v149
	v_add_f32_e32 v148, 1.0, v150
	v_rcp_f32_e32 v148, v148
	v_add_f32_e32 v149, 1.0, v151
	v_rcp_f32_e32 v149, v149
	global_store_dwordx4 v[186:187], v[144:147], off offset:256
	s_waitcnt vmcnt(7)
	s_nop 0
	v_lshlrev_b32_e32 v144, 16, v140
	v_and_b32_e32 v145, 0xffff0000, v140
	v_mul_f32_e32 v140, 0xbfb8aa3b, v78
	v_pk_mul_f32 v[146:147], v[76:77], v[148:149]
	v_exp_f32_e32 v140, v140
	v_mul_f32_e32 v148, 0xbfb8aa3b, v79
	v_exp_f32_e32 v148, v148
	v_pk_mul_f32 v[144:145], v[146:147], v[144:145]
	v_add_f32_e32 v140, 1.0, v140
	v_rcp_f32_e32 v146, v140
	v_add_f32_e32 v140, 1.0, v148
	v_rcp_f32_e32 v147, v140
	v_cvt_pk_bf16_f32 v140, v144, v145
	v_lshlrev_b32_e32 v144, 16, v141
	v_and_b32_e32 v145, 0xffff0000, v141
	v_mul_f32_e32 v141, 0xbfb8aa3b, v72
	v_exp_f32_e32 v141, v141
	v_mul_f32_e32 v148, 0xbfb8aa3b, v73
	v_exp_f32_e32 v148, v148
	v_pk_mul_f32 v[146:147], v[78:79], v[146:147]
	v_add_f32_e32 v141, 1.0, v141
	v_pk_mul_f32 v[144:145], v[146:147], v[144:145]
	v_rcp_f32_e32 v146, v141
	v_add_f32_e32 v141, 1.0, v148
	v_rcp_f32_e32 v147, v141
	v_cvt_pk_bf16_f32 v141, v144, v145
	v_lshlrev_b32_e32 v144, 16, v142
	v_and_b32_e32 v145, 0xffff0000, v142
	v_mul_f32_e32 v142, 0xbfb8aa3b, v74
	v_exp_f32_e32 v142, v142
	v_mul_f32_e32 v148, 0xbfb8aa3b, v75
	v_exp_f32_e32 v148, v148
	v_pk_mul_f32 v[146:147], v[72:73], v[146:147]
	v_add_f32_e32 v142, 1.0, v142
	v_pk_mul_f32 v[144:145], v[146:147], v[144:145]
	v_rcp_f32_e32 v146, v142
	v_add_f32_e32 v142, 1.0, v148
	v_rcp_f32_e32 v147, v142
	v_cvt_pk_bf16_f32 v142, v144, v145
	v_lshlrev_b32_e32 v144, 16, v143
	v_and_b32_e32 v145, 0xffff0000, v143
	v_pk_mul_f32 v[146:147], v[74:75], v[146:147]
	v_mul_f32_e32 v143, 0xbfb8aa3b, v12
	v_pk_mul_f32 v[144:145], v[146:147], v[144:145]
	v_exp_f32_e32 v146, v143
	v_mul_f32_e32 v143, 0xbfb8aa3b, v13
	v_exp_f32_e32 v147, v143
	v_cvt_pk_bf16_f32 v143, v144, v145
	v_add_f32_e32 v144, 1.0, v146
	v_rcp_f32_e32 v144, v144
	v_add_f32_e32 v145, 1.0, v147
	v_rcp_f32_e32 v145, v145
	global_store_dwordx4 v[184:185], v[140:143], off
	s_waitcnt vmcnt(7)
; __device__ __forceinline__ unsigned cvt_pk_bf16(float lo, float hi) { f32x2_t v = {lo, hi}; bf16x2_t b = __builtin_convertvector(v, bf16x2_t); return __builtin_bit_cast(unsigned, b); }
; __device__ __forceinline__ float bf2f(unsigned u) { return __uint_as_float(u << 16); }
; __device__ __forceinline__ float siluf_(float v) { return v * sigmoidf_(v); }
;     __device__ __forceinline__ void operator()(const f32x4 (&acc)[2][2][4][2], const pg8::Unit& u, int wr, int wc, int fr, int fq) const {
;     ...
;             bf16_t* base = seg == 3 ? asb : ahg;
; #pragma unroll
;             for (int ai = 0; ai < 2; ++ai) {
;                 u32x4 ov[4][2];
; #pragma unroll
;                 for (int m = 0; m < 4; ++m)
; #pragma unroll
;                     for (int bj = 0; bj < 2; ++bj) ov[m][bj] = *(const u32x4*)(base + (size_t)(row0 + ai * 128 + m * 16) * 1024 + col0 + bj * 128);
; #pragma unroll
;                 for (int m = 0; m < 4; ++m)
; #pragma unroll
;                     for (int bj = 0; bj < 2; ++bj) {
;                         const u32x4 o = ov[m][bj];
;                         const f32x4 a = acc[ai][bj][m][0], b = acc[ai][bj][m][1];
;                         u32x4 w;
;                         w.x = cvt_pk_bf16(bf2f(o.x & 0xffffu) * siluf_(a[0]), bf2f(o.x >> 16) * siluf_(a[1]));
;                         w.y = cvt_pk_bf16(bf2f(o.y & 0xffffu) * siluf_(a[2]), bf2f(o.y >> 16) * siluf_(a[3]));
;                         w.z = cvt_pk_bf16(bf2f(o.z & 0xffffu) * siluf_(b[0]), bf2f(o.z >> 16) * siluf_(b[1]));
;                         w.w = cvt_pk_bf16(bf2f(o.w & 0xffffu) * siluf_(b[2]), bf2f(o.w >> 16) * siluf_(b[3]));
;                         *(u32x4*)(base + (size_t)(row0 + ai * 128 + m * 16) * 1024 + col0 + bj * 128) = w;
;                     }
	s_nop 0
	v_lshlrev_b32_e32 v140, 16, v136
	v_and_b32_e32 v141, 0xffff0000, v136
	v_mul_f32_e32 v136, 0xbfb8aa3b, v14
	v_pk_mul_f32 v[142:143], v[12:13], v[144:145]
	v_exp_f32_e32 v136, v136
	v_mul_f32_e32 v144, 0xbfb8aa3b, v15
	v_exp_f32_e32 v144, v144
	v_pk_mul_f32 v[140:141], v[142:143], v[140:141]
	v_add_f32_e32 v136, 1.0, v136
	v_rcp_f32_e32 v142, v136
	v_add_f32_e32 v136, 1.0, v144
	v_rcp_f32_e32 v143, v136
	v_cvt_pk_bf16_f32 v136, v140, v141
	v_lshlrev_b32_e32 v140, 16, v137
	v_and_b32_e32 v141, 0xffff0000, v137
	v_mul_f32_e32 v137, 0xbfb8aa3b, v8
	v_exp_f32_e32 v137, v137
	v_mul_f32_e32 v144, 0xbfb8aa3b, v9
	v_exp_f32_e32 v144, v144
	v_pk_mul_f32 v[142:143], v[14:15], v[142:143]
	v_add_f32_e32 v137, 1.0, v137
	v_pk_mul_f32 v[140:141], v[142:143], v[140:141]
	v_rcp_f32_e32 v142, v137
	v_add_f32_e32 v137, 1.0, v144
	v_rcp_f32_e32 v143, v137
	v_cvt_pk_bf16_f32 v137, v140, v141
	v_lshlrev_b32_e32 v140, 16, v138
	v_and_b32_e32 v141, 0xffff0000, v138
	v_mul_f32_e32 v138, 0xbfb8aa3b, v10
	v_exp_f32_e32 v138, v138
	v_mul_f32_e32 v144, 0xbfb8aa3b, v11
	v_exp_f32_e32 v144, v144
	v_pk_mul_f32 v[142:143], v[8:9], v[142:143]
	v_add_f32_e32 v138, 1.0, v138
	v_pk_mul_f32 v[140:141], v[142:143], v[140:141]
	v_rcp_f32_e32 v142, v138
	v_add_f32_e32 v138, 1.0, v144
	v_rcp_f32_e32 v143, v138
	v_cvt_pk_bf16_f32 v138, v140, v141
	v_lshlrev_b32_e32 v140, 16, v139
	v_and_b32_e32 v141, 0xffff0000, v139
	v_pk_mul_f32 v[142:143], v[10:11], v[142:143]
	v_mul_f32_e32 v139, 0xbfb8aa3b, v68
	s_cbranch_execz .Ldry_p5a_real
.Ldry_p5a_c7:
	v_pk_mul_f32 v[140:141], v[142:143], v[140:141]
	v_exp_f32_e32 v142, v139
	v_mul_f32_e32 v139, 0xbfb8aa3b, v69
	v_exp_f32_e32 v143, v139
	v_cvt_pk_bf16_f32 v139, v140, v141
	v_add_f32_e32 v140, 1.0, v142
	v_rcp_f32_e32 v140, v140
	v_add_f32_e32 v141, 1.0, v143
	v_rcp_f32_e32 v141, v141
	global_store_dwordx4 v[182:183], v[136:139], off offset:256
	s_waitcnt vmcnt(7)
	s_nop 0
	v_lshlrev_b32_e32 v136, 16, v132
	v_and_b32_e32 v137, 0xffff0000, v132
	v_mul_f32_e32 v132, 0xbfb8aa3b, v70
	v_pk_mul_f32 v[138:139], v[68:69], v[140:141]
	v_exp_f32_e32 v132, v132
	v_mul_f32_e32 v140, 0xbfb8aa3b, v71
	v_exp_f32_e32 v140, v140
	v_pk_mul_f32 v[136:137], v[138:139], v[136:137]
	v_add_f32_e32 v132, 1.0, v132
	v_rcp_f32_e32 v138, v132
	v_add_f32_e32 v132, 1.0, v140
	v_rcp_f32_e32 v139, v132
	v_cvt_pk_bf16_f32 v132, v136, v137
	v_lshlrev_b32_e32 v136, 16, v133
	v_and_b32_e32 v137, 0xffff0000, v133
	v_mul_f32_e32 v133, 0xbfb8aa3b, v64
	v_exp_f32_e32 v133, v133
	v_mul_f32_e32 v140, 0xbfb8aa3b, v65
	v_exp_f32_e32 v140, v140
	v_pk_mul_f32 v[138:139], v[70:71], v[138:139]
	v_add_f32_e32 v133, 1.0, v133
	v_pk_mul_f32 v[136:137], v[138:139], v[136:137]
	v_rcp_f32_e32 v138, v133
	v_add_f32_e32 v133, 1.0, v140
	v_rcp_f32_e32 v139, v133
	v_cvt_pk_bf16_f32 v133, v136, v137
	v_lshlrev_b32_e32 v136, 16, v134
	v_and_b32_e32 v137, 0xffff0000, v134
	v_mul_f32_e32 v134, 0xbfb8aa3b, v66
	v_exp_f32_e32 v134, v134
	v_mul_f32_e32 v140, 0xbfb8aa3b, v67
	v_exp_f32_e32 v140, v140
	v_pk_mul_f32 v[138:139], v[64:65], v[138:139]
	v_add_f32_e32 v134, 1.0, v134
	v_pk_mul_f32 v[136:137], v[138:139], v[136:137]
	v_rcp_f32_e32 v138, v134
	v_add_f32_e32 v134, 1.0, v140
	v_rcp_f32_e32 v139, v134
	v_cvt_pk_bf16_f32 v134, v136, v137
	v_lshlrev_b32_e32 v136, 16, v135
	v_and_b32_e32 v137, 0xffff0000, v135
	v_pk_mul_f32 v[138:139], v[66:67], v[138:139]
	v_mul_f32_e32 v135, 0xbfb8aa3b, v4
	v_pk_mul_f32 v[136:137], v[138:139], v[136:137]
	v_exp_f32_e32 v138, v135
	v_mul_f32_e32 v135, 0xbfb8aa3b, v5
	v_exp_f32_e32 v139, v135
	v_cvt_pk_bf16_f32 v135, v136, v137
	v_add_f32_e32 v136, 1.0, v138
	v_rcp_f32_e32 v136, v136
	v_add_f32_e32 v137, 1.0, v139
	v_rcp_f32_e32 v137, v137
	global_store_dwordx4 v[178:179], v[132:135], off
	s_waitcnt vmcnt(7)
	s_nop 0
	v_lshlrev_b32_e32 v132, 16, v128
	v_and_b32_e32 v133, 0xffff0000, v128
	v_mul_f32_e32 v128, 0xbfb8aa3b, v6
	v_pk_mul_f32 v[134:135], v[4:5], v[136:137]
	v_exp_f32_e32 v128, v128
	v_mul_f32_e32 v136, 0xbfb8aa3b, v7
	v_exp_f32_e32 v136, v136
	v_pk_mul_f32 v[132:133], v[134:135], v[132:133]
	v_add_f32_e32 v128, 1.0, v128
	v_rcp_f32_e32 v134, v128
	v_add_f32_e32 v128, 1.0, v136
	v_rcp_f32_e32 v135, v128
	v_cvt_pk_bf16_f32 v128, v132, v133
	v_lshlrev_b32_e32 v132, 16, v129
	v_and_b32_e32 v133, 0xffff0000, v129
	v_mul_f32_e32 v129, 0xbfb8aa3b, v0
	v_exp_f32_e32 v129, v129
	v_mul_f32_e32 v136, 0xbfb8aa3b, v1
	v_exp_f32_e32 v136, v136
	v_pk_mul_f32 v[134:135], v[6:7], v[134:135]
	v_add_f32_e32 v129, 1.0, v129
	v_pk_mul_f32 v[132:133], v[134:135], v[132:133]
	v_rcp_f32_e32 v134, v129
	v_add_f32_e32 v129, 1.0, v136
	v_rcp_f32_e32 v135, v129
	v_cvt_pk_bf16_f32 v129, v132, v133
	v_lshlrev_b32_e32 v132, 16, v130
	v_and_b32_e32 v133, 0xffff0000, v130
	v_mul_f32_e32 v130, 0xbfb8aa3b, v2
	v_exp_f32_e32 v130, v130
	v_mul_f32_e32 v136, 0xbfb8aa3b, v3
	v_exp_f32_e32 v136, v136
	v_pk_mul_f32 v[134:135], v[0:1], v[134:135]
	v_add_f32_e32 v130, 1.0, v130
	v_pk_mul_f32 v[132:133], v[134:135], v[132:133]
	v_rcp_f32_e32 v134, v130
	v_add_f32_e32 v130, 1.0, v136
	v_rcp_f32_e32 v135, v130
	v_cvt_pk_bf16_f32 v130, v132, v133
	v_lshlrev_b32_e32 v132, 16, v131
	v_and_b32_e32 v133, 0xffff0000, v131
	v_pk_mul_f32 v[134:135], v[2:3], v[134:135]
	s_nop 0
	v_pk_mul_f32 v[132:133], v[134:135], v[132:133]
	s_nop 0
	v_cvt_pk_bf16_f32 v131, v132, v133
	global_store_dwordx4 v[180:181], v[128:131], off offset:256
	s_cbranch_execz .Ldry_p5a_real
	s_cbranch_execz .LBB0_531

; __device__ __forceinline__ unsigned cvt_pk_bf16(float lo, float hi) { f32x2_t v = {lo, hi}; bf16x2_t b = __builtin_convertvector(v, bf16x2_t); return __builtin_bit_cast(unsigned, b); }
; __device__ __forceinline__ float sigmoidf_(float v) { return __builtin_amdgcn_rcpf(1.f + __expf(-v)); }
;     __device__ __forceinline__ void operator()(const f32x4 (&acc)[2][2][4][2], const pg8::Unit& u, int wr, int wc, int fr, int fq) const {
;     ...
;         if (seg >= 8) {
; #pragma unroll
;             for (int bj = 0; bj < 2; ++bj) {
;                 const int col = (seg - 8) * 1024 + col0 + bj * 128;
;                 const f32x4 b0 = *(const f32x4*)(bgate + col), b1 = *(const f32x4*)(bgate + col + 4);
; #pragma unroll
;                 for (int ai = 0; ai < 2; ++ai)
; #pragma unroll
;                     for (int m = 0; m < 4; ++m) {
;                         f32x4 a = acc[ai][bj][m][0] + b0, b = acc[ai][bj][m][1] + b1;
; #pragma unroll
;                         for (int j = 0; j < 4; ++j) { a[j] = sigmoidf_(a[j]); b[j] = sigmoidf_(b[j]); }
;                         u32x4 w; w.x = cvt_pk_bf16(a[0], a[1]); w.y = cvt_pk_bf16(a[2], a[3]); w.z = cvt_pk_bf16(b[0], b[1]); w.w = cvt_pk_bf16(b[2], b[3]);
;                         *(u32x4*)(gates + (size_t)(row0 + ai * 128 + m * 16) * 2048 + col) = w;
;                     }
;             }
.LBB0_531:
	s_mov_b64 s[100:101], s[26:27]
	v_readfirstlane_b32 s98, v200
	s_nop 0
	s_lshr_b32 s98, s98, 6
	s_cmp_eq_u32 s98, 0
	s_cbranch_scc1 .Ldry_p5b_real
	s_mov_b64 exec, 0
	s_cmp_eq_u32 s98, 1
	s_cbranch_scc1 .Ldry_p5b_c1
	s_cmp_eq_u32 s98, 2
	s_cbranch_scc1 .Ldry_p5b_c2
	s_cmp_eq_u32 s98, 3
	s_cbranch_scc1 .Ldry_p5b_c3
	s_cmp_eq_u32 s98, 4
	s_cbranch_scc1 .Ldry_p5b_c4
	s_cmp_eq_u32 s98, 5
	s_cbranch_scc1 .Ldry_p5b_c5
	s_cmp_eq_u32 s98, 6
	s_cbranch_scc1 .Ldry_p5b_c6
	s_branch .Ldry_p5b_c7
.Ldry_p5b_real:
	s_mov_b64 exec, -1
	s_mov_b64 s[26:27], s[100:101]
	s_lshl_b32 s3, s27, 10
	s_addk_i32 s3, 0xe000
	v_readlane_b32 s12, v250, 1
	v_or_b32_e32 v160, s3, v196
	v_readlane_b32 s18, v250, 7
	v_readlane_b32 s19, v250, 8
	v_lshlrev_b64 v[136:137], 12, v[176:177]
	v_lshlrev_b64 v[140:141], 12, v[174:175]
	v_lshl_add_u64 v[138:139], v[160:161], 2, s[18:19]
	global_load_dwordx4 v[132:135], v[138:139], off
	global_load_dwordx4 v[128:131], v[138:139], off offset:16
	v_lshl_add_u64 v[136:137], s[72:73], 0, v[136:137]
	v_lshl_add_u64 v[142:143], s[72:73], 0, v[140:141]
	v_lshlrev_b64 v[144:145], 1, v[160:161]
	v_lshl_add_u64 v[140:141], v[136:137], 0, v[144:145]
	v_lshl_add_u64 v[136:137], v[142:143], 0, v[144:145]
	s_mov_b32 s3, 0x80000
	v_readlane_b32 s13, v250, 2
	s_mov_b64 s[12:13], 0x90000
	v_readlane_b32 s14, v250, 3
	v_readlane_b32 s15, v250, 4
	v_readlane_b32 s16, v250, 5
	v_readlane_b32 s17, v250, 6
	v_readlane_b32 s20, v250, 9
	v_readlane_b32 s21, v250, 10
	v_readlane_b32 s22, v250, 11
	v_readlane_b32 s23, v250, 12
	v_readlane_b32 s24, v250, 13
	v_readlane_b32 s25, v250, 14
	v_readlane_b32 s26, v250, 15
	v_readlane_b32 s27, v250, 16
	s_waitcnt vmcnt(0)
	v_pk_add_f32 v[126:127], v[126:127], v[134:135]
	v_pk_add_f32 v[124:125], v[124:125], v[132:133]
	v_pk_add_f32 v[122:123], v[122:123], v[130:131]
	v_pk_add_f32 v[120:121], v[120:121], v[128:129]
	v_pk_add_f32 v[118:119], v[118:119], v[134:135]
	v_pk_add_f32 v[116:117], v[116:117], v[132:133]
	v_pk_add_f32 v[114:115], v[114:115], v[130:131]
	v_pk_add_f32 v[112:113], v[112:113], v[128:129]
	v_pk_add_f32 v[142:143], v[110:111], v[134:135]
	v_pk_add_f32 v[146:147], v[108:109], v[132:133]
	v_mul_f32_e32 v108, 0xbfb8aa3b, v124
	v_mul_f32_e32 v109, 0xbfb8aa3b, v120
	v_mul_f32_e32 v110, 0xbfb8aa3b, v125
	v_mul_f32_e32 v111, 0xbfb8aa3b, v121
	v_mul_f32_e32 v120, 0xbfb8aa3b, v126
	v_mul_f32_e32 v121, 0xbfb8aa3b, v122
	v_mul_f32_e32 v122, 0xbfb8aa3b, v127
	v_mul_f32_e32 v123, 0xbfb8aa3b, v123
	v_mul_f32_e32 v116, 0xbfb8aa3b, v116
	v_mul_f32_e32 v112, 0xbfb8aa3b, v112
	v_mul_f32_e32 v117, 0xbfb8aa3b, v117
	v_mul_f32_e32 v113, 0xbfb8aa3b, v113
	v_mul_f32_e32 v118, 0xbfb8aa3b, v118
	v_mul_f32_e32 v114, 0xbfb8aa3b, v114
	v_mul_f32_e32 v119, 0xbfb8aa3b, v119
	v_mul_f32_e32 v115, 0xbfb8aa3b, v115
	v_exp_f32_e32 v108, v108
	v_exp_f32_e32 v109, v109
	v_exp_f32_e32 v110, v110
	v_exp_f32_e32 v111, v111
	v_exp_f32_e32 v120, v120
	v_exp_f32_e32 v121, v121
	v_exp_f32_e32 v122, v122
	v_exp_f32_e32 v123, v123
	v_exp_f32_e32 v116, v116
	v_exp_f32_e32 v112, v112
	v_exp_f32_e32 v117, v117
	v_exp_f32_e32 v113, v113
	v_exp_f32_e32 v118, v118
	v_exp_f32_e32 v114, v114
	v_exp_f32_e32 v119, v119
	v_exp_f32_e32 v115, v115
	v_add_f32_e32 v108, 1.0, v108
	v_add_f32_e32 v109, 1.0, v109
	v_add_f32_e32 v110, 1.0, v110
	v_add_f32_e32 v111, 1.0, v111
	v_add_f32_e32 v120, 1.0, v120
	v_add_f32_e32 v121, 1.0, v121
	v_add_f32_e32 v122, 1.0, v122
	v_add_f32_e32 v123, 1.0, v123
	v_add_f32_e32 v116, 1.0, v116
	v_add_f32_e32 v112, 1.0, v112
	v_add_f32_e32 v117, 1.0, v117
	v_add_f32_e32 v113, 1.0, v113
	v_add_f32_e32 v118, 1.0, v118
	v_add_f32_e32 v114, 1.0, v114
	v_add_f32_e32 v119, 1.0, v119
	s_cbranch_execz .Ldry_p5b_real
.Ldry_p5b_c1:
	v_add_f32_e32 v115, 1.0, v115
	v_rcp_f32_e32 v108, v108
	v_rcp_f32_e32 v124, v109
	v_rcp_f32_e32 v109, v110
	v_rcp_f32_e32 v110, v111
	v_rcp_f32_e32 v111, v120
	v_rcp_f32_e32 v120, v121
	v_rcp_f32_e32 v121, v122
	v_rcp_f32_e32 v122, v123
	v_rcp_f32_e32 v116, v116
	v_rcp_f32_e32 v123, v112
	v_rcp_f32_e32 v112, v117
	v_rcp_f32_e32 v117, v113
	v_rcp_f32_e32 v113, v118
	v_rcp_f32_e32 v118, v114
	v_rcp_f32_e32 v114, v119
	v_rcp_f32_e32 v115, v115
	v_cvt_pk_bf16_f32 v108, v108, v109
	v_cvt_pk_bf16_f32 v109, v111, v121
	v_cvt_pk_bf16_f32 v110, v124, v110
	v_cvt_pk_bf16_f32 v111, v120, v122
	v_pk_add_f32 v[104:105], v[104:105], v[128:129]
	v_pk_add_f32 v[106:107], v[106:107], v[130:131]
	v_cvt_pk_bf16_f32 v112, v116, v112
	v_cvt_pk_bf16_f32 v113, v113, v114
	v_cvt_pk_bf16_f32 v114, v123, v117
	v_cvt_pk_bf16_f32 v115, v118, v115
	global_store_dwordx4 v[140:141], v[108:111], off
	global_store_dwordx4 v[136:137], v[112:115], off
	v_mul_f32_e32 v104, 0xbfb8aa3b, v104
	v_mul_f32_e32 v108, 0xbfb8aa3b, v146
	v_mul_f32_e32 v109, 0xbfb8aa3b, v147
	v_mul_f32_e32 v105, 0xbfb8aa3b, v105
	v_mul_f32_e32 v106, 0xbfb8aa3b, v106
	v_exp_f32_e32 v108, v108
	v_exp_f32_e32 v104, v104
	v_exp_f32_e32 v109, v109
	v_exp_f32_e32 v105, v105
	v_exp_f32_e32 v106, v106
	v_mul_f32_e32 v111, 0xbfb8aa3b, v143
	v_mul_f32_e32 v110, 0xbfb8aa3b, v142
	v_exp_f32_e32 v111, v111
	v_mul_f32_e32 v107, 0xbfb8aa3b, v107
	v_exp_f32_e32 v110, v110
	v_exp_f32_e32 v107, v107
	v_add_f32_e32 v108, 1.0, v108
	v_add_f32_e32 v104, 1.0, v104
	v_add_f32_e32 v109, 1.0, v109
	v_add_f32_e32 v105, 1.0, v105
	v_add_f32_e32 v106, 1.0, v106
	v_rcp_f32_e32 v108, v108
	v_rcp_f32_e32 v104, v104
	v_rcp_f32_e32 v109, v109
	v_rcp_f32_e32 v105, v105
	v_rcp_f32_e32 v112, v106
	v_add_f32_e32 v106, 1.0, v111
	v_pk_add_f32 v[100:101], v[100:101], v[132:133]
	v_pk_add_f32 v[96:97], v[96:97], v[128:129]
	v_pk_add_f32 v[98:99], v[98:99], v[130:131]
	v_add_f32_e32 v110, 1.0, v110
	v_rcp_f32_e32 v111, v106
	v_add_f32_e32 v106, 1.0, v107
	v_pk_add_f32 v[102:103], v[102:103], v[134:135]
	v_mul_f32_e32 v100, 0xbfb8aa3b, v100
	v_mul_f32_e32 v96, 0xbfb8aa3b, v96
	v_mul_f32_e32 v101, 0xbfb8aa3b, v101
	v_mul_f32_e32 v97, 0xbfb8aa3b, v97
	v_mul_f32_e32 v98, 0xbfb8aa3b, v98
	v_rcp_f32_e32 v110, v110
	v_rcp_f32_e32 v113, v106
	v_exp_f32_e32 v100, v100
	v_exp_f32_e32 v96, v96
	v_exp_f32_e32 v101, v101
	v_exp_f32_e32 v97, v97
	v_exp_f32_e32 v98, v98
	v_mul_f32_e32 v103, 0xbfb8aa3b, v103
	v_mul_f32_e32 v102, 0xbfb8aa3b, v102
	v_exp_f32_e32 v103, v103
	v_mul_f32_e32 v99, 0xbfb8aa3b, v99
	v_cvt_pk_bf16_f32 v106, v108, v109
	v_cvt_pk_bf16_f32 v108, v104, v105
	v_lshlrev_b64 v[104:105], 12, v[172:173]
	v_exp_f32_e32 v102, v102
	v_exp_f32_e32 v99, v99
	v_lshl_add_u64 v[104:105], s[72:73], 0, v[104:105]
	v_cvt_pk_bf16_f32 v107, v110, v111
	v_cvt_pk_bf16_f32 v109, v112, v113
	v_lshl_add_u64 v[104:105], v[104:105], 0, v[144:145]
	v_add_f32_e32 v100, 1.0, v100
	s_cbranch_execz .Ldry_p5b_real
; __device__ __forceinline__ unsigned cvt_pk_bf16(float lo, float hi) { f32x2_t v = {lo, hi}; bf16x2_t b = __builtin_convertvector(v, bf16x2_t); return __builtin_bit_cast(unsigned, b); }
; __device__ __forceinline__ float sigmoidf_(float v) { return __builtin_amdgcn_rcpf(1.f + __expf(-v)); }
;     __device__ __forceinline__ void operator()(const f32x4 (&acc)[2][2][4][2], const pg8::Unit& u, int wr, int wc, int fr, int fq) const {
;     ...
;         if (seg >= 8) {
; #pragma unroll
;             for (int bj = 0; bj < 2; ++bj) {
;                 const int col = (seg - 8) * 1024 + col0 + bj * 128;
;                 const f32x4 b0 = *(const f32x4*)(bgate + col), b1 = *(const f32x4*)(bgate + col + 4);
; #pragma unroll
;                 for (int ai = 0; ai < 2; ++ai)
; #pragma unroll
;                     for (int m = 0; m < 4; ++m) {
;                         f32x4 a = acc[ai][bj][m][0] + b0, b = acc[ai][bj][m][1] + b1;
; #pragma unroll
;                         for (int j = 0; j < 4; ++j) { a[j] = sigmoidf_(a[j]); b[j] = sigmoidf_(b[j]); }
;                         u32x4 w; w.x = cvt_pk_bf16(a[0], a[1]); w.y = cvt_pk_bf16(a[2], a[3]); w.z = cvt_pk_bf16(b[0], b[1]); w.w = cvt_pk_bf16(b[2], b[3]);
;                         *(u32x4*)(gates + (size_t)(row0 + ai * 128 + m * 16) * 2048 + col) = w;
;                     }
;             }
.Ldry_p5b_c2:
	v_add_f32_e32 v96, 1.0, v96
	v_add_f32_e32 v101, 1.0, v101
	v_add_f32_e32 v97, 1.0, v97
	v_add_f32_e32 v98, 1.0, v98
	global_store_dwordx4 v[104:105], v[106:109], off
	v_rcp_f32_e32 v100, v100
	v_rcp_f32_e32 v96, v96
	v_rcp_f32_e32 v101, v101
	v_rcp_f32_e32 v97, v97
	v_rcp_f32_e32 v106, v98
	v_add_f32_e32 v98, 1.0, v103
	v_pk_add_f32 v[88:89], v[88:89], v[128:129]
	v_add_f32_e32 v102, 1.0, v102
	v_rcp_f32_e32 v103, v98
	v_add_f32_e32 v98, 1.0, v99
	v_pk_add_f32 v[92:93], v[92:93], v[132:133]
	v_mul_f32_e32 v88, 0xbfb8aa3b, v88
	v_rcp_f32_e32 v102, v102
	v_rcp_f32_e32 v107, v98
	v_exp_f32_e32 v88, v88
	v_mul_f32_e32 v93, 0xbfb8aa3b, v93
	v_exp_f32_e32 v93, v93
	v_cvt_pk_bf16_f32 v98, v100, v101
	v_cvt_pk_bf16_f32 v100, v96, v97
	v_lshlrev_b64 v[96:97], 12, v[170:171]
	v_lshl_add_u64 v[96:97], s[72:73], 0, v[96:97]
	v_cvt_pk_bf16_f32 v99, v102, v103
	v_cvt_pk_bf16_f32 v101, v106, v107
	v_lshl_add_u64 v[96:97], v[96:97], 0, v[144:145]
	v_pk_add_f32 v[94:95], v[94:95], v[134:135]
	v_add_f32_e32 v88, 1.0, v88
	v_mul_f32_e32 v89, 0xbfb8aa3b, v89
	global_store_dwordx4 v[96:97], v[98:101], off
	v_exp_f32_e32 v89, v89
	v_pk_add_f32 v[90:91], v[90:91], v[130:131]
	v_rcp_f32_e32 v98, v88
	v_add_f32_e32 v88, 1.0, v93
	v_mul_f32_e32 v93, 0xbfb8aa3b, v94
	v_exp_f32_e32 v93, v93
	v_mul_f32_e32 v92, 0xbfb8aa3b, v92
	v_add_f32_e32 v89, 1.0, v89
	v_mul_f32_e32 v90, 0xbfb8aa3b, v90
	v_exp_f32_e32 v92, v92
	v_exp_f32_e32 v90, v90
	v_rcp_f32_e32 v94, v89
	v_add_f32_e32 v89, 1.0, v93
	v_mul_f32_e32 v93, 0xbfb8aa3b, v95
	v_mul_f32_e32 v91, 0xbfb8aa3b, v91
	v_exp_f32_e32 v93, v93
	v_exp_f32_e32 v91, v91
	v_add_f32_e32 v92, 1.0, v92
	v_add_f32_e32 v90, 1.0, v90
	v_pk_add_f32 v[80:81], v[80:81], v[128:129]
	v_rcp_f32_e32 v92, v92
	v_rcp_f32_e32 v88, v88
	v_rcp_f32_e32 v95, v90
	v_add_f32_e32 v90, 1.0, v93
	v_add_f32_e32 v91, 1.0, v91
	v_pk_add_f32 v[84:85], v[84:85], v[132:133]
	v_mul_f32_e32 v80, 0xbfb8aa3b, v80
	v_rcp_f32_e32 v89, v89
	v_rcp_f32_e32 v90, v90
	v_rcp_f32_e32 v91, v91
	v_exp_f32_e32 v80, v80
	v_mul_f32_e32 v85, 0xbfb8aa3b, v85
	v_exp_f32_e32 v85, v85
	v_cvt_pk_bf16_f32 v88, v92, v88
	v_add_co_u32_e32 v92, vcc, s3, v140
	v_cvt_pk_bf16_f32 v89, v89, v90
	v_cvt_pk_bf16_f32 v90, v98, v94
	v_cvt_pk_bf16_f32 v91, v95, v91
	v_addc_co_u32_e32 v93, vcc, 0, v141, vcc
	v_pk_add_f32 v[86:87], v[86:87], v[134:135]
	v_add_f32_e32 v80, 1.0, v80
	v_mul_f32_e32 v81, 0xbfb8aa3b, v81
	global_store_dwordx4 v[92:93], v[88:91], off
	v_exp_f32_e32 v81, v81
	v_pk_add_f32 v[82:83], v[82:83], v[130:131]
	v_rcp_f32_e32 v88, v80
	v_add_f32_e32 v80, 1.0, v85
	v_mul_f32_e32 v85, 0xbfb8aa3b, v86
	v_exp_f32_e32 v85, v85
	v_mul_f32_e32 v84, 0xbfb8aa3b, v84
	v_add_f32_e32 v81, 1.0, v81
	v_mul_f32_e32 v82, 0xbfb8aa3b, v82
	v_exp_f32_e32 v84, v84
	v_exp_f32_e32 v82, v82
	v_rcp_f32_e32 v86, v81
	v_add_f32_e32 v81, 1.0, v85
	s_cbranch_execz .Ldry_p5b_real
.Ldry_p5b_c3:
	v_mul_f32_e32 v85, 0xbfb8aa3b, v87
	v_mul_f32_e32 v83, 0xbfb8aa3b, v83
	v_exp_f32_e32 v85, v85
	v_exp_f32_e32 v83, v83
	v_add_f32_e32 v84, 1.0, v84
	v_add_f32_e32 v82, 1.0, v82
	v_pk_add_f32 v[72:73], v[72:73], v[128:129]
	v_rcp_f32_e32 v84, v84
	v_rcp_f32_e32 v80, v80
	v_rcp_f32_e32 v87, v82
	v_add_f32_e32 v82, 1.0, v85
	v_add_f32_e32 v83, 1.0, v83
	v_pk_add_f32 v[76:77], v[76:77], v[132:133]
	v_mul_f32_e32 v72, 0xbfb8aa3b, v72
	v_rcp_f32_e32 v81, v81
	v_rcp_f32_e32 v82, v82
	v_rcp_f32_e32 v83, v83
	v_exp_f32_e32 v72, v72
	v_mul_f32_e32 v77, 0xbfb8aa3b, v77
	v_exp_f32_e32 v77, v77
	s_mov_b32 s3, 0x90000
	v_cvt_pk_bf16_f32 v80, v84, v80
	v_add_co_u32_e32 v84, vcc, s3, v140
	v_cvt_pk_bf16_f32 v81, v81, v82
	v_cvt_pk_bf16_f32 v82, v88, v86
	v_cvt_pk_bf16_f32 v83, v87, v83
	v_addc_co_u32_e32 v85, vcc, 0, v141, vcc
	v_pk_add_f32 v[78:79], v[78:79], v[134:135]
	v_add_f32_e32 v72, 1.0, v72
	v_mul_f32_e32 v73, 0xbfb8aa3b, v73
	global_store_dwordx4 v[84:85], v[80:83], off
	v_exp_f32_e32 v73, v73
	v_pk_add_f32 v[74:75], v[74:75], v[130:131]
	v_rcp_f32_e32 v80, v72
	v_add_f32_e32 v72, 1.0, v77
	v_mul_f32_e32 v77, 0xbfb8aa3b, v78
	v_exp_f32_e32 v77, v77
	v_mul_f32_e32 v76, 0xbfb8aa3b, v76
	v_add_f32_e32 v73, 1.0, v73
	v_mul_f32_e32 v74, 0xbfb8aa3b, v74
	v_exp_f32_e32 v76, v76
	v_exp_f32_e32 v74, v74
	v_rcp_f32_e32 v78, v73
	v_add_f32_e32 v73, 1.0, v77
	v_mul_f32_e32 v77, 0xbfb8aa3b, v79
	v_mul_f32_e32 v75, 0xbfb8aa3b, v75
	v_exp_f32_e32 v77, v77
	v_exp_f32_e32 v75, v75
	v_add_f32_e32 v76, 1.0, v76
	v_add_f32_e32 v74, 1.0, v74
	v_pk_add_f32 v[64:65], v[64:65], v[128:129]
	v_rcp_f32_e32 v76, v76
	v_rcp_f32_e32 v72, v72
	v_rcp_f32_e32 v79, v74
	v_add_f32_e32 v74, 1.0, v77
	v_add_f32_e32 v75, 1.0, v75
	v_pk_add_f32 v[68:69], v[68:69], v[132:133]
	v_mul_f32_e32 v64, 0xbfb8aa3b, v64
	v_rcp_f32_e32 v73, v73
	v_rcp_f32_e32 v74, v74
	v_rcp_f32_e32 v75, v75
	v_exp_f32_e32 v64, v64
	v_mul_f32_e32 v69, 0xbfb8aa3b, v69
	v_exp_f32_e32 v69, v69
	v_cvt_pk_bf16_f32 v72, v76, v72
	v_add_co_u32_e32 v76, vcc, s90, v140
	v_cvt_pk_bf16_f32 v73, v73, v74
	v_cvt_pk_bf16_f32 v74, v80, v78
	v_cvt_pk_bf16_f32 v75, v79, v75
	v_addc_co_u32_e32 v77, vcc, 0, v141, vcc
	v_pk_add_f32 v[70:71], v[70:71], v[134:135]
	v_add_f32_e32 v64, 1.0, v64
	v_mul_f32_e32 v65, 0xbfb8aa3b, v65
	global_store_dwordx4 v[76:77], v[72:75], off
	v_exp_f32_e32 v65, v65
	v_pk_add_f32 v[66:67], v[66:67], v[130:131]
	v_rcp_f32_e32 v72, v64
	v_add_f32_e32 v64, 1.0, v69
	v_mul_f32_e32 v69, 0xbfb8aa3b, v70
	v_exp_f32_e32 v69, v69
	v_mul_f32_e32 v68, 0xbfb8aa3b, v68
	v_add_f32_e32 v65, 1.0, v65
	v_mul_f32_e32 v66, 0xbfb8aa3b, v66
	v_exp_f32_e32 v68, v68
	v_exp_f32_e32 v66, v66
	v_rcp_f32_e32 v70, v65
	v_add_f32_e32 v65, 1.0, v69
	v_mul_f32_e32 v69, 0xbfb8aa3b, v71
	v_mul_f32_e32 v67, 0xbfb8aa3b, v67
	s_cbranch_execz .Ldry_p5b_real
; __device__ __forceinline__ unsigned cvt_pk_bf16(float lo, float hi) { f32x2_t v = {lo, hi}; bf16x2_t b = __builtin_convertvector(v, bf16x2_t); return __builtin_bit_cast(unsigned, b); }
; __device__ __forceinline__ float sigmoidf_(float v) { return __builtin_amdgcn_rcpf(1.f + __expf(-v)); }
;     __device__ __forceinline__ void operator()(const f32x4 (&acc)[2][2][4][2], const pg8::Unit& u, int wr, int wc, int fr, int fq) const {
;     ...
;         if (seg >= 8) {
; #pragma unroll
;             for (int bj = 0; bj < 2; ++bj) {
;                 const int col = (seg - 8) * 1024 + col0 + bj * 128;
;                 const f32x4 b0 = *(const f32x4*)(bgate + col), b1 = *(const f32x4*)(bgate + col + 4);
; #pragma unroll
;                 for (int ai = 0; ai < 2; ++ai)
; #pragma unroll
;                     for (int m = 0; m < 4; ++m) {
;                         f32x4 a = acc[ai][bj][m][0] + b0, b = acc[ai][bj][m][1] + b1;
; #pragma unroll
;                         for (int j = 0; j < 4; ++j) { a[j] = sigmoidf_(a[j]); b[j] = sigmoidf_(b[j]); }
;                         u32x4 w; w.x = cvt_pk_bf16(a[0], a[1]); w.y = cvt_pk_bf16(a[2], a[3]); w.z = cvt_pk_bf16(b[0], b[1]); w.w = cvt_pk_bf16(b[2], b[3]);
;                         *(u32x4*)(gates + (size_t)(row0 + ai * 128 + m * 16) * 2048 + col) = w;
;                     }
;             }
.Ldry_p5b_c4:
	v_exp_f32_e32 v69, v69
	v_exp_f32_e32 v67, v67
	v_add_f32_e32 v68, 1.0, v68
	v_add_f32_e32 v66, 1.0, v66
	v_rcp_f32_e32 v68, v68
	v_rcp_f32_e32 v64, v64
	v_rcp_f32_e32 v71, v66
	v_add_f32_e32 v66, 1.0, v69
	v_add_f32_e32 v67, 1.0, v67
	v_rcp_f32_e32 v65, v65
	v_rcp_f32_e32 v66, v66
	v_rcp_f32_e32 v67, v67
	v_cvt_pk_bf16_f32 v64, v68, v64
	v_add_co_u32_e32 v68, vcc, s91, v140
	v_cvt_pk_bf16_f32 v65, v65, v66
	v_cvt_pk_bf16_f32 v66, v72, v70
	v_cvt_pk_bf16_f32 v67, v71, v67
	v_addc_co_u32_e32 v69, vcc, 0, v141, vcc
	global_store_dwordx4 v[68:69], v[64:67], off
	global_load_dwordx4 v[68:71], v[138:139], off offset:512
	s_nop 0
	global_load_dwordx4 v[64:67], v[138:139], off offset:528
	v_lshl_add_u64 v[78:79], v[140:141], 0, s[86:87]
	v_lshl_add_u64 v[76:77], v[140:141], 0, s[12:13]
	v_lshl_add_u64 v[74:75], v[140:141], 0, s[88:89]
	s_mov_b64 s[12:13], 0xb0000
	v_lshl_add_u64 v[72:73], v[140:141], 0, s[12:13]
	s_waitcnt vmcnt(1)
	v_pk_add_f32 v[60:61], v[60:61], v[68:69]
	s_waitcnt vmcnt(0)
	v_pk_add_f32 v[56:57], v[56:57], v[64:65]
	v_mul_f32_e32 v61, 0xbfb8aa3b, v61
	v_mul_f32_e32 v56, 0xbfb8aa3b, v56
	v_exp_f32_e32 v56, v56
	v_exp_f32_e32 v61, v61
	v_pk_add_f32 v[62:63], v[62:63], v[70:71]
	v_mul_f32_e32 v57, 0xbfb8aa3b, v57
	v_add_f32_e32 v56, 1.0, v56
	v_exp_f32_e32 v57, v57
	v_rcp_f32_e32 v80, v56
	v_add_f32_e32 v56, 1.0, v61
	v_mul_f32_e32 v61, 0xbfb8aa3b, v62
	v_exp_f32_e32 v61, v61
	v_pk_add_f32 v[58:59], v[58:59], v[66:67]
	v_add_f32_e32 v57, 1.0, v57
	v_mul_f32_e32 v58, 0xbfb8aa3b, v58
	v_mul_f32_e32 v60, 0xbfb8aa3b, v60
	v_exp_f32_e32 v58, v58
	v_rcp_f32_e32 v62, v57
	v_add_f32_e32 v57, 1.0, v61
	v_mul_f32_e32 v61, 0xbfb8aa3b, v63
	v_mul_f32_e32 v59, 0xbfb8aa3b, v59
	v_exp_f32_e32 v60, v60
	v_exp_f32_e32 v61, v61
	v_exp_f32_e32 v59, v59
	v_add_f32_e32 v58, 1.0, v58
	v_pk_add_f32 v[48:49], v[48:49], v[64:65]
	v_add_f32_e32 v60, 1.0, v60
	v_rcp_f32_e32 v63, v58
	v_add_f32_e32 v58, 1.0, v61
	v_add_f32_e32 v59, 1.0, v59
	v_pk_add_f32 v[52:53], v[52:53], v[68:69]
	v_mul_f32_e32 v48, 0xbfb8aa3b, v48
	v_rcp_f32_e32 v60, v60
	v_rcp_f32_e32 v56, v56
	v_rcp_f32_e32 v57, v57
	v_rcp_f32_e32 v58, v58
	v_rcp_f32_e32 v59, v59
	v_exp_f32_e32 v48, v48
	v_mul_f32_e32 v53, 0xbfb8aa3b, v53
	v_exp_f32_e32 v53, v53
	v_cvt_pk_bf16_f32 v56, v60, v56
	v_cvt_pk_bf16_f32 v57, v57, v58
	v_cvt_pk_bf16_f32 v58, v80, v62
	v_cvt_pk_bf16_f32 v59, v63, v59
	v_pk_add_f32 v[54:55], v[54:55], v[70:71]
	v_add_f32_e32 v48, 1.0, v48
	v_mul_f32_e32 v49, 0xbfb8aa3b, v49
	global_store_dwordx4 v[140:141], v[56:59], off offset:256
	v_exp_f32_e32 v49, v49
	v_pk_add_f32 v[50:51], v[50:51], v[66:67]
	v_rcp_f32_e32 v56, v48
	v_add_f32_e32 v48, 1.0, v53
	v_mul_f32_e32 v53, 0xbfb8aa3b, v54
	v_exp_f32_e32 v53, v53
	v_add_f32_e32 v49, 1.0, v49
	v_mul_f32_e32 v50, 0xbfb8aa3b, v50
	v_mul_f32_e32 v52, 0xbfb8aa3b, v52
	v_exp_f32_e32 v50, v50
	v_rcp_f32_e32 v54, v49
	s_cbranch_execz .Ldry_p5b_real
.Ldry_p5b_c5:
	v_add_f32_e32 v49, 1.0, v53
	v_mul_f32_e32 v53, 0xbfb8aa3b, v55
	v_mul_f32_e32 v51, 0xbfb8aa3b, v51
	v_exp_f32_e32 v52, v52
	v_exp_f32_e32 v53, v53
	v_exp_f32_e32 v51, v51
	v_add_f32_e32 v50, 1.0, v50
	v_pk_add_f32 v[40:41], v[40:41], v[64:65]
	v_add_f32_e32 v52, 1.0, v52
	v_rcp_f32_e32 v55, v50
	v_add_f32_e32 v50, 1.0, v53
	v_add_f32_e32 v51, 1.0, v51
	v_pk_add_f32 v[44:45], v[44:45], v[68:69]
	v_mul_f32_e32 v40, 0xbfb8aa3b, v40
	v_rcp_f32_e32 v52, v52
	v_rcp_f32_e32 v48, v48
	v_rcp_f32_e32 v49, v49
	v_rcp_f32_e32 v50, v50
	v_rcp_f32_e32 v51, v51
	v_exp_f32_e32 v40, v40
	v_mul_f32_e32 v45, 0xbfb8aa3b, v45
	v_exp_f32_e32 v45, v45
	v_cvt_pk_bf16_f32 v48, v52, v48
	v_cvt_pk_bf16_f32 v49, v49, v50
	v_cvt_pk_bf16_f32 v50, v56, v54
	v_cvt_pk_bf16_f32 v51, v55, v51
	v_pk_add_f32 v[46:47], v[46:47], v[70:71]
	v_add_f32_e32 v40, 1.0, v40
	v_mul_f32_e32 v41, 0xbfb8aa3b, v41
	global_store_dwordx4 v[136:137], v[48:51], off offset:256
	v_exp_f32_e32 v41, v41
	v_pk_add_f32 v[42:43], v[42:43], v[66:67]
	v_rcp_f32_e32 v48, v40
	v_add_f32_e32 v40, 1.0, v45
	v_mul_f32_e32 v45, 0xbfb8aa3b, v46
	v_exp_f32_e32 v45, v45
	v_add_f32_e32 v41, 1.0, v41
	v_mul_f32_e32 v42, 0xbfb8aa3b, v42
	v_mul_f32_e32 v44, 0xbfb8aa3b, v44
	v_exp_f32_e32 v42, v42
	v_rcp_f32_e32 v46, v41
	v_add_f32_e32 v41, 1.0, v45
	v_mul_f32_e32 v45, 0xbfb8aa3b, v47
	v_mul_f32_e32 v43, 0xbfb8aa3b, v43
	v_exp_f32_e32 v44, v44
	v_exp_f32_e32 v45, v45
	v_exp_f32_e32 v43, v43
	v_add_f32_e32 v42, 1.0, v42
	v_pk_add_f32 v[32:33], v[32:33], v[64:65]
	v_add_f32_e32 v44, 1.0, v44
	v_rcp_f32_e32 v47, v42
	v_add_f32_e32 v42, 1.0, v45
	v_add_f32_e32 v43, 1.0, v43
	v_pk_add_f32 v[36:37], v[36:37], v[68:69]
	v_mul_f32_e32 v32, 0xbfb8aa3b, v32
	v_rcp_f32_e32 v44, v44
	v_rcp_f32_e32 v40, v40
	v_rcp_f32_e32 v41, v41
	v_rcp_f32_e32 v42, v42
	v_rcp_f32_e32 v43, v43
	v_exp_f32_e32 v32, v32
	v_mul_f32_e32 v37, 0xbfb8aa3b, v37
	v_exp_f32_e32 v37, v37
	v_cvt_pk_bf16_f32 v40, v44, v40
	v_cvt_pk_bf16_f32 v41, v41, v42
	v_cvt_pk_bf16_f32 v42, v48, v46
	v_cvt_pk_bf16_f32 v43, v47, v43
	v_pk_add_f32 v[38:39], v[38:39], v[70:71]
	v_add_f32_e32 v32, 1.0, v32
	v_mul_f32_e32 v33, 0xbfb8aa3b, v33
	global_store_dwordx4 v[104:105], v[40:43], off offset:256
	v_exp_f32_e32 v33, v33
	v_pk_add_f32 v[34:35], v[34:35], v[66:67]
	v_rcp_f32_e32 v40, v32
	v_add_f32_e32 v32, 1.0, v37
	v_mul_f32_e32 v37, 0xbfb8aa3b, v38
	v_exp_f32_e32 v37, v37
	v_add_f32_e32 v33, 1.0, v33
	v_mul_f32_e32 v34, 0xbfb8aa3b, v34
	v_mul_f32_e32 v36, 0xbfb8aa3b, v36
	v_exp_f32_e32 v34, v34
	v_rcp_f32_e32 v38, v33
	v_add_f32_e32 v33, 1.0, v37
	v_mul_f32_e32 v37, 0xbfb8aa3b, v39
	v_mul_f32_e32 v35, 0xbfb8aa3b, v35
	v_exp_f32_e32 v36, v36
	v_exp_f32_e32 v37, v37
	v_exp_f32_e32 v35, v35
	v_add_f32_e32 v34, 1.0, v34
	s_cbranch_execz .Ldry_p5b_real
; __device__ __forceinline__ unsigned cvt_pk_bf16(float lo, float hi) { f32x2_t v = {lo, hi}; bf16x2_t b = __builtin_convertvector(v, bf16x2_t); return __builtin_bit_cast(unsigned, b); }
; __device__ __forceinline__ float sigmoidf_(float v) { return __builtin_amdgcn_rcpf(1.f + __expf(-v)); }
;     __device__ __forceinline__ void operator()(const f32x4 (&acc)[2][2][4][2], const pg8::Unit& u, int wr, int wc, int fr, int fq) const {
;     ...
;         if (seg >= 8) {
; #pragma unroll
;             for (int bj = 0; bj < 2; ++bj) {
;                 const int col = (seg - 8) * 1024 + col0 + bj * 128;
;                 const f32x4 b0 = *(const f32x4*)(bgate + col), b1 = *(const f32x4*)(bgate + col + 4);
; #pragma unroll
;                 for (int ai = 0; ai < 2; ++ai)
; #pragma unroll
;                     for (int m = 0; m < 4; ++m) {
;                         f32x4 a = acc[ai][bj][m][0] + b0, b = acc[ai][bj][m][1] + b1;
; #pragma unroll
;                         for (int j = 0; j < 4; ++j) { a[j] = sigmoidf_(a[j]); b[j] = sigmoidf_(b[j]); }
;                         u32x4 w; w.x = cvt_pk_bf16(a[0], a[1]); w.y = cvt_pk_bf16(a[2], a[3]); w.z = cvt_pk_bf16(b[0], b[1]); w.w = cvt_pk_bf16(b[2], b[3]);
;                         *(u32x4*)(gates + (size_t)(row0 + ai * 128 + m * 16) * 2048 + col) = w;
;                     }
;             }
.Ldry_p5b_c6:
	v_pk_add_f32 v[24:25], v[24:25], v[64:65]
	v_add_f32_e32 v36, 1.0, v36
	v_rcp_f32_e32 v39, v34
	v_add_f32_e32 v34, 1.0, v37
	v_add_f32_e32 v35, 1.0, v35
	v_pk_add_f32 v[28:29], v[28:29], v[68:69]
	v_mul_f32_e32 v24, 0xbfb8aa3b, v24
	v_rcp_f32_e32 v36, v36
	v_rcp_f32_e32 v32, v32
	v_rcp_f32_e32 v33, v33
	v_rcp_f32_e32 v34, v34
	v_rcp_f32_e32 v35, v35
	v_exp_f32_e32 v24, v24
	v_mul_f32_e32 v29, 0xbfb8aa3b, v29
	v_exp_f32_e32 v29, v29
	v_cvt_pk_bf16_f32 v32, v36, v32
	v_cvt_pk_bf16_f32 v33, v33, v34
	v_cvt_pk_bf16_f32 v34, v40, v38
	v_cvt_pk_bf16_f32 v35, v39, v35
	v_pk_add_f32 v[30:31], v[30:31], v[70:71]
	v_add_f32_e32 v24, 1.0, v24
	v_mul_f32_e32 v25, 0xbfb8aa3b, v25
	global_store_dwordx4 v[96:97], v[32:35], off offset:256
	v_exp_f32_e32 v25, v25
	v_pk_add_f32 v[26:27], v[26:27], v[66:67]
	v_rcp_f32_e32 v32, v24
	v_add_f32_e32 v24, 1.0, v29
	v_mul_f32_e32 v29, 0xbfb8aa3b, v30
	v_exp_f32_e32 v29, v29
	v_add_f32_e32 v25, 1.0, v25
	v_mul_f32_e32 v26, 0xbfb8aa3b, v26
	v_mul_f32_e32 v28, 0xbfb8aa3b, v28
	v_exp_f32_e32 v26, v26
	v_rcp_f32_e32 v30, v25
	v_add_f32_e32 v25, 1.0, v29
	v_mul_f32_e32 v29, 0xbfb8aa3b, v31
	v_mul_f32_e32 v27, 0xbfb8aa3b, v27
	v_exp_f32_e32 v28, v28
	v_exp_f32_e32 v29, v29
	v_exp_f32_e32 v27, v27
	v_add_f32_e32 v26, 1.0, v26
	v_pk_add_f32 v[16:17], v[16:17], v[64:65]
	v_add_f32_e32 v28, 1.0, v28
	v_rcp_f32_e32 v31, v26
	v_add_f32_e32 v26, 1.0, v29
	v_add_f32_e32 v27, 1.0, v27
	v_pk_add_f32 v[20:21], v[20:21], v[68:69]
	v_mul_f32_e32 v16, 0xbfb8aa3b, v16
	v_rcp_f32_e32 v28, v28
	v_rcp_f32_e32 v24, v24
	v_rcp_f32_e32 v25, v25
	v_rcp_f32_e32 v26, v26
	v_rcp_f32_e32 v27, v27
	v_exp_f32_e32 v16, v16
	v_mul_f32_e32 v21, 0xbfb8aa3b, v21
	v_exp_f32_e32 v21, v21
	v_cvt_pk_bf16_f32 v24, v28, v24
	v_cvt_pk_bf16_f32 v25, v25, v26
	v_cvt_pk_bf16_f32 v26, v32, v30
	v_cvt_pk_bf16_f32 v27, v31, v27
	v_pk_add_f32 v[22:23], v[22:23], v[70:71]
	v_add_f32_e32 v16, 1.0, v16
	v_mul_f32_e32 v17, 0xbfb8aa3b, v17
	global_store_dwordx4 v[78:79], v[24:27], off offset:256
	v_exp_f32_e32 v17, v17
	v_pk_add_f32 v[18:19], v[18:19], v[66:67]
	v_rcp_f32_e32 v24, v16
	v_add_f32_e32 v16, 1.0, v21
	v_mul_f32_e32 v21, 0xbfb8aa3b, v22
	v_exp_f32_e32 v21, v21
	v_add_f32_e32 v17, 1.0, v17
	v_mul_f32_e32 v18, 0xbfb8aa3b, v18
	v_mul_f32_e32 v20, 0xbfb8aa3b, v20
	v_exp_f32_e32 v18, v18
	v_rcp_f32_e32 v22, v17
	v_add_f32_e32 v17, 1.0, v21
	v_mul_f32_e32 v21, 0xbfb8aa3b, v23
	v_mul_f32_e32 v19, 0xbfb8aa3b, v19
	v_exp_f32_e32 v20, v20
	v_exp_f32_e32 v21, v21
	v_exp_f32_e32 v19, v19
	v_add_f32_e32 v18, 1.0, v18
	v_pk_add_f32 v[8:9], v[8:9], v[64:65]
	v_add_f32_e32 v20, 1.0, v20
	v_rcp_f32_e32 v23, v18
	v_add_f32_e32 v18, 1.0, v21
	v_add_f32_e32 v19, 1.0, v19
	v_pk_add_f32 v[12:13], v[12:13], v[68:69]
	v_mul_f32_e32 v8, 0xbfb8aa3b, v8
	s_cbranch_execz .Ldry_p5b_real
.Ldry_p5b_c7:
	v_rcp_f32_e32 v20, v20
	v_rcp_f32_e32 v16, v16
	v_rcp_f32_e32 v17, v17
	v_rcp_f32_e32 v18, v18
	v_rcp_f32_e32 v19, v19
	v_exp_f32_e32 v8, v8
	v_mul_f32_e32 v13, 0xbfb8aa3b, v13
	v_exp_f32_e32 v13, v13
	v_cvt_pk_bf16_f32 v16, v20, v16
	v_cvt_pk_bf16_f32 v17, v17, v18
	v_cvt_pk_bf16_f32 v18, v24, v22
	v_cvt_pk_bf16_f32 v19, v23, v19
	v_pk_add_f32 v[14:15], v[14:15], v[70:71]
	v_add_f32_e32 v8, 1.0, v8
	v_mul_f32_e32 v9, 0xbfb8aa3b, v9
	global_store_dwordx4 v[76:77], v[16:19], off offset:256
	v_exp_f32_e32 v9, v9
	v_pk_add_f32 v[10:11], v[10:11], v[66:67]
	v_rcp_f32_e32 v16, v8
	v_add_f32_e32 v8, 1.0, v13
	v_mul_f32_e32 v13, 0xbfb8aa3b, v14
	v_exp_f32_e32 v13, v13
	v_add_f32_e32 v9, 1.0, v9
	v_mul_f32_e32 v10, 0xbfb8aa3b, v10
	v_mul_f32_e32 v12, 0xbfb8aa3b, v12
	v_exp_f32_e32 v10, v10
	v_rcp_f32_e32 v14, v9
	v_add_f32_e32 v9, 1.0, v13
	v_mul_f32_e32 v13, 0xbfb8aa3b, v15
	v_mul_f32_e32 v11, 0xbfb8aa3b, v11
	v_exp_f32_e32 v12, v12
	v_exp_f32_e32 v13, v13
	v_exp_f32_e32 v11, v11
	v_add_f32_e32 v10, 1.0, v10
	v_pk_add_f32 v[0:1], v[0:1], v[64:65]
	v_add_f32_e32 v12, 1.0, v12
	v_rcp_f32_e32 v15, v10
	v_add_f32_e32 v10, 1.0, v13
	v_add_f32_e32 v11, 1.0, v11
	v_pk_add_f32 v[4:5], v[4:5], v[68:69]
	v_mul_f32_e32 v0, 0xbfb8aa3b, v0
	v_rcp_f32_e32 v12, v12
	v_rcp_f32_e32 v8, v8
	v_rcp_f32_e32 v9, v9
	v_rcp_f32_e32 v10, v10
	v_rcp_f32_e32 v11, v11
	v_exp_f32_e32 v0, v0
	v_mul_f32_e32 v5, 0xbfb8aa3b, v5
	v_exp_f32_e32 v5, v5
	v_cvt_pk_bf16_f32 v8, v12, v8
	v_cvt_pk_bf16_f32 v9, v9, v10
	v_cvt_pk_bf16_f32 v10, v16, v14
	v_cvt_pk_bf16_f32 v11, v15, v11
	v_pk_add_f32 v[6:7], v[6:7], v[70:71]
	v_add_f32_e32 v0, 1.0, v0
	v_mul_f32_e32 v1, 0xbfb8aa3b, v1
	global_store_dwordx4 v[74:75], v[8:11], off offset:256
	v_exp_f32_e32 v1, v1
	v_pk_add_f32 v[2:3], v[2:3], v[66:67]
	v_rcp_f32_e32 v8, v0
	v_add_f32_e32 v0, 1.0, v5
	v_mul_f32_e32 v5, 0xbfb8aa3b, v6
	v_exp_f32_e32 v5, v5
	v_add_f32_e32 v1, 1.0, v1
	v_mul_f32_e32 v2, 0xbfb8aa3b, v2
	v_mul_f32_e32 v4, 0xbfb8aa3b, v4
	v_exp_f32_e32 v2, v2
	v_rcp_f32_e32 v6, v1
	v_add_f32_e32 v1, 1.0, v5
	v_mul_f32_e32 v5, 0xbfb8aa3b, v7
	v_mul_f32_e32 v3, 0xbfb8aa3b, v3
	v_exp_f32_e32 v4, v4
	v_exp_f32_e32 v5, v5
	v_exp_f32_e32 v3, v3
	v_add_f32_e32 v2, 1.0, v2
	v_add_f32_e32 v4, 1.0, v4
	v_rcp_f32_e32 v7, v2
	v_add_f32_e32 v2, 1.0, v5
	v_add_f32_e32 v3, 1.0, v3
	v_rcp_f32_e32 v4, v4
	v_rcp_f32_e32 v0, v0
	v_rcp_f32_e32 v1, v1
	v_rcp_f32_e32 v2, v2
	v_rcp_f32_e32 v3, v3
	v_cvt_pk_bf16_f32 v0, v4, v0
	v_cvt_pk_bf16_f32 v1, v1, v2
	v_cvt_pk_bf16_f32 v2, v8, v6
	v_cvt_pk_bf16_f32 v3, v7, v3
	global_store_dwordx4 v[72:73], v[0:3], off offset:256
	s_cbranch_execz .Ldry_p5b_real
	s_andn2_b64 vcc, exec, s[4:5]
	s_mov_b64 s[4:5], -1
	s_cbranch_vccnz .LBB0_516

;     __device__ __forceinline__ void operator()(const f32x4 (&acc)[2][2][4][2], const pg8::Unit& u, int wr, int wc, int fr, int fq) const {
;         const bool second = u.pm >= 64;
;         const int pm = second ? u.pm - 64 : u.pm, pn = second ? u.pn - 4 : u.pn;
;         const int row0 = pm * 256 + wr * 64 + fr, col0 = pn * 256 + wc * 32 + 8 * fq;
; #pragma unroll
;         for (int ai = 0; ai < 2; ++ai)
; #pragma unroll
;         for (int mh = 0; mh < 2; ++mh) {
;             u32x4 gv[2][2], tv[2][2];
; #pragma unroll
;             for (int mm = 0; mm < 2; ++mm)
; #pragma unroll
;                 for (int bj = 0; bj < 2; ++bj) {
;                     const size_t row = (size_t)(row0 + ai * 128 + (2 * mh + mm) * 16); const int col = col0 + bj * 128;
;                     gv[mm][bj] = *(const u32x4*)(gates + row * 2048 + (second ? 1024 : 0) + col);
;                     if (second) tv[mm][bj] = *(const u32x4*)((const bf16_t*)tmp + row * 1024 + col);
.LBB0_612:
	s_mov_b64 s[98:99], s[4:5]
	s_mov_b64 s[100:101], s[24:25]
	v_readfirstlane_b32 s3, v200
	s_nop 0
	s_lshr_b32 s3, s3, 6
	s_cmp_eq_u32 s3, 0
	s_cbranch_scc1 .Ldry_p6_real
	s_mov_b64 exec, 0
	s_cmp_eq_u32 s3, 1
	s_cbranch_scc1 .Ldry_p6_c1
	s_cmp_eq_u32 s3, 2
	s_cbranch_scc1 .Ldry_p6_c2
	s_cmp_eq_u32 s3, 3
	s_cbranch_scc1 .Ldry_p6_c3
	s_cmp_eq_u32 s3, 4
	s_cbranch_scc1 .Ldry_p6_c4
	s_cmp_eq_u32 s3, 5
	s_cbranch_scc1 .Ldry_p6_c5
	s_cmp_eq_u32 s3, 6
	s_cbranch_scc1 .Ldry_p6_c6
	s_branch .Ldry_p6_c7
.Ldry_p6_real:
	s_mov_b64 exec, -1
	s_mov_b64 s[4:5], s[98:99]
	s_mov_b64 s[24:25], s[100:101]
	s_lshl_b32 s3, s4, 8
	s_lshl_b32 s17, s24, 8
	s_add_i32 s5, s3, 0xffffc000
	s_add_i32 s19, s17, 0xfffffc00
	s_cmp_gt_i32 s4, 63
	s_cselect_b64 s[26:27], -1, 0
	s_and_b64 s[24:25], s[26:27], exec
	s_cselect_b32 s3, s5, s3
	s_cselect_b32 s5, s19, s17
	s_cselect_b32 s17, 0x800, 0
	v_add_u32_e32 v178, s3, v186
	s_add_u32 s24, s72, s17
	v_ashrrev_i32_e32 v179, 31, v178
	s_addc_u32 s25, s73, 0
	v_or_b32_e32 v176, s5, v188
	v_lshlrev_b64 v[72:73], 12, v[178:179]
	v_lshl_add_u64 v[72:73], s[24:25], 0, v[72:73]
	v_ashrrev_i32_e32 v177, 31, v176
	v_lshl_add_u64 v[74:75], v[176:177], 1, v[72:73]
	global_load_dwordx4 v[156:159], v[74:75], off
	v_lshlrev_b64 v[182:183], 11, v[178:179]
	v_lshl_add_u64 v[72:73], s[64:65], 0, v[182:183]
	s_cmp_lt_i32 s4, 64
	v_lshl_add_u64 v[72:73], v[176:177], 1, v[72:73]
	s_cbranch_scc1 .LBB0_614
	global_load_dwordx4 v[100:103], v[72:73], off

; __device__ __forceinline__ unsigned cvt_pk_bf16(float lo, float hi) { f32x2_t v = {lo, hi}; bf16x2_t b = __builtin_convertvector(v, bf16x2_t); return __builtin_bit_cast(unsigned, b); }
; __device__ __forceinline__ float bf2f(unsigned u) { return __uint_as_float(u << 16); }
;     __device__ __forceinline__ void operator()(const f32x4 (&acc)[2][2][4][2], const pg8::Unit& u, int wr, int wc, int fr, int fq) const {
;     ...
;             for (int mm = 0; mm < 2; ++mm)
; #pragma unroll
;                 for (int bj = 0; bj < 2; ++bj) {
;                     const int m = 2 * mh + mm;
;                     const size_t row = (size_t)(row0 + ai * 128 + m * 16); const int col = col0 + bj * 128;
;                     const u32x4 gt = gv[mm][bj];
;                     f32x4 a = acc[ai][bj][m][0], b = acc[ai][bj][m][1];
;                     a[0] *= bf2f(gt.x & 0xffffu); a[1] *= bf2f(gt.x >> 16); a[2] *= bf2f(gt.y & 0xffffu); a[3] *= bf2f(gt.y >> 16);
;                     b[0] *= bf2f(gt.z & 0xffffu); b[1] *= bf2f(gt.z >> 16); b[2] *= bf2f(gt.w & 0xffffu); b[3] *= bf2f(gt.w >> 16);
;                     if (!second) { u32x4 w; w.x = cvt_pk_bf16(a[0], a[1]); w.y = cvt_pk_bf16(a[2], a[3]); w.z = cvt_pk_bf16(b[0], b[1]); w.w = cvt_pk_bf16(b[2], b[3]); *(u32x4*)((bf16_t*)tmp + row * 1024 + col) = w; }
;                     else {
;                         { const u32x4 t = tv[mm][bj]; a[0] += bf2f(t.x & 0xffffu); a[1] += bf2f(t.x >> 16); a[2] += bf2f(t.y & 0xffffu); a[3] += bf2f(t.y >> 16);
;                           b[0] += bf2f(t.z & 0xffffu); b[1] += bf2f(t.z >> 16); b[2] += bf2f(t.w & 0xffffu); b[3] += bf2f(t.w >> 16); }
;                         u32x4 w; w.x = cvt_pk_bf16(a[0], a[1]); w.y = cvt_pk_bf16(a[2], a[3]); w.z = cvt_pk_bf16(b[0], b[1]); w.w = cvt_pk_bf16(b[2], b[3]);
;                         *(u32x4*)(Y + row * 1024 + col) = w;
;                     }
.LBB0_623:
	v_cvt_pk_bf16_f32 v140, v140, v141
	v_cvt_pk_bf16_f32 v141, v142, v143
	v_cvt_pk_bf16_f32 v142, v136, v137
	v_lshl_add_u64 v[136:137], s[26:27], 0, v[182:183]
	v_cvt_pk_bf16_f32 v143, v138, v139
	v_lshl_add_u64 v[136:137], v[176:177], 1, v[136:137]
	global_store_dwordx4 v[136:137], v[140:143], off
	v_lshlrev_b32_e32 v136, 16, v152
	v_and_b32_e32 v137, 0xffff0000, v152
	v_pk_mul_f32 v[132:133], v[132:133], v[136:137]
	v_lshlrev_b32_e32 v136, 16, v153
	v_and_b32_e32 v137, 0xffff0000, v153
	v_pk_mul_f32 v[134:135], v[134:135], v[136:137]
	v_lshlrev_b32_e32 v136, 16, v154
	s_cbranch_execz .Ldry_p6_real
.Ldry_p6_c1:
	v_and_b32_e32 v137, 0xffff0000, v154
	v_pk_mul_f32 v[128:129], v[128:129], v[136:137]
	v_lshlrev_b32_e32 v136, 16, v155
	v_and_b32_e32 v137, 0xffff0000, v155
	s_and_b64 vcc, exec, s[4:5]
	v_pk_mul_f32 v[130:131], v[130:131], v[136:137]
	s_cbranch_vccnz .LBB0_625
	v_lshlrev_b32_e32 v136, 16, v96
	v_and_b32_e32 v137, 0xffff0000, v96
	v_pk_add_f32 v[132:133], v[132:133], v[136:137]
	v_lshlrev_b32_e32 v136, 16, v97
	v_and_b32_e32 v137, 0xffff0000, v97
	v_pk_add_f32 v[134:135], v[134:135], v[136:137]
	v_lshlrev_b32_e32 v136, 16, v98
	v_and_b32_e32 v137, 0xffff0000, v98
	v_pk_add_f32 v[128:129], v[128:129], v[136:137]
	v_lshlrev_b32_e32 v136, 16, v99
	v_and_b32_e32 v137, 0xffff0000, v99
	v_pk_add_f32 v[130:131], v[130:131], v[136:137]
	s_mov_b64 s[26:27], s[42:43]
	s_branch .LBB0_626

; __device__ __forceinline__ unsigned cvt_pk_bf16(float lo, float hi) { f32x2_t v = {lo, hi}; bf16x2_t b = __builtin_convertvector(v, bf16x2_t); return __builtin_bit_cast(unsigned, b); }
; __device__ __forceinline__ float bf2f(unsigned u) { return __uint_as_float(u << 16); }
;     __device__ __forceinline__ void operator()(const f32x4 (&acc)[2][2][4][2], const pg8::Unit& u, int wr, int wc, int fr, int fq) const {
;     ...
;             for (int mm = 0; mm < 2; ++mm)
; #pragma unroll
;                 for (int bj = 0; bj < 2; ++bj) {
;                     const int m = 2 * mh + mm;
;                     const size_t row = (size_t)(row0 + ai * 128 + m * 16); const int col = col0 + bj * 128;
;                     const u32x4 gt = gv[mm][bj];
;                     f32x4 a = acc[ai][bj][m][0], b = acc[ai][bj][m][1];
;                     a[0] *= bf2f(gt.x & 0xffffu); a[1] *= bf2f(gt.x >> 16); a[2] *= bf2f(gt.y & 0xffffu); a[3] *= bf2f(gt.y >> 16);
;                     b[0] *= bf2f(gt.z & 0xffffu); b[1] *= bf2f(gt.z >> 16); b[2] *= bf2f(gt.w & 0xffffu); b[3] *= bf2f(gt.w >> 16);
;                     if (!second) { u32x4 w; w.x = cvt_pk_bf16(a[0], a[1]); w.y = cvt_pk_bf16(a[2], a[3]); w.z = cvt_pk_bf16(b[0], b[1]); w.w = cvt_pk_bf16(b[2], b[3]); *(u32x4*)((bf16_t*)tmp + row * 1024 + col) = w; }
;                     else {
;                         { const u32x4 t = tv[mm][bj]; a[0] += bf2f(t.x & 0xffffu); a[1] += bf2f(t.x >> 16); a[2] += bf2f(t.y & 0xffffu); a[3] += bf2f(t.y >> 16);
;                           b[0] += bf2f(t.z & 0xffffu); b[1] += bf2f(t.z >> 16); b[2] += bf2f(t.w & 0xffffu); b[3] += bf2f(t.w >> 16); }
;                         u32x4 w; w.x = cvt_pk_bf16(a[0], a[1]); w.y = cvt_pk_bf16(a[2], a[3]); w.z = cvt_pk_bf16(b[0], b[1]); w.w = cvt_pk_bf16(b[2], b[3]);
;                         *(u32x4*)(Y + row * 1024 + col) = w;
;                     }
.LBB0_629:
	v_cvt_pk_bf16_f32 v124, v124, v125
	v_cvt_pk_bf16_f32 v125, v126, v127
	v_cvt_pk_bf16_f32 v126, v120, v121
	v_lshl_add_u64 v[120:121], s[26:27], 0, v[180:181]
	v_cvt_pk_bf16_f32 v127, v122, v123
	v_lshl_add_u64 v[120:121], v[176:177], 1, v[120:121]
	global_store_dwordx4 v[120:121], v[124:127], off
	v_lshlrev_b32_e32 v120, 16, v144
	v_and_b32_e32 v121, 0xffff0000, v144
	v_pk_mul_f32 v[116:117], v[116:117], v[120:121]
	v_lshlrev_b32_e32 v120, 16, v145
	v_and_b32_e32 v121, 0xffff0000, v145
	v_pk_mul_f32 v[118:119], v[118:119], v[120:121]
	v_lshlrev_b32_e32 v120, 16, v146
	v_and_b32_e32 v121, 0xffff0000, v146
	v_pk_mul_f32 v[112:113], v[112:113], v[120:121]
	v_lshlrev_b32_e32 v120, 16, v147
	v_and_b32_e32 v121, 0xffff0000, v147
	s_and_b64 vcc, exec, s[4:5]
	v_pk_mul_f32 v[114:115], v[114:115], v[120:121]
	s_cbranch_vccnz .LBB0_631
	v_lshlrev_b32_e32 v120, 16, v72
	v_and_b32_e32 v121, 0xffff0000, v72
	v_pk_add_f32 v[116:117], v[116:117], v[120:121]
	v_lshlrev_b32_e32 v120, 16, v73
	v_and_b32_e32 v121, 0xffff0000, v73
	v_pk_add_f32 v[118:119], v[118:119], v[120:121]
	v_lshlrev_b32_e32 v120, 16, v74
	v_and_b32_e32 v121, 0xffff0000, v74
	v_pk_add_f32 v[112:113], v[112:113], v[120:121]
	v_lshlrev_b32_e32 v120, 16, v75
	v_and_b32_e32 v121, 0xffff0000, v75
	v_pk_add_f32 v[114:115], v[114:115], v[120:121]
	s_mov_b64 s[26:27], s[42:43]
	s_branch .LBB0_632
.LBB0_631:
	s_cbranch_execz .Ldry_p6_real
.Ldry_p6_c2:
	s_mov_b64 s[26:27], s[64:65]

; __device__ __forceinline__ unsigned cvt_pk_bf16(float lo, float hi) { f32x2_t v = {lo, hi}; bf16x2_t b = __builtin_convertvector(v, bf16x2_t); return __builtin_bit_cast(unsigned, b); }
; __device__ __forceinline__ float bf2f(unsigned u) { return __uint_as_float(u << 16); }
;     __device__ __forceinline__ void operator()(const f32x4 (&acc)[2][2][4][2], const pg8::Unit& u, int wr, int wc, int fr, int fq) const {
;     ...
;             for (int mm = 0; mm < 2; ++mm)
; #pragma unroll
;                 for (int bj = 0; bj < 2; ++bj) {
;                     const int m = 2 * mh + mm;
;                     const size_t row = (size_t)(row0 + ai * 128 + m * 16); const int col = col0 + bj * 128;
;                     const u32x4 gt = gv[mm][bj];
;                     f32x4 a = acc[ai][bj][m][0], b = acc[ai][bj][m][1];
;                     a[0] *= bf2f(gt.x & 0xffffu); a[1] *= bf2f(gt.x >> 16); a[2] *= bf2f(gt.y & 0xffffu); a[3] *= bf2f(gt.y >> 16);
;                     b[0] *= bf2f(gt.z & 0xffffu); b[1] *= bf2f(gt.z >> 16); b[2] *= bf2f(gt.w & 0xffffu); b[3] *= bf2f(gt.w >> 16);
;                     if (!second) { u32x4 w; w.x = cvt_pk_bf16(a[0], a[1]); w.y = cvt_pk_bf16(a[2], a[3]); w.z = cvt_pk_bf16(b[0], b[1]); w.w = cvt_pk_bf16(b[2], b[3]); *(u32x4*)((bf16_t*)tmp + row * 1024 + col) = w; }
;                     else {
;                         { const u32x4 t = tv[mm][bj]; a[0] += bf2f(t.x & 0xffffu); a[1] += bf2f(t.x >> 16); a[2] += bf2f(t.y & 0xffffu); a[3] += bf2f(t.y >> 16);
;                           b[0] += bf2f(t.z & 0xffffu); b[1] += bf2f(t.z >> 16); b[2] += bf2f(t.w & 0xffffu); b[3] += bf2f(t.w >> 16); }
;                         u32x4 w; w.x = cvt_pk_bf16(a[0], a[1]); w.y = cvt_pk_bf16(a[2], a[3]); w.z = cvt_pk_bf16(b[0], b[1]); w.w = cvt_pk_bf16(b[2], b[3]);
;                         *(u32x4*)(Y + row * 1024 + col) = w;
;                     }
.LBB0_643:
	v_cvt_pk_bf16_f32 v108, v108, v109
	v_cvt_pk_bf16_f32 v109, v110, v111
	v_cvt_pk_bf16_f32 v110, v104, v105
	v_lshl_add_u64 v[104:105], s[26:27], 0, v[132:133]
	v_cvt_pk_bf16_f32 v111, v106, v107
	v_lshl_add_u64 v[104:105], v[176:177], 1, v[104:105]
	global_store_dwordx4 v[104:105], v[108:111], off
	s_waitcnt vmcnt(3)
	v_lshlrev_b32_e32 v104, 16, v120
	v_and_b32_e32 v105, 0xffff0000, v120
	v_pk_mul_f32 v[92:93], v[92:93], v[104:105]
	v_lshlrev_b32_e32 v104, 16, v121
	v_and_b32_e32 v105, 0xffff0000, v121
	v_pk_mul_f32 v[94:95], v[94:95], v[104:105]
	v_lshlrev_b32_e32 v104, 16, v122
	v_and_b32_e32 v105, 0xffff0000, v122
	v_pk_mul_f32 v[88:89], v[88:89], v[104:105]
	v_lshlrev_b32_e32 v104, 16, v123
	v_and_b32_e32 v105, 0xffff0000, v123
	s_and_b64 vcc, exec, s[4:5]
	s_cbranch_execz .Ldry_p6_real
.Ldry_p6_c3:
	v_pk_mul_f32 v[90:91], v[90:91], v[104:105]
	s_cbranch_vccnz .LBB0_645
	v_lshlrev_b32_e32 v104, 16, v96
	v_and_b32_e32 v105, 0xffff0000, v96
	v_pk_add_f32 v[92:93], v[92:93], v[104:105]
	v_lshlrev_b32_e32 v104, 16, v97
	v_and_b32_e32 v105, 0xffff0000, v97
	v_pk_add_f32 v[94:95], v[94:95], v[104:105]
	v_lshlrev_b32_e32 v104, 16, v98
	v_and_b32_e32 v105, 0xffff0000, v98
	v_pk_add_f32 v[88:89], v[88:89], v[104:105]
	v_lshlrev_b32_e32 v104, 16, v99
	v_and_b32_e32 v105, 0xffff0000, v99
	v_pk_add_f32 v[90:91], v[90:91], v[104:105]
	s_mov_b64 s[26:27], s[42:43]
	s_branch .LBB0_646

; __device__ __forceinline__ unsigned cvt_pk_bf16(float lo, float hi) { f32x2_t v = {lo, hi}; bf16x2_t b = __builtin_convertvector(v, bf16x2_t); return __builtin_bit_cast(unsigned, b); }
;     __device__ __forceinline__ void operator()(const f32x4 (&acc)[2][2][4][2], const pg8::Unit& u, int wr, int wc, int fr, int fq) const {
;     ...
;             u32x4 gv[2][2], tv[2][2];
; #pragma unroll
;             for (int mm = 0; mm < 2; ++mm)
; #pragma unroll
;                 for (int bj = 0; bj < 2; ++bj) {
;                     const size_t row = (size_t)(row0 + ai * 128 + (2 * mh + mm) * 16); const int col = col0 + bj * 128;
;                     gv[mm][bj] = *(const u32x4*)(gates + row * 2048 + (second ? 1024 : 0) + col);
;                     if (second) tv[mm][bj] = *(const u32x4*)((const bf16_t*)tmp + row * 1024 + col);
;                 }
; #pragma unroll
;             for (int mm = 0; mm < 2; ++mm)
; #pragma unroll
;                 for (int bj = 0; bj < 2; ++bj) {
;                     const int m = 2 * mh + mm;
;                     const size_t row = (size_t)(row0 + ai * 128 + m * 16); const int col = col0 + bj * 128;
;                     const u32x4 gt = gv[mm][bj];
;                     f32x4 a = acc[ai][bj][m][0], b = acc[ai][bj][m][1];
;                     a[0] *= bf2f(gt.x & 0xffffu); a[1] *= bf2f(gt.x >> 16); a[2] *= bf2f(gt.y & 0xffffu); a[3] *= bf2f(gt.y >> 16);
;                     b[0] *= bf2f(gt.z & 0xffffu); b[1] *= bf2f(gt.z >> 16); b[2] *= bf2f(gt.w & 0xffffu); b[3] *= bf2f(gt.w >> 16);
;                     if (!second) { u32x4 w; w.x = cvt_pk_bf16(a[0], a[1]); w.y = cvt_pk_bf16(a[2], a[3]); w.z = cvt_pk_bf16(b[0], b[1]); w.w = cvt_pk_bf16(b[2], b[3]); *(u32x4*)((bf16_t*)tmp + row * 1024 + col) = w; }
;                     else {
;                         { const u32x4 t = tv[mm][bj]; a[0] += bf2f(t.x & 0xffffu); a[1] += bf2f(t.x >> 16); a[2] += bf2f(t.y & 0xffffu); a[3] += bf2f(t.y >> 16);
;                           b[0] += bf2f(t.z & 0xffffu); b[1] += bf2f(t.z >> 16); b[2] += bf2f(t.w & 0xffffu); b[3] += bf2f(t.w >> 16); }
;                         u32x4 w; w.x = cvt_pk_bf16(a[0], a[1]); w.y = cvt_pk_bf16(a[2], a[3]); w.z = cvt_pk_bf16(b[0], b[1]); w.w = cvt_pk_bf16(b[2], b[3]);
;                         *(u32x4*)(Y + row * 1024 + col) = w;
;                     }
.LBB0_652:
	v_cvt_pk_bf16_f32 v68, v68, v69
	v_cvt_pk_bf16_f32 v69, v70, v71
	s_cbranch_execz .Ldry_p6_real
.Ldry_p6_c4:
	v_cvt_pk_bf16_f32 v70, v64, v65
	v_lshl_add_u64 v[64:65], s[26:27], 0, v[130:131]
	v_cvt_pk_bf16_f32 v71, v66, v67
	v_lshl_add_u64 v[64:65], v[64:65], 0, v[128:129]
	global_store_dwordx4 v[64:65], v[68:71], off offset:256
	v_add_u32_e32 v64, 0x80, v178
	v_ashrrev_i32_e32 v65, 31, v64
	v_lshlrev_b64 v[66:67], 12, v[64:65]
	v_lshl_add_u64 v[66:67], s[24:25], 0, v[66:67]
	v_lshl_add_u64 v[66:67], v[66:67], 0, v[128:129]
	global_load_dwordx4 v[80:83], v[66:67], off
	v_lshlrev_b64 v[90:91], 11, v[64:65]
	v_lshl_add_u64 v[64:65], s[64:65], 0, v[90:91]
	s_and_b64 vcc, exec, s[4:5]
	v_lshl_add_u64 v[64:65], v[176:177], 1, v[64:65]
	s_cbranch_vccnz .LBB0_654
	global_load_dwordx4 v[100:103], v[64:65], off

; __device__ __forceinline__ unsigned cvt_pk_bf16(float lo, float hi) { f32x2_t v = {lo, hi}; bf16x2_t b = __builtin_convertvector(v, bf16x2_t); return __builtin_bit_cast(unsigned, b); }
; __device__ __forceinline__ float bf2f(unsigned u) { return __uint_as_float(u << 16); }
;     __device__ __forceinline__ void operator()(const f32x4 (&acc)[2][2][4][2], const pg8::Unit& u, int wr, int wc, int fr, int fq) const {
;     ...
;             for (int mm = 0; mm < 2; ++mm)
; #pragma unroll
;                 for (int bj = 0; bj < 2; ++bj) {
;                     const int m = 2 * mh + mm;
;                     const size_t row = (size_t)(row0 + ai * 128 + m * 16); const int col = col0 + bj * 128;
;                     const u32x4 gt = gv[mm][bj];
;                     f32x4 a = acc[ai][bj][m][0], b = acc[ai][bj][m][1];
;                     a[0] *= bf2f(gt.x & 0xffffu); a[1] *= bf2f(gt.x >> 16); a[2] *= bf2f(gt.y & 0xffffu); a[3] *= bf2f(gt.y >> 16);
;                     b[0] *= bf2f(gt.z & 0xffffu); b[1] *= bf2f(gt.z >> 16); b[2] *= bf2f(gt.w & 0xffffu); b[3] *= bf2f(gt.w >> 16);
;                     if (!second) { u32x4 w; w.x = cvt_pk_bf16(a[0], a[1]); w.y = cvt_pk_bf16(a[2], a[3]); w.z = cvt_pk_bf16(b[0], b[1]); w.w = cvt_pk_bf16(b[2], b[3]); *(u32x4*)((bf16_t*)tmp + row * 1024 + col) = w; }
;                     else {
;                         { const u32x4 t = tv[mm][bj]; a[0] += bf2f(t.x & 0xffffu); a[1] += bf2f(t.x >> 16); a[2] += bf2f(t.y & 0xffffu); a[3] += bf2f(t.y >> 16);
;                           b[0] += bf2f(t.z & 0xffffu); b[1] += bf2f(t.z >> 16); b[2] += bf2f(t.w & 0xffffu); b[3] += bf2f(t.w >> 16); }
;                         u32x4 w; w.x = cvt_pk_bf16(a[0], a[1]); w.y = cvt_pk_bf16(a[2], a[3]); w.z = cvt_pk_bf16(b[0], b[1]); w.w = cvt_pk_bf16(b[2], b[3]);
;                         *(u32x4*)(Y + row * 1024 + col) = w;
;                     }
.LBB0_663:
	v_cvt_pk_bf16_f32 v60, v60, v61
	v_cvt_pk_bf16_f32 v61, v62, v63
	v_cvt_pk_bf16_f32 v62, v56, v57
	v_lshl_add_u64 v[56:57], s[26:27], 0, v[90:91]
	v_cvt_pk_bf16_f32 v63, v58, v59
	v_lshl_add_u64 v[56:57], v[176:177], 1, v[56:57]
	global_store_dwordx4 v[56:57], v[60:63], off
	s_waitcnt vmcnt(3)
	v_lshlrev_b32_e32 v56, 16, v76
	v_and_b32_e32 v57, 0xffff0000, v76
	v_pk_mul_f32 v[52:53], v[52:53], v[56:57]
	v_lshlrev_b32_e32 v56, 16, v77
	v_and_b32_e32 v57, 0xffff0000, v77
	v_pk_mul_f32 v[54:55], v[54:55], v[56:57]
	v_lshlrev_b32_e32 v56, 16, v78
	v_and_b32_e32 v57, 0xffff0000, v78
	v_pk_mul_f32 v[48:49], v[48:49], v[56:57]
	v_lshlrev_b32_e32 v56, 16, v79
	v_and_b32_e32 v57, 0xffff0000, v79
	s_and_b64 vcc, exec, s[4:5]
	v_pk_mul_f32 v[50:51], v[50:51], v[56:57]
	s_cbranch_vccnz .LBB0_665
	v_lshlrev_b32_e32 v56, 16, v96
	v_and_b32_e32 v57, 0xffff0000, v96
	s_cbranch_execz .Ldry_p6_real
.Ldry_p6_c5:
	v_pk_add_f32 v[52:53], v[52:53], v[56:57]
	v_lshlrev_b32_e32 v56, 16, v97
	v_and_b32_e32 v57, 0xffff0000, v97
	v_pk_add_f32 v[54:55], v[54:55], v[56:57]
	v_lshlrev_b32_e32 v56, 16, v98
	v_and_b32_e32 v57, 0xffff0000, v98
	v_pk_add_f32 v[48:49], v[48:49], v[56:57]
	v_lshlrev_b32_e32 v56, 16, v99
	v_and_b32_e32 v57, 0xffff0000, v99
	v_pk_add_f32 v[50:51], v[50:51], v[56:57]
	s_mov_b64 s[26:27], s[42:43]
	s_branch .LBB0_666

; __device__ __forceinline__ unsigned cvt_pk_bf16(float lo, float hi) { f32x2_t v = {lo, hi}; bf16x2_t b = __builtin_convertvector(v, bf16x2_t); return __builtin_bit_cast(unsigned, b); }
;     __device__ __forceinline__ void operator()(const f32x4 (&acc)[2][2][4][2], const pg8::Unit& u, int wr, int wc, int fr, int fq) const {
;     ...
;             u32x4 gv[2][2], tv[2][2];
; #pragma unroll
;             for (int mm = 0; mm < 2; ++mm)
; #pragma unroll
;                 for (int bj = 0; bj < 2; ++bj) {
;                     const size_t row = (size_t)(row0 + ai * 128 + (2 * mh + mm) * 16); const int col = col0 + bj * 128;
;                     gv[mm][bj] = *(const u32x4*)(gates + row * 2048 + (second ? 1024 : 0) + col);
;                     if (second) tv[mm][bj] = *(const u32x4*)((const bf16_t*)tmp + row * 1024 + col);
;                 }
; #pragma unroll
;             for (int mm = 0; mm < 2; ++mm)
; #pragma unroll
;                 for (int bj = 0; bj < 2; ++bj) {
;                     const int m = 2 * mh + mm;
;                     const size_t row = (size_t)(row0 + ai * 128 + m * 16); const int col = col0 + bj * 128;
;                     const u32x4 gt = gv[mm][bj];
;                     f32x4 a = acc[ai][bj][m][0], b = acc[ai][bj][m][1];
;                     a[0] *= bf2f(gt.x & 0xffffu); a[1] *= bf2f(gt.x >> 16); a[2] *= bf2f(gt.y & 0xffffu); a[3] *= bf2f(gt.y >> 16);
;                     b[0] *= bf2f(gt.z & 0xffffu); b[1] *= bf2f(gt.z >> 16); b[2] *= bf2f(gt.w & 0xffffu); b[3] *= bf2f(gt.w >> 16);
;                     if (!second) { u32x4 w; w.x = cvt_pk_bf16(a[0], a[1]); w.y = cvt_pk_bf16(a[2], a[3]); w.z = cvt_pk_bf16(b[0], b[1]); w.w = cvt_pk_bf16(b[2], b[3]); *(u32x4*)((bf16_t*)tmp + row * 1024 + col) = w; }
;                     else {
;                         { const u32x4 t = tv[mm][bj]; a[0] += bf2f(t.x & 0xffffu); a[1] += bf2f(t.x >> 16); a[2] += bf2f(t.y & 0xffffu); a[3] += bf2f(t.y >> 16);
;                           b[0] += bf2f(t.z & 0xffffu); b[1] += bf2f(t.z >> 16); b[2] += bf2f(t.w & 0xffffu); b[3] += bf2f(t.w >> 16); }
;                         u32x4 w; w.x = cvt_pk_bf16(a[0], a[1]); w.y = cvt_pk_bf16(a[2], a[3]); w.z = cvt_pk_bf16(b[0], b[1]); w.w = cvt_pk_bf16(b[2], b[3]);
;                         *(u32x4*)(Y + row * 1024 + col) = w;
;                     }
.LBB0_672:
	v_cvt_pk_bf16_f32 v36, v36, v37
	v_cvt_pk_bf16_f32 v37, v38, v39
	v_cvt_pk_bf16_f32 v38, v32, v33
	v_lshl_add_u64 v[32:33], s[26:27], 0, v[88:89]
	v_cvt_pk_bf16_f32 v39, v34, v35
	s_cbranch_execz .Ldry_p6_real
.Ldry_p6_c6:
	v_lshl_add_u64 v[32:33], v[32:33], 0, v[128:129]
	global_store_dwordx4 v[32:33], v[36:39], off offset:256
	v_add_u32_e32 v32, 0xa0, v178
	v_ashrrev_i32_e32 v33, 31, v32
	v_lshlrev_b64 v[34:35], 12, v[32:33]
	v_lshl_add_u64 v[34:35], s[24:25], 0, v[34:35]
	v_lshl_add_u64 v[34:35], v[34:35], 0, v[128:129]
	global_load_dwordx4 v[44:47], v[34:35], off
	v_lshlrev_b64 v[50:51], 11, v[32:33]
	v_lshl_add_u64 v[32:33], s[64:65], 0, v[50:51]
	s_and_b64 vcc, exec, s[4:5]
	v_lshl_add_u64 v[32:33], v[176:177], 1, v[32:33]
	s_cbranch_vccnz .LBB0_674
	global_load_dwordx4 v[100:103], v[32:33], off

; __device__ __forceinline__ unsigned cvt_pk_bf16(float lo, float hi) { f32x2_t v = {lo, hi}; bf16x2_t b = __builtin_convertvector(v, bf16x2_t); return __builtin_bit_cast(unsigned, b); }
; __device__ __forceinline__ float bf2f(unsigned u) { return __uint_as_float(u << 16); }
;     __device__ __forceinline__ void operator()(const f32x4 (&acc)[2][2][4][2], const pg8::Unit& u, int wr, int wc, int fr, int fq) const {
;     ...
;             for (int mm = 0; mm < 2; ++mm)
; #pragma unroll
;                 for (int bj = 0; bj < 2; ++bj) {
;                     const int m = 2 * mh + mm;
;                     const size_t row = (size_t)(row0 + ai * 128 + m * 16); const int col = col0 + bj * 128;
;                     const u32x4 gt = gv[mm][bj];
;                     f32x4 a = acc[ai][bj][m][0], b = acc[ai][bj][m][1];
;                     a[0] *= bf2f(gt.x & 0xffffu); a[1] *= bf2f(gt.x >> 16); a[2] *= bf2f(gt.y & 0xffffu); a[3] *= bf2f(gt.y >> 16);
;                     b[0] *= bf2f(gt.z & 0xffffu); b[1] *= bf2f(gt.z >> 16); b[2] *= bf2f(gt.w & 0xffffu); b[3] *= bf2f(gt.w >> 16);
;                     if (!second) { u32x4 w; w.x = cvt_pk_bf16(a[0], a[1]); w.y = cvt_pk_bf16(a[2], a[3]); w.z = cvt_pk_bf16(b[0], b[1]); w.w = cvt_pk_bf16(b[2], b[3]); *(u32x4*)((bf16_t*)tmp + row * 1024 + col) = w; }
;                     else {
;                         { const u32x4 t = tv[mm][bj]; a[0] += bf2f(t.x & 0xffffu); a[1] += bf2f(t.x >> 16); a[2] += bf2f(t.y & 0xffffu); a[3] += bf2f(t.y >> 16);
;                           b[0] += bf2f(t.z & 0xffffu); b[1] += bf2f(t.z >> 16); b[2] += bf2f(t.w & 0xffffu); b[3] += bf2f(t.w >> 16); }
;                         u32x4 w; w.x = cvt_pk_bf16(a[0], a[1]); w.y = cvt_pk_bf16(a[2], a[3]); w.z = cvt_pk_bf16(b[0], b[1]); w.w = cvt_pk_bf16(b[2], b[3]);
;                         *(u32x4*)(Y + row * 1024 + col) = w;
;                     }
.LBB0_683:
	v_cvt_pk_bf16_f32 v28, v28, v29
	v_cvt_pk_bf16_f32 v29, v30, v31
	v_cvt_pk_bf16_f32 v30, v24, v25
	v_lshl_add_u64 v[24:25], s[24:25], 0, v[50:51]
	v_cvt_pk_bf16_f32 v31, v26, v27
	v_lshl_add_u64 v[24:25], v[176:177], 1, v[24:25]
	global_store_dwordx4 v[24:25], v[28:31], off
	s_waitcnt vmcnt(3)
	v_lshlrev_b32_e32 v24, 16, v40
	v_and_b32_e32 v25, 0xffff0000, v40
	v_pk_mul_f32 v[20:21], v[20:21], v[24:25]
	v_lshlrev_b32_e32 v24, 16, v41
	v_and_b32_e32 v25, 0xffff0000, v41
	v_pk_mul_f32 v[22:23], v[22:23], v[24:25]
	v_lshlrev_b32_e32 v24, 16, v42
	v_and_b32_e32 v25, 0xffff0000, v42
	v_pk_mul_f32 v[16:17], v[16:17], v[24:25]
	v_lshlrev_b32_e32 v24, 16, v43
	v_and_b32_e32 v25, 0xffff0000, v43
	s_and_b64 vcc, exec, s[4:5]
	v_pk_mul_f32 v[18:19], v[18:19], v[24:25]
	s_cbranch_vccnz .LBB0_685
	v_lshlrev_b32_e32 v24, 16, v96
	v_and_b32_e32 v25, 0xffff0000, v96
	v_pk_add_f32 v[20:21], v[20:21], v[24:25]
	v_lshlrev_b32_e32 v24, 16, v97
	v_and_b32_e32 v25, 0xffff0000, v97
	v_pk_add_f32 v[22:23], v[22:23], v[24:25]
	s_cbranch_execz .Ldry_p6_real
.Ldry_p6_c7:
	v_lshlrev_b32_e32 v24, 16, v98
	v_and_b32_e32 v25, 0xffff0000, v98
	v_pk_add_f32 v[16:17], v[16:17], v[24:25]
	v_lshlrev_b32_e32 v24, 16, v99
	v_and_b32_e32 v25, 0xffff0000, v99
	v_pk_add_f32 v[18:19], v[18:19], v[24:25]
	s_mov_b64 s[24:25], s[42:43]
	s_branch .LBB0_686

; __device__ __forceinline__ unsigned cvt_pk_bf16(float lo, float hi) { f32x2_t v = {lo, hi}; bf16x2_t b = __builtin_convertvector(v, bf16x2_t); return __builtin_bit_cast(unsigned, b); }
; #define PG8_BAR __builtin_amdgcn_s_barrier()
; template <class Epi, class Sched, bool ALIGN_EPI = false, bool SP2 = false>
; __device__ __forceinline__ void gemm_phase(LAS unsigned char* lds, const Gemm g, const Sched& S, const Epi& E) {
;     ...
;         if constexpr (!Epi::AFTER_DRAIN) { E(acc, cur, wr, wc, fr, fq); S.done(cur); }
;         if (!has_next) break;
; #pragma unroll
;         for (int a = 0; a < 2; ++a)
; #pragma unroll
;             for (int b = 0; b < 2; ++b)
; #pragma unroll
;                 for (int m = 0; m < 4; ++m)
; #pragma unroll
;                     for (int n = 0; n < 2; ++n) acc[a][b][m][n] = (f32x4){0.f, 0.f, 0.f, 0.f};
;         cur = nxt; cA = nA; cB = nB; ++ui;
;         if constexpr (ALIGN_EPI) { if (wr == 1) PG8_BAR; }
;     __device__ __forceinline__ void operator()(const f32x4 (&acc)[2][2][4][2], const pg8::Unit& u, int wr, int wc, int fr, int fq) const {
;     ...
;                         u32x4 w; w.x = cvt_pk_bf16(a[0], a[1]); w.y = cvt_pk_bf16(a[2], a[3]); w.z = cvt_pk_bf16(b[0], b[1]); w.w = cvt_pk_bf16(b[2], b[3]);
;                         *(u32x4*)(Y + row * 1024 + col) = w;
.LBB0_692:
	v_cvt_pk_bf16_f32 v4, v4, v5
	v_cvt_pk_bf16_f32 v5, v6, v7
	v_cvt_pk_bf16_f32 v6, v0, v1
	v_lshl_add_u64 v[0:1], s[4:5], 0, v[48:49]
	v_cvt_pk_bf16_f32 v7, v2, v3
	v_lshl_add_u64 v[0:1], v[176:177], 1, v[0:1]
	s_andn2_b64 vcc, exec, s[6:7]
	s_mov_b64 s[4:5], -1
	global_store_dwordx4 v[0:1], v[4:7], off offset:256
	s_cbranch_execz .Ldry_p6_real
	s_cbranch_vccnz .LBB0_601
	s_andn2_b64 vcc, exec, s[10:11]
	s_cbranch_vccnz .LBB0_600
	s_barrier
	s_branch .LBB0_600

; #define LAS __attribute__((address_space(3)))
; #define PG8_WAIT_V(n) asm volatile("s_waitcnt vmcnt(" #n ")" ::: "memory")
; #define PG8_BAR __builtin_amdgcn_s_barrier()
; template <class Epi, class Sched, bool ALIGN_EPI = false, bool SP2 = false>
; __device__ __forceinline__ void gemm_phase(LAS unsigned char* lds, const Gemm g, const Sched& S, const Epi& E) {
;     ...
;     PG8_WAIT_V(0);
;     if constexpr (!ALIGN_EPI) { if (wr == 0) PG8_BAR; }
;     PG8_BAR;
;     __device__ __forceinline__ void fused(f32x4 (&acc)[2][2][4][2], const pg8::Unit& u, int wr, int wc, int fr, int fq, LAS unsigned char* lds, int wid, int lane) const {
;         const int tid = threadIdx.x;
;         const int row0 = u.pm * 256 + wr * 64 + fr, col0 = u.pn * 256 + wc * 32 + 8 * fq;
;         LAS float* P = (LAS float*)lds;
;         LAS float* Sr = (LAS float*)(lds + 4096);
; #pragma unroll
;         for (int ai = 0; ai < 2; ++ai) {
;             f32x4 xa[4][2], xc[4][2];
; #pragma unroll
;             for (int m = 0; m < 4; ++m)
; #pragma unroll
;                 for (int bj = 0; bj < 2; ++bj) {
;                     const size_t off = (size_t)(row0 + ai * 128 + m * 16) * 1024 + col0 + bj * 128;
;                     xa[m][bj] = *(const f32x4*)(x + off); xc[m][bj] = *(const f32x4*)(x + off + 4);
;                 }
; #pragma unroll
;             for (int m = 0; m < 4; ++m) {
;                 float ss = 0.f;
; #pragma unroll
;                 for (int bj = 0; bj < 2; ++bj) {
;                     const f32x4 a = acc[ai][bj][m][0] + xa[m][bj], b = acc[ai][bj][m][1] + xc[m][bj];
;                     acc[ai][bj][m][0] = a; acc[ai][bj][m][1] = b;
;                     ss += (a[0] * a[0] + a[1] * a[1]) + (a[2] * a[2] + a[3] * a[3]) + (b[0] * b[0] + b[1] * b[1]) + (b[2] * b[2] + b[3] * b[3]);
;                 }
;                 ss += __shfl_xor(ss, 16); ss += __shfl_xor(ss, 32);
;                 if (fq == 0) P[(ai * 128 + wr * 64 + m * 16 + fr) * 4 + wc] = ss;
;             }
;         }
.LBB0_775:
	s_lshl_b32 s3, s8, 8
	s_add_i32 s3, s3, s9
	s_lshl_b32 s2, s1, 5
	v_or_b32_e32 v196, s3, v201
	s_lshl_b32 s3, s0, 8
	s_or_b32 s2, s3, s2
	v_lshl_or_b32 v188, v203, 3, s2
	v_readlane_b32 s12, v250, 1
	v_ashrrev_i32_e32 v189, 31, v188
	v_readlane_b32 s13, v250, 2
	v_ashrrev_i32_e32 v197, 31, v196
	v_lshlrev_b64 v[192:193], 12, v[196:197]
	v_lshl_add_u64 v[198:199], v[188:189], 2, s[12:13]
	v_lshl_add_u64 v[128:129], v[198:199], 0, v[192:193]
	s_waitcnt vmcnt(0)
	s_barrier
	s_mov_b64 s[100:101], s[0:1]
	v_readfirstlane_b32 s98, v200
	s_nop 0
	s_lshr_b32 s98, s98, 6
	s_cmp_eq_u32 s98, 0
	s_cbranch_scc1 .Ldry_p7a_real
	s_mov_b64 exec, 0
	s_cmp_eq_u32 s98, 1
	s_cbranch_scc1 .Ldry_p7a_c1
	s_cmp_eq_u32 s98, 2
	s_cbranch_scc1 .Ldry_p7a_c2
	s_cmp_eq_u32 s98, 3
	s_cbranch_scc1 .Ldry_p7a_c3
	s_cmp_eq_u32 s98, 4
	s_cbranch_scc1 .Ldry_p7a_c4
	s_cmp_eq_u32 s98, 5
	s_cbranch_scc1 .Ldry_p7a_c5
	s_cmp_eq_u32 s98, 6
	s_cbranch_scc1 .Ldry_p7a_c6
	s_branch .Ldry_p7a_c7
.Ldry_p7a_real:
	s_mov_b64 exec, -1
	s_mov_b64 s[0:1], s[100:101]
	global_load_dwordx4 v[180:183], v[128:129], off
	global_load_dwordx4 v[206:209], v[128:129], off offset:16
	global_load_dwordx4 v[210:213], v[128:129], off offset:512
	global_load_dwordx4 v[214:217], v[128:129], off offset:528
	v_or_b32_e32 v128, 16, v196
	v_or_b32_e32 v130, 32, v196
	v_or_b32_e32 v132, 48, v196
	v_ashrrev_i32_e32 v129, 31, v128
	v_ashrrev_i32_e32 v131, 31, v130
	v_ashrrev_i32_e32 v133, 31, v132
	v_lshlrev_b64 v[194:195], 12, v[128:129]
	v_lshlrev_b64 v[190:191], 12, v[130:131]
	v_lshlrev_b64 v[186:187], 12, v[132:133]
	v_lshl_add_u64 v[128:129], v[198:199], 0, v[194:195]
	v_lshl_add_u64 v[130:131], v[198:199], 0, v[190:191]
	v_lshl_add_u64 v[132:133], v[198:199], 0, v[186:187]
	global_load_dwordx4 v[168:171], v[128:129], off offset:16
	global_load_dwordx4 v[172:175], v[128:129], off
	global_load_dwordx4 v[160:163], v[128:129], off offset:528
	global_load_dwordx4 v[164:167], v[128:129], off offset:512
	global_load_dwordx4 v[152:155], v[130:131], off offset:16
	global_load_dwordx4 v[156:159], v[130:131], off
	global_load_dwordx4 v[144:147], v[130:131], off offset:528
	global_load_dwordx4 v[148:151], v[130:131], off offset:512
	global_load_dwordx4 v[136:139], v[132:133], off offset:16
	global_load_dwordx4 v[140:143], v[132:133], off
	s_nop 0
	global_load_dwordx4 v[128:131], v[132:133], off offset:528
	s_nop 0
	global_load_dwordx4 v[132:135], v[132:133], off offset:512
	v_mbcnt_lo_u32_b32 v178, -1, 0
	v_mbcnt_hi_u32_b32 v205, -1, v178
	v_and_b32_e32 v179, 64, v205
	v_xor_b32_e32 v178, 16, v205
	v_add_u32_e32 v218, 64, v179
	v_cmp_lt_i32_e32 vcc, v178, v218
	s_lshl_b32 s1, s1, 2
	s_add_i32 s1, s1, 0
	v_cndmask_b32_e32 v178, v205, v178, vcc
	v_lshlrev_b32_e32 v204, 2, v178
	v_lshl_add_u32 v202, v202, 4, s1
	v_readlane_b32 s14, v250, 3
	v_readlane_b32 s15, v250, 4
	v_readlane_b32 s16, v250, 5
	v_readlane_b32 s17, v250, 6
	v_readlane_b32 s18, v250, 7
	v_readlane_b32 s19, v250, 8
	v_readlane_b32 s20, v250, 9
	v_readlane_b32 s21, v250, 10
	v_readlane_b32 s22, v250, 11
	v_readlane_b32 s23, v250, 12
	v_readlane_b32 s24, v250, 13
	v_readlane_b32 s25, v250, 14
	v_readlane_b32 s26, v250, 15
	s_cbranch_execz .Ldry_p7a_real
.Ldry_p7a_c1:
	v_readlane_b32 s27, v250, 16
	s_waitcnt vmcnt(0)
	v_pk_add_f32 v[178:179], v[126:127], v[182:183]
	v_pk_add_f32 v[180:181], v[124:125], v[180:181]
	v_pk_add_f32 v[118:119], v[118:119], v[212:213]
	v_pk_add_f32 v[116:117], v[116:117], v[210:211]
	v_pk_add_f32 v[184:185], v[120:121], v[206:207]
	v_pk_add_f32 v[112:113], v[112:113], v[214:215]
	v_mul_f32_e32 v120, v181, v181
	v_mul_f32_e32 v121, v179, v179
	v_mul_f32_e32 v124, v117, v117
	v_mul_f32_e32 v125, v119, v119
	v_pk_add_f32 v[182:183], v[122:123], v[208:209]
	v_pk_add_f32 v[114:115], v[114:115], v[216:217]
	v_mul_f32_e32 v122, v185, v185
	v_mul_f32_e32 v126, v113, v113
	v_fmac_f32_e32 v120, v180, v180
	v_fmac_f32_e32 v121, v178, v178
	v_fmac_f32_e32 v124, v116, v116
	v_fmac_f32_e32 v125, v118, v118
	v_mul_f32_e32 v123, v183, v183
	v_mul_f32_e32 v127, v115, v115
	v_fmac_f32_e32 v122, v184, v184
	v_fmac_f32_e32 v126, v112, v112
	v_add_f32_e32 v120, v120, v121
	v_add_f32_e32 v121, v124, v125
	v_fmac_f32_e32 v123, v182, v182
	v_fmac_f32_e32 v127, v114, v114
	v_add_f32_e32 v120, v120, v122
	v_add_f32_e32 v121, v121, v126
	v_add_f32_e32 v120, v123, v120
	v_add_f32_e32 v121, v127, v121
	v_add_f32_e32 v120, v120, v121
	ds_bpermute_b32 v121, v204, v120
	v_xor_b32_e32 v122, 32, v205
	v_cmp_lt_i32_e32 vcc, v122, v218
	s_waitcnt lgkmcnt(0)
	v_add_f32_e32 v120, v120, v121
	v_cndmask_b32_e32 v122, v205, v122, vcc
	v_lshlrev_b32_e32 v205, 2, v122
	ds_bpermute_b32 v121, v205, v120
	v_cmp_eq_u32_e32 vcc, 0, v203
	s_and_saveexec_b64 s[2:3], vcc
	s_cbranch_execz .LBB0_777
	s_waitcnt lgkmcnt(0)
	v_add_f32_e32 v120, v120, v121
	ds_write_b32 v202, v120
.LBB0_777:
	s_or_b64 exec, exec, s[2:3]
	v_pk_add_f32 v[174:175], v[110:111], v[174:175]
	v_pk_add_f32 v[172:173], v[108:109], v[172:173]
	v_pk_add_f32 v[124:125], v[102:103], v[166:167]
	v_pk_add_f32 v[126:127], v[100:101], v[164:165]
	v_pk_add_f32 v[168:169], v[104:105], v[168:169]
	v_mul_f32_e32 v104, v173, v173
	v_mul_f32_e32 v105, v175, v175
	s_cbranch_execz .Ldry_p7a_real
;     __device__ __forceinline__ void fused(f32x4 (&acc)[2][2][4][2], const pg8::Unit& u, int wr, int wc, int fr, int fq, LAS unsigned char* lds, int wid, int lane) const {
;     ...
;             for (int m = 0; m < 4; ++m) {
;                 float ss = 0.f;
; #pragma unroll
;                 for (int bj = 0; bj < 2; ++bj) {
;                     const f32x4 a = acc[ai][bj][m][0] + xa[m][bj], b = acc[ai][bj][m][1] + xc[m][bj];
;                     acc[ai][bj][m][0] = a; acc[ai][bj][m][1] = b;
;                     ss += (a[0] * a[0] + a[1] * a[1]) + (a[2] * a[2] + a[3] * a[3]) + (b[0] * b[0] + b[1] * b[1]) + (b[2] * b[2] + b[3] * b[3]);
;                 }
;                 ss += __shfl_xor(ss, 16); ss += __shfl_xor(ss, 32);
;                 if (fq == 0) P[(ai * 128 + wr * 64 + m * 16 + fr) * 4 + wc] = ss;
;             }
.Ldry_p7a_c2:
	v_pk_add_f32 v[122:123], v[96:97], v[160:161]
	v_mul_f32_e32 v96, v127, v127
	v_mul_f32_e32 v97, v125, v125
	v_fmac_f32_e32 v104, v172, v172
	v_fmac_f32_e32 v105, v174, v174
	v_fmac_f32_e32 v96, v126, v126
	v_fmac_f32_e32 v97, v124, v124
	v_add_f32_e32 v104, v104, v105
	v_mul_f32_e32 v105, v169, v169
	v_add_f32_e32 v96, v96, v97
	v_mul_f32_e32 v97, v123, v123
	v_pk_add_f32 v[170:171], v[106:107], v[170:171]
	v_fmac_f32_e32 v105, v168, v168
	s_waitcnt lgkmcnt(0)
	v_pk_add_f32 v[120:121], v[98:99], v[162:163]
	v_fmac_f32_e32 v97, v122, v122
	v_add_f32_e32 v104, v104, v105
	v_mul_f32_e32 v105, v171, v171
	v_add_f32_e32 v96, v96, v97
	v_mul_f32_e32 v97, v121, v121
	v_fmac_f32_e32 v105, v170, v170
	v_fmac_f32_e32 v97, v120, v120
	v_add_f32_e32 v104, v105, v104
	v_add_f32_e32 v96, v97, v96
	v_add_f32_e32 v96, v104, v96
	ds_bpermute_b32 v97, v204, v96
	s_waitcnt lgkmcnt(0)
	v_add_f32_e32 v96, v96, v97
	ds_bpermute_b32 v97, v205, v96
	s_and_saveexec_b64 s[2:3], vcc
	s_cbranch_execz .LBB0_779
	s_waitcnt lgkmcnt(0)
	v_add_f32_e32 v96, v96, v97
	ds_write_b32 v202, v96 offset:256
.LBB0_779:
	s_or_b64 exec, exec, s[2:3]
	v_pk_add_f32 v[158:159], v[94:95], v[158:159]
	v_pk_add_f32 v[156:157], v[92:93], v[156:157]
	v_pk_add_f32 v[150:151], v[86:87], v[150:151]
	v_pk_add_f32 v[148:149], v[84:85], v[148:149]
	v_pk_add_f32 v[152:153], v[88:89], v[152:153]
	v_mul_f32_e32 v88, v157, v157
	v_mul_f32_e32 v89, v159, v159
	v_pk_add_f32 v[144:145], v[76:77], v[144:145]
	v_mul_f32_e32 v76, v149, v149
	v_mul_f32_e32 v77, v151, v151
	v_fmac_f32_e32 v88, v156, v156
	v_fmac_f32_e32 v89, v158, v158
	v_fmac_f32_e32 v76, v148, v148
	v_fmac_f32_e32 v77, v150, v150
	v_add_f32_e32 v88, v88, v89
	v_mul_f32_e32 v89, v153, v153
	v_add_f32_e32 v76, v76, v77
	v_mul_f32_e32 v77, v145, v145
	v_pk_add_f32 v[154:155], v[90:91], v[154:155]
	s_cbranch_execz .Ldry_p7a_real
.Ldry_p7a_c3:
	v_fmac_f32_e32 v89, v152, v152
	v_pk_add_f32 v[146:147], v[78:79], v[146:147]
	v_fmac_f32_e32 v77, v144, v144
	v_add_f32_e32 v88, v88, v89
	v_mul_f32_e32 v89, v155, v155
	v_add_f32_e32 v76, v76, v77
	v_mul_f32_e32 v77, v147, v147
	v_fmac_f32_e32 v89, v154, v154
	v_fmac_f32_e32 v77, v146, v146
	v_add_f32_e32 v88, v89, v88
	v_add_f32_e32 v76, v77, v76
	v_add_f32_e32 v76, v88, v76
	ds_bpermute_b32 v77, v204, v76
	s_waitcnt lgkmcnt(0)
	v_add_f32_e32 v76, v76, v77
	ds_bpermute_b32 v77, v205, v76
	s_and_saveexec_b64 s[2:3], vcc
	s_cbranch_execz .LBB0_781
	s_waitcnt lgkmcnt(0)
	v_add_f32_e32 v76, v76, v77
	ds_write_b32 v202, v76 offset:512
.LBB0_781:
	s_or_b64 exec, exec, s[2:3]
	v_pk_add_f32 v[142:143], v[82:83], v[142:143]
	v_pk_add_f32 v[140:141], v[80:81], v[140:141]
	v_pk_add_f32 v[134:135], v[70:71], v[134:135]
	v_pk_add_f32 v[132:133], v[68:69], v[132:133]
	v_pk_add_f32 v[160:161], v[72:73], v[136:137]
	v_mul_f32_e32 v72, v141, v141
	v_mul_f32_e32 v73, v143, v143
	v_pk_add_f32 v[128:129], v[64:65], v[128:129]
	v_mul_f32_e32 v64, v133, v133
	v_mul_f32_e32 v65, v135, v135
	v_fmac_f32_e32 v72, v140, v140
	v_fmac_f32_e32 v73, v142, v142
	v_fmac_f32_e32 v64, v132, v132
	v_fmac_f32_e32 v65, v134, v134
	v_add_f32_e32 v72, v72, v73
	v_mul_f32_e32 v73, v161, v161
	v_add_f32_e32 v64, v64, v65
	v_mul_f32_e32 v65, v129, v129
	v_pk_add_f32 v[138:139], v[74:75], v[138:139]
	v_fmac_f32_e32 v73, v160, v160
	v_pk_add_f32 v[130:131], v[66:67], v[130:131]
	v_fmac_f32_e32 v65, v128, v128
	v_add_f32_e32 v72, v72, v73
	v_mul_f32_e32 v73, v139, v139
	v_add_f32_e32 v64, v64, v65
	v_mul_f32_e32 v65, v131, v131
	v_fmac_f32_e32 v73, v138, v138
	v_fmac_f32_e32 v65, v130, v130
	v_add_f32_e32 v72, v73, v72
	v_add_f32_e32 v64, v65, v64
	v_add_f32_e32 v64, v72, v64
	ds_bpermute_b32 v65, v204, v64
	s_waitcnt lgkmcnt(0)
	s_cbranch_execz .Ldry_p7a_real
.Ldry_p7a_c4:
	v_add_f32_e32 v64, v64, v65
	ds_bpermute_b32 v65, v205, v64
	s_and_saveexec_b64 s[2:3], vcc
	s_cbranch_execz .LBB0_783
	s_waitcnt lgkmcnt(0)
	v_add_f32_e32 v64, v64, v65
	ds_write_b32 v202, v64 offset:768
;     __device__ __forceinline__ void fused(f32x4 (&acc)[2][2][4][2], const pg8::Unit& u, int wr, int wc, int fr, int fq, LAS unsigned char* lds, int wid, int lane) const {
;     ...
;         for (int ai = 0; ai < 2; ++ai) {
;             f32x4 xa[4][2], xc[4][2];
; #pragma unroll
;             for (int m = 0; m < 4; ++m)
; #pragma unroll
;                 for (int bj = 0; bj < 2; ++bj) {
;                     const size_t off = (size_t)(row0 + ai * 128 + m * 16) * 1024 + col0 + bj * 128;
;                     xa[m][bj] = *(const f32x4*)(x + off); xc[m][bj] = *(const f32x4*)(x + off + 4);
;                 }
; #pragma unroll
;             for (int m = 0; m < 4; ++m) {
;                 float ss = 0.f;
; #pragma unroll
;                 for (int bj = 0; bj < 2; ++bj) {
;                     const f32x4 a = acc[ai][bj][m][0] + xa[m][bj], b = acc[ai][bj][m][1] + xc[m][bj];
;                     acc[ai][bj][m][0] = a; acc[ai][bj][m][1] = b;
;                     ss += (a[0] * a[0] + a[1] * a[1]) + (a[2] * a[2] + a[3] * a[3]) + (b[0] * b[0] + b[1] * b[1]) + (b[2] * b[2] + b[3] * b[3]);
;                 }
;                 ss += __shfl_xor(ss, 16); ss += __shfl_xor(ss, 32);
;                 if (fq == 0) P[(ai * 128 + wr * 64 + m * 16 + fr) * 4 + wc] = ss;
;             }
.LBB0_783:
	s_or_b64 exec, exec, s[2:3]
	s_waitcnt lgkmcnt(0)
	v_lshlrev_b64 v[64:65], 12, v[196:197]
	s_mov_b64 s[2:3], 0x80000
	v_lshl_add_u64 v[166:167], v[64:65], 0, s[2:3]
	v_lshl_add_u64 v[66:67], v[198:199], 0, v[166:167]
	global_load_dwordx4 v[206:209], v[66:67], off
	global_load_dwordx4 v[210:213], v[66:67], off offset:16
	global_load_dwordx4 v[214:217], v[66:67], off offset:512
	global_load_dwordx4 v[218:221], v[66:67], off offset:528
	s_mov_b64 s[2:3], 0x90000
	s_mov_b64 s[4:5], 0xa0000
	s_mov_b64 s[6:7], 0xb0000
	v_lshl_add_u64 v[164:165], v[64:65], 0, s[2:3]
	v_lshl_add_u64 v[162:163], v[64:65], 0, s[4:5]
	v_lshl_add_u64 v[136:137], v[64:65], 0, s[6:7]
	v_lshl_add_u64 v[64:65], v[198:199], 0, v[164:165]
	v_lshl_add_u64 v[66:67], v[198:199], 0, v[162:163]
	v_lshl_add_u64 v[68:69], v[198:199], 0, v[136:137]
	global_load_dwordx4 v[104:107], v[64:65], off offset:16
	global_load_dwordx4 v[108:111], v[64:65], off
	global_load_dwordx4 v[96:99], v[64:65], off offset:528
	global_load_dwordx4 v[100:103], v[64:65], off offset:512
	global_load_dwordx4 v[88:91], v[66:67], off offset:16
	global_load_dwordx4 v[92:95], v[66:67], off
	global_load_dwordx4 v[80:83], v[66:67], off offset:528
	global_load_dwordx4 v[84:87], v[66:67], off offset:512
	global_load_dwordx4 v[72:75], v[68:69], off offset:16
	global_load_dwordx4 v[76:79], v[68:69], off
	s_nop 0
	global_load_dwordx4 v[64:67], v[68:69], off offset:528
	s_nop 0
	global_load_dwordx4 v[68:71], v[68:69], off offset:512
	s_waitcnt vmcnt(15)
	v_pk_add_f32 v[62:63], v[62:63], v[208:209]
	v_pk_add_f32 v[60:61], v[60:61], v[206:207]
	s_waitcnt vmcnt(13)
	v_pk_add_f32 v[54:55], v[54:55], v[216:217]
	v_pk_add_f32 v[52:53], v[52:53], v[214:215]
	v_pk_add_f32 v[56:57], v[56:57], v[210:211]
	s_waitcnt vmcnt(12)
	v_pk_add_f32 v[48:49], v[48:49], v[218:219]
	v_mul_f32_e32 v196, v61, v61
	v_mul_f32_e32 v197, v63, v63
	v_mul_f32_e32 v203, v53, v53
	v_mul_f32_e32 v206, v55, v55
	v_pk_add_f32 v[58:59], v[58:59], v[212:213]
	s_cbranch_execz .Ldry_p7a_real
.Ldry_p7a_c5:
	v_pk_add_f32 v[50:51], v[50:51], v[220:221]
	v_mul_f32_e32 v198, v57, v57
	v_mul_f32_e32 v207, v49, v49
	v_fmac_f32_e32 v196, v60, v60
	v_fmac_f32_e32 v197, v62, v62
	v_fmac_f32_e32 v203, v52, v52
	v_fmac_f32_e32 v206, v54, v54
	v_mul_f32_e32 v199, v59, v59
	v_mul_f32_e32 v208, v51, v51
	v_fmac_f32_e32 v198, v56, v56
	v_fmac_f32_e32 v207, v48, v48
	v_add_f32_e32 v196, v196, v197
	v_add_f32_e32 v197, v203, v206
	v_fmac_f32_e32 v199, v58, v58
	v_fmac_f32_e32 v208, v50, v50
	v_add_f32_e32 v196, v196, v198
	v_add_f32_e32 v197, v197, v207
	v_add_f32_e32 v196, v199, v196
	v_add_f32_e32 v197, v208, v197
	v_add_f32_e32 v196, v196, v197
	ds_bpermute_b32 v197, v204, v196
	s_waitcnt lgkmcnt(0)
	v_add_f32_e32 v196, v196, v197
	ds_bpermute_b32 v197, v205, v196
	s_and_saveexec_b64 s[2:3], vcc
	s_cbranch_execz .LBB0_785
	s_waitcnt lgkmcnt(0)
	v_add_f32_e32 v196, v196, v197
	ds_write_b32 v202, v196 offset:2048
.LBB0_785:
	s_or_b64 exec, exec, s[2:3]
	s_waitcnt vmcnt(10)
	v_pk_add_f32 v[46:47], v[46:47], v[110:111]
	v_pk_add_f32 v[44:45], v[44:45], v[108:109]
	s_waitcnt vmcnt(8)
	v_pk_add_f32 v[38:39], v[38:39], v[102:103]
	v_pk_add_f32 v[36:37], v[36:37], v[100:101]
	v_pk_add_f32 v[40:41], v[40:41], v[104:105]
	v_mul_f32_e32 v104, v45, v45
	v_mul_f32_e32 v105, v47, v47
	v_pk_add_f32 v[32:33], v[32:33], v[96:97]
	v_mul_f32_e32 v96, v37, v37
	v_mul_f32_e32 v97, v39, v39
	v_fmac_f32_e32 v104, v44, v44
	v_fmac_f32_e32 v105, v46, v46
	v_fmac_f32_e32 v96, v36, v36
	v_fmac_f32_e32 v97, v38, v38
	v_add_f32_e32 v104, v104, v105
	v_mul_f32_e32 v105, v41, v41
	v_add_f32_e32 v96, v96, v97
	v_mul_f32_e32 v97, v33, v33
	v_pk_add_f32 v[42:43], v[42:43], v[106:107]
	v_fmac_f32_e32 v105, v40, v40
	v_pk_add_f32 v[34:35], v[34:35], v[98:99]
	v_fmac_f32_e32 v97, v32, v32
	s_cbranch_execz .Ldry_p7a_real
.Ldry_p7a_c6:
	v_add_f32_e32 v104, v104, v105
	v_mul_f32_e32 v105, v43, v43
	v_add_f32_e32 v96, v96, v97
	v_mul_f32_e32 v97, v35, v35
	v_fmac_f32_e32 v105, v42, v42
	v_fmac_f32_e32 v97, v34, v34
	v_add_f32_e32 v104, v105, v104
	v_add_f32_e32 v96, v97, v96
	v_add_f32_e32 v96, v104, v96
	ds_bpermute_b32 v97, v204, v96
	s_waitcnt lgkmcnt(0)
	v_add_f32_e32 v96, v96, v97
	ds_bpermute_b32 v97, v205, v96
	s_and_saveexec_b64 s[2:3], vcc
	s_cbranch_execz .LBB0_787
	s_waitcnt lgkmcnt(0)
	v_add_f32_e32 v96, v96, v97
	ds_write_b32 v202, v96 offset:2304
.LBB0_787:
	s_or_b64 exec, exec, s[2:3]
	s_waitcnt vmcnt(6)
	v_pk_add_f32 v[30:31], v[30:31], v[94:95]
	v_pk_add_f32 v[28:29], v[28:29], v[92:93]
	s_waitcnt vmcnt(4)
	v_pk_add_f32 v[22:23], v[22:23], v[86:87]
	v_pk_add_f32 v[20:21], v[20:21], v[84:85]
	v_pk_add_f32 v[24:25], v[24:25], v[88:89]
	v_mul_f32_e32 v88, v29, v29
	v_mul_f32_e32 v89, v31, v31
	v_pk_add_f32 v[12:13], v[12:13], v[80:81]
	v_mul_f32_e32 v80, v21, v21
	v_mul_f32_e32 v81, v23, v23
	v_fmac_f32_e32 v88, v28, v28
	v_fmac_f32_e32 v89, v30, v30
	v_fmac_f32_e32 v80, v20, v20
	v_fmac_f32_e32 v81, v22, v22
	v_add_f32_e32 v88, v88, v89
	v_mul_f32_e32 v89, v25, v25
	v_add_f32_e32 v80, v80, v81
	v_mul_f32_e32 v81, v13, v13
	v_pk_add_f32 v[26:27], v[26:27], v[90:91]
	v_fmac_f32_e32 v89, v24, v24
	v_pk_add_f32 v[14:15], v[14:15], v[82:83]
	v_fmac_f32_e32 v81, v12, v12
	v_add_f32_e32 v88, v88, v89
	v_mul_f32_e32 v89, v27, v27
	v_add_f32_e32 v80, v80, v81
	v_mul_f32_e32 v81, v15, v15
	v_fmac_f32_e32 v89, v26, v26
	v_fmac_f32_e32 v81, v14, v14
	v_add_f32_e32 v88, v89, v88
	v_add_f32_e32 v80, v81, v80
	v_add_f32_e32 v80, v88, v80
	ds_bpermute_b32 v81, v204, v80
	s_waitcnt lgkmcnt(0)
	v_add_f32_e32 v80, v80, v81
	s_cbranch_execz .Ldry_p7a_real
.Ldry_p7a_c7:
	ds_bpermute_b32 v81, v205, v80
	s_and_saveexec_b64 s[2:3], vcc
	s_cbranch_execz .LBB0_789
	s_waitcnt lgkmcnt(0)
	v_add_f32_e32 v80, v80, v81
	ds_write_b32 v202, v80 offset:2560

;     __device__ __forceinline__ void fused(f32x4 (&acc)[2][2][4][2], const pg8::Unit& u, int wr, int wc, int fr, int fq, LAS unsigned char* lds, int wid, int lane) const {
;     ...
;         __syncthreads();
;         if (tid < 256) {
;             const float t = (P[tid * 4] + P[tid * 4 + 1]) + (P[tid * 4 + 2] + P[tid * 4 + 3]);
;             __hip_atomic_store(xb + ((size_t)(u.pm * 4 + u.pn)) * 256 + tid, t, __ATOMIC_RELAXED, __HIP_MEMORY_SCOPE_AGENT);
;         }
.LBB0_791:
	s_or_b64 exec, exec, s[2:3]
	s_add_u32 s4, s66, 0x20000
	s_movk_i32 s1, 0x100
	s_addc_u32 s5, s67, 0
	v_cmp_gt_u32_e64 s[2:3], s1, v200
	s_cbranch_execz .Ldry_p7a_real
	s_waitcnt lgkmcnt(0)
	s_barrier
	s_and_saveexec_b64 s[6:7], s[2:3]
	s_cbranch_execz .LBB0_793
	v_add_u32_e32 v0, 0, v177
	ds_read_b128 v[0:3], v0
	s_lshl_b32 s1, s8, 2
	s_add_i32 s0, s1, s0
	s_ashr_i32 s1, s0, 31
	s_lshl_b64 s[0:1], s[0:1], 10
	s_waitcnt lgkmcnt(0)
	v_mov_b32_e32 v4, v1
	v_mov_b32_e32 v5, v2
	v_mov_b32_e32 v1, v3
	v_pk_add_f32 v[0:1], v[4:5], v[0:1]
	s_add_u32 s0, s4, s0
	v_pk_add_f32 v[0:1], v[0:1], v[0:1] op_sel:[0,1] op_sel_hi:[1,0]
	s_addc_u32 s1, s5, s1
	global_store_dword v176, v0, s[0:1] sc1

;     __device__ __forceinline__ void fused(f32x4 (&acc)[2][2][4][2], const pg8::Unit& u, int wr, int wc, int fr, int fq, LAS unsigned char* lds, int wid, int lane) const {
;     ...
; #pragma unroll
;         for (int bj = 0; bj < 2; ++bj) {
;             const f32x4 g0 = *(const f32x4*)(fng + col0 + bj * 128), g1 = *(const f32x4*)(fng + col0 + bj * 128 + 4);
; #pragma unroll
;             for (int ai = 0; ai < 2; ++ai)
; #pragma unroll
;                 for (int m = 0; m < 4; ++m) {
;                     const float rstd = Sr[ai * 128 + wr * 64 + m * 16 + fr];
;                     const size_t off = (size_t)(row0 + ai * 128 + m * 16) * 1024 + col0 + bj * 128;
;                     *(f32x4*)(out + off) = acc[ai][bj][m][0] * rstd * g0; *(f32x4*)(out + off + 4) = acc[ai][bj][m][1] * rstd * g1;
;                 }
;         }
.LBB0_807:
	s_or_b64 exec, exec, s[0:1]
	v_lshlrev_b64 v[86:87], 2, v[188:189]
	v_lshl_add_u64 v[82:83], s[62:63], 0, v[86:87]
	s_waitcnt lgkmcnt(0)
	s_barrier
	v_readfirstlane_b32 s98, v200
	s_nop 0
	s_lshr_b32 s98, s98, 6
	s_cmp_eq_u32 s98, 0
	s_cbranch_scc1 .Ldry_p7b_real
	s_mov_b64 exec, 0
	s_cmp_eq_u32 s98, 1
	s_cbranch_scc1 .Ldry_p7b_c1
	s_cmp_eq_u32 s98, 2
	s_cbranch_scc1 .Ldry_p7b_c2
	s_cmp_eq_u32 s98, 3
	s_cbranch_scc1 .Ldry_p7b_c3
	s_cmp_eq_u32 s98, 4
	s_cbranch_scc1 .Ldry_p7b_c4
	s_cmp_eq_u32 s98, 5
	s_cbranch_scc1 .Ldry_p7b_c5
	s_cmp_eq_u32 s98, 6
	s_cbranch_scc1 .Ldry_p7b_c6
	s_branch .Ldry_p7b_c7
.Ldry_p7b_real:
	s_mov_b64 exec, -1
	global_load_dwordx4 v[4:7], v[82:83], off
	global_load_dwordx4 v[0:3], v[82:83], off offset:16
	s_lshl_b32 s0, s9, 2
	v_lshl_add_u64 v[66:67], s[64:65], 0, v[194:195]
	v_lshl_add_u64 v[84:85], s[64:65], 0, v[186:187]
	s_add_i32 s0, s0, 0
	v_lshl_add_u64 v[64:65], s[64:65], 0, v[192:193]
	v_lshl_add_u64 v[88:89], s[64:65], 0, v[166:167]
	v_lshl_add_u64 v[70:71], v[66:67], 0, v[86:87]
	v_lshl_add_u64 v[66:67], v[84:85], 0, v[86:87]
	v_lshl_add_u32 v84, v201, 2, s0
	v_lshl_add_u64 v[80:81], v[64:65], 0, v[86:87]
	v_lshl_add_u64 v[64:65], v[88:89], 0, v[86:87]
	v_add_u32_e32 v89, 0x1000, v84
	ds_read_b32 v88, v84 offset:4096
	ds_read2_b32 v[110:111], v89 offset1:16
	ds_read2_b32 v[176:177], v89 offset0:16 offset1:32
	ds_read2_b32 v[186:187], v89 offset0:32 offset1:48
	ds_read2_b32 v[84:85], v89 offset0:128 offset1:144
	v_lshl_add_u64 v[68:69], s[64:65], 0, v[190:191]
	s_waitcnt lgkmcnt(3)
	v_mov_b32_e32 v98, v111
	s_waitcnt lgkmcnt(2)
	v_mov_b32_e32 v100, v177
	v_pk_mul_f32 v[90:91], v[178:179], v[88:89] op_sel_hi:[1,0]
	v_pk_mul_f32 v[92:93], v[180:181], v[88:89] op_sel_hi:[1,0]
	s_cbranch_execz .Ldry_p7b_real
.Ldry_p7b_c1:
	v_pk_mul_f32 v[94:95], v[182:183], v[88:89] op_sel_hi:[1,0]
	v_pk_mul_f32 v[96:97], v[184:185], v[88:89] op_sel_hi:[1,0]
	s_waitcnt lgkmcnt(1)
	v_mov_b32_e32 v88, v187
	s_waitcnt lgkmcnt(0)
	v_pk_mul_f32 v[180:181], v[56:57], v[84:85] op_sel_hi:[1,0]
	v_mov_b32_e32 v56, v85
	v_pk_mul_f32 v[62:63], v[62:63], v[84:85] op_sel_hi:[1,0]
	v_pk_mul_f32 v[166:167], v[60:61], v[84:85] op_sel_hi:[1,0]
	v_pk_mul_f32 v[178:179], v[58:59], v[84:85] op_sel_hi:[1,0]
	v_pk_mul_f32 v[102:103], v[174:175], v[98:99] op_sel_hi:[1,0]
	v_pk_mul_f32 v[104:105], v[172:173], v[98:99] op_sel_hi:[1,0]
	v_pk_mul_f32 v[106:107], v[170:171], v[98:99] op_sel_hi:[1,0]
	v_pk_mul_f32 v[98:99], v[168:169], v[98:99] op_sel_hi:[1,0]
	v_pk_mul_f32 v[108:109], v[158:159], v[100:101] op_sel_hi:[1,0]
	v_pk_mul_f32 v[156:157], v[156:157], v[100:101] op_sel_hi:[1,0]
	v_pk_mul_f32 v[154:155], v[154:155], v[100:101] op_sel_hi:[1,0]
	v_pk_mul_f32 v[152:153], v[152:153], v[100:101] op_sel_hi:[1,0]
	v_pk_mul_f32 v[142:143], v[142:143], v[88:89] op_sel_hi:[1,0]
	v_pk_mul_f32 v[140:141], v[140:141], v[88:89] op_sel_hi:[1,0]
	v_pk_mul_f32 v[138:139], v[138:139], v[88:89] op_sel_hi:[1,0]
	v_pk_mul_f32 v[158:159], v[160:161], v[88:89] op_sel_hi:[1,0]
	v_pk_mul_f32 v[160:161], v[46:47], v[56:57] op_sel_hi:[1,0]
	v_pk_mul_f32 v[170:171], v[44:45], v[56:57] op_sel_hi:[1,0]
	v_lshl_add_u64 v[68:69], v[68:69], 0, v[86:87]
	s_cbranch_execz .Ldry_p7b_real
.Ldry_p7b_c2:
	v_pk_mul_f32 v[42:43], v[42:43], v[56:57] op_sel_hi:[1,0]
	v_pk_mul_f32 v[40:41], v[40:41], v[56:57] op_sel_hi:[1,0]
	v_pk_mul_f32 v[54:55], v[54:55], v[84:85] op_sel_hi:[1,0]
	s_waitcnt vmcnt(1)
	v_pk_mul_f32 v[46:47], v[6:7], v[90:91]
	v_pk_mul_f32 v[44:45], v[4:5], v[92:93]
	s_waitcnt vmcnt(0)
	v_pk_mul_f32 v[60:61], v[2:3], v[94:95]
	v_pk_mul_f32 v[58:59], v[0:1], v[96:97]
	v_pk_mul_f32 v[92:93], v[6:7], v[102:103]
	v_pk_mul_f32 v[90:91], v[4:5], v[104:105]
	v_pk_mul_f32 v[96:97], v[2:3], v[106:107]
	v_pk_mul_f32 v[94:95], v[0:1], v[98:99]
	v_pk_mul_f32 v[100:101], v[6:7], v[108:109]
	v_pk_mul_f32 v[98:99], v[4:5], v[156:157]
	v_pk_mul_f32 v[104:105], v[2:3], v[154:155]
	v_pk_mul_f32 v[102:103], v[0:1], v[152:153]
	v_pk_mul_f32 v[108:109], v[6:7], v[142:143]
	v_pk_mul_f32 v[106:107], v[4:5], v[140:141]
	v_pk_mul_f32 v[140:141], v[2:3], v[138:139]
	v_pk_mul_f32 v[138:139], v[0:1], v[158:159]
	v_pk_mul_f32 v[154:155], v[6:7], v[62:63]
	v_pk_mul_f32 v[152:153], v[4:5], v[166:167]
	v_pk_mul_f32 v[158:159], v[2:3], v[178:179]
	v_pk_mul_f32 v[156:157], v[0:1], v[180:181]
	global_store_dwordx4 v[80:81], v[44:47], off
	s_cbranch_execz .Ldry_p7b_real
.Ldry_p7b_c3:
	global_store_dwordx4 v[80:81], v[58:61], off offset:16
	global_store_dwordx4 v[70:71], v[90:93], off
	global_store_dwordx4 v[70:71], v[94:97], off offset:16
	global_store_dwordx4 v[68:69], v[98:101], off
	global_store_dwordx4 v[68:69], v[102:105], off offset:16
	global_store_dwordx4 v[66:67], v[106:109], off
	global_store_dwordx4 v[66:67], v[138:141], off offset:16
	global_store_dwordx4 v[64:65], v[152:155], off
	global_store_dwordx4 v[64:65], v[156:159], off offset:16
	ds_read2_b32 v[90:91], v89 offset0:160 offset1:176
	v_lshl_add_u64 v[44:45], s[64:65], 0, v[164:165]
	v_lshl_add_u64 v[62:63], v[44:45], 0, v[86:87]
	v_pk_mul_f32 v[42:43], v[2:3], v[42:43]
	v_pk_mul_f32 v[40:41], v[0:1], v[40:41]
	global_store_dwordx4 v[62:63], v[40:43], off offset:16
	s_waitcnt lgkmcnt(0)
	v_pk_mul_f32 v[26:27], v[26:27], v[90:91] op_sel_hi:[1,0]
	v_pk_mul_f32 v[24:25], v[24:25], v[90:91] op_sel_hi:[1,0]
	v_lshl_add_u64 v[40:41], s[64:65], 0, v[162:163]
	v_lshl_add_u64 v[92:93], v[40:41], 0, v[86:87]
	v_pk_mul_f32 v[26:27], v[2:3], v[26:27]
	v_pk_mul_f32 v[24:25], v[0:1], v[24:25]
	v_mov_b32_e32 v94, v91
	v_pk_mul_f32 v[30:31], v[30:31], v[90:91] op_sel_hi:[1,0]
	global_store_dwordx4 v[92:93], v[24:27], off offset:16
	s_cbranch_execz .Ldry_p7b_real
;     __device__ __forceinline__ void fused(f32x4 (&acc)[2][2][4][2], const pg8::Unit& u, int wr, int wc, int fr, int fq, LAS unsigned char* lds, int wid, int lane) const {
;     ...
; #pragma unroll
;         for (int bj = 0; bj < 2; ++bj) {
;             const f32x4 g0 = *(const f32x4*)(fng + col0 + bj * 128), g1 = *(const f32x4*)(fng + col0 + bj * 128 + 4);
; #pragma unroll
;             for (int ai = 0; ai < 2; ++ai)
; #pragma unroll
;                 for (int m = 0; m < 4; ++m) {
;                     const float rstd = Sr[ai * 128 + wr * 64 + m * 16 + fr];
;                     const size_t off = (size_t)(row0 + ai * 128 + m * 16) * 1024 + col0 + bj * 128;
;                     *(f32x4*)(out + off) = acc[ai][bj][m][0] * rstd * g0; *(f32x4*)(out + off + 4) = acc[ai][bj][m][1] * rstd * g1;
;                 }
;         }
.Ldry_p7b_c4:
	v_pk_mul_f32 v[168:169], v[6:7], v[160:161]
	v_pk_mul_f32 v[28:29], v[28:29], v[90:91] op_sel_hi:[1,0]
	v_pk_mul_f32 v[24:25], v[78:79], v[94:95] op_sel_hi:[1,0]
	v_pk_mul_f32 v[30:31], v[6:7], v[30:31]
	v_pk_mul_f32 v[26:27], v[76:77], v[94:95] op_sel_hi:[1,0]
	v_pk_mul_f32 v[6:7], v[6:7], v[24:25]
	v_lshl_add_u64 v[24:25], s[64:65], 0, v[136:137]
	v_pk_mul_f32 v[166:167], v[4:5], v[170:171]
	v_pk_mul_f32 v[28:29], v[4:5], v[28:29]
	v_pk_mul_f32 v[4:5], v[4:5], v[26:27]
	v_lshl_add_u64 v[96:97], v[24:25], 0, v[86:87]
	global_store_dwordx4 v[96:97], v[4:7], off
	global_store_dwordx4 v[62:63], v[166:169], off
	global_store_dwordx4 v[92:93], v[28:31], off
	v_pk_mul_f32 v[4:5], v[74:75], v[94:95] op_sel_hi:[1,0]
	v_pk_mul_f32 v[6:7], v[72:73], v[94:95] op_sel_hi:[1,0]
	v_pk_mul_f32 v[2:3], v[2:3], v[4:5]
	v_pk_mul_f32 v[0:1], v[0:1], v[6:7]
	global_store_dwordx4 v[96:97], v[0:3], off offset:16
	global_load_dwordx4 v[0:3], v[82:83], off offset:512
	s_nop 0
	global_load_dwordx4 v[4:7], v[82:83], off offset:528
	v_pk_mul_f32 v[24:25], v[118:119], v[110:111] op_sel_hi:[1,0]
	v_pk_mul_f32 v[28:29], v[116:117], v[110:111] op_sel_hi:[1,0]
	v_pk_mul_f32 v[30:31], v[114:115], v[110:111] op_sel_hi:[1,0]
	v_pk_mul_f32 v[40:41], v[112:113], v[110:111] op_sel_hi:[1,0]
	s_cbranch_execz .Ldry_p7b_real
.Ldry_p7b_c5:
	v_pk_mul_f32 v[42:43], v[124:125], v[176:177] op_sel_hi:[1,0]
	v_pk_mul_f32 v[44:45], v[126:127], v[176:177] op_sel_hi:[1,0]
	v_pk_mul_f32 v[46:47], v[120:121], v[176:177] op_sel_hi:[1,0]
	v_pk_mul_f32 v[58:59], v[122:123], v[176:177] op_sel_hi:[1,0]
	v_pk_mul_f32 v[60:61], v[150:151], v[186:187] op_sel_hi:[1,0]
	v_pk_mul_f32 v[72:73], v[148:149], v[186:187] op_sel_hi:[1,0]
	v_pk_mul_f32 v[74:75], v[146:147], v[186:187] op_sel_hi:[1,0]
	v_pk_mul_f32 v[76:77], v[144:145], v[186:187] op_sel_hi:[1,0]
	v_pk_mul_f32 v[82:83], v[52:53], v[84:85] op_sel_hi:[1,0]
	v_pk_mul_f32 v[78:79], v[134:135], v[88:89] op_sel_hi:[1,0]
	v_pk_mul_f32 v[86:87], v[132:133], v[88:89] op_sel_hi:[1,0]
	v_pk_mul_f32 v[100:101], v[130:131], v[88:89] op_sel_hi:[1,0]
	v_pk_mul_f32 v[88:89], v[128:129], v[88:89] op_sel_hi:[1,0]
	v_pk_mul_f32 v[98:99], v[50:51], v[84:85] op_sel_hi:[1,0]
	v_pk_mul_f32 v[14:15], v[14:15], v[90:91] op_sel_hi:[1,0]
	v_pk_mul_f32 v[12:13], v[12:13], v[90:91] op_sel_hi:[1,0]
	v_pk_mul_f32 v[22:23], v[22:23], v[90:91] op_sel_hi:[1,0]
	v_pk_mul_f32 v[20:21], v[20:21], v[90:91] op_sel_hi:[1,0]
	s_waitcnt vmcnt(1)
	v_pk_mul_f32 v[26:27], v[2:3], v[24:25]
	v_pk_mul_f32 v[24:25], v[0:1], v[28:29]
	s_waitcnt vmcnt(0)
	v_pk_mul_f32 v[30:31], v[6:7], v[30:31]
	v_pk_mul_f32 v[28:29], v[4:5], v[40:41]
	v_pk_mul_f32 v[42:43], v[2:3], v[42:43]
	v_pk_mul_f32 v[40:41], v[0:1], v[44:45]
	s_cbranch_execz .Ldry_p7b_real
.Ldry_p7b_c6:
	v_pk_mul_f32 v[46:47], v[6:7], v[46:47]
	v_pk_mul_f32 v[44:45], v[4:5], v[58:59]
	v_pk_mul_f32 v[52:53], v[2:3], v[60:61]
	v_pk_mul_f32 v[50:51], v[0:1], v[72:73]
	v_pk_mul_f32 v[60:61], v[6:7], v[74:75]
	v_pk_mul_f32 v[58:59], v[4:5], v[76:77]
	v_pk_mul_f32 v[74:75], v[2:3], v[78:79]
	v_pk_mul_f32 v[72:73], v[0:1], v[86:87]
	v_pk_mul_f32 v[78:79], v[6:7], v[100:101]
	v_pk_mul_f32 v[76:77], v[4:5], v[88:89]
	v_pk_mul_f32 v[88:89], v[2:3], v[54:55]
	v_pk_mul_f32 v[86:87], v[0:1], v[82:83]
	global_store_dwordx4 v[80:81], v[24:27], off offset:512
	global_store_dwordx4 v[80:81], v[28:31], off offset:528
	global_store_dwordx4 v[70:71], v[40:43], off offset:512
	global_store_dwordx4 v[70:71], v[44:47], off offset:528
	global_store_dwordx4 v[68:69], v[50:53], off offset:512
	global_store_dwordx4 v[68:69], v[58:61], off offset:528
	global_store_dwordx4 v[66:67], v[72:75], off offset:512
	global_store_dwordx4 v[66:67], v[76:79], off offset:528
	global_store_dwordx4 v[64:65], v[86:89], off offset:512
	v_pk_mul_f32 v[24:25], v[48:49], v[84:85] op_sel_hi:[1,0]
	v_pk_mul_f32 v[26:27], v[6:7], v[98:99]
	v_pk_mul_f32 v[24:25], v[4:5], v[24:25]
	v_pk_mul_f32 v[14:15], v[6:7], v[14:15]
	s_cbranch_execz .Ldry_p7b_real
.Ldry_p7b_c7:
	v_pk_mul_f32 v[12:13], v[4:5], v[12:13]
	global_store_dwordx4 v[64:65], v[24:27], off offset:528
	v_pk_mul_f32 v[28:29], v[36:37], v[56:57] op_sel_hi:[1,0]
	global_store_dwordx4 v[92:93], v[12:15], off offset:528
	v_pk_mul_f32 v[24:25], v[38:39], v[56:57] op_sel_hi:[1,0]
	v_pk_mul_f32 v[22:23], v[2:3], v[22:23]
	v_pk_mul_f32 v[12:13], v[16:17], v[94:95] op_sel_hi:[1,0]
	v_pk_mul_f32 v[14:15], v[18:19], v[94:95] op_sel_hi:[1,0]
	v_pk_mul_f32 v[26:27], v[2:3], v[24:25]
	v_pk_mul_f32 v[24:25], v[0:1], v[28:29]
	v_pk_mul_f32 v[20:21], v[0:1], v[20:21]
	v_pk_mul_f32 v[2:3], v[2:3], v[12:13]
	v_pk_mul_f32 v[0:1], v[0:1], v[14:15]
	global_store_dwordx4 v[62:63], v[24:27], off offset:512
	v_pk_mul_f32 v[28:29], v[32:33], v[56:57] op_sel_hi:[1,0]
	global_store_dwordx4 v[96:97], v[0:3], off offset:512
	v_pk_mul_f32 v[24:25], v[34:35], v[56:57] op_sel_hi:[1,0]
	global_store_dwordx4 v[92:93], v[20:23], off offset:512
	v_pk_mul_f32 v[0:1], v[8:9], v[94:95] op_sel_hi:[1,0]
	v_pk_mul_f32 v[8:9], v[10:11], v[94:95] op_sel_hi:[1,0]
	v_pk_mul_f32 v[26:27], v[6:7], v[24:25]
	v_pk_mul_f32 v[24:25], v[4:5], v[28:29]
	v_pk_mul_f32 v[2:3], v[6:7], v[0:1]
	v_pk_mul_f32 v[0:1], v[4:5], v[8:9]
	global_store_dwordx4 v[62:63], v[24:27], off offset:528
	global_store_dwordx4 v[96:97], v[0:3], off offset:528
	s_cbranch_execz .Ldry_p7b_real
